# attention loops: score-minus-max subtractions packed pairwise into v_pk_add_f32 (neg), exps read the score registers in place
# speedup vs baseline: 1.0085x; 1.0085x over previous
; #define MFMA32(a, b, c) __builtin_amdgcn_mfma_f32_32x32x16_bf16((a), (b), (c), 0, 0, 0)
; template <int D>
; DI void attn_pass(const bfr* __restrict__ P, int b, int tq_wave, int qcol, int kcol, int vcol, int key0, int nkt, char* smem, f32x16 (&o)[2]) {
;     ...
;   for (int kt = 0; kt < nkt; ++kt) {
;     bfr* sK = sbase + (kt & 1) * 9216;
;     bfr* sV = sK + 64 * 72;
;     { int c = gt, row = c >> 3, kc = c & 7; *(u32x4*)(sK + row * KP + kc * 8) = kreg[0]; }
;     for (int i = 0; i < 1; ++i) {
;       int c = gt, row = c >> 3, kc = c & 7;
;       unsigned wds[4] = {vreg[i].x, vreg[i].y, vreg[i].z, vreg[i].w};
; #pragma unroll
;       for (int e = 0; e < 4; ++e) {
;         sV[(kc * 8 + 2 * e) * 72 + (row ^ (kc << 3))] = (bfr)(wds[e] & 0xffffu);
;         sV[(kc * 8 + 2 * e + 1) * 72 + (row ^ (kc << 3))] = (bfr)(wds[e] >> 16);
;       }
;     }
;     __syncthreads();
;     if (kt + 1 < nkt) {
;       const bfr* Pn = Pb + (size_t)(kt + 1) * 64 * PW;
;       { int c = gt, row = c >> 3, kc = c & 7; kreg[0] = *(const u32x4*)(Pn + (size_t)row * PW + kcol + kc * 8); vreg[0] = *(const u32x4*)(Pn + (size_t)row * PW + vcol + kc * 8); }
;     }
;     f32x16 s[2];
; #pragma unroll
;     for (int t2 = 0; t2 < 2; ++t2) {
; #pragma unroll
;       for (int i = 0; i < 16; ++i) s[t2][i] = 0.f;
; #pragma unroll
;       for (int ks = 0; ks < KS; ++ks) {
;         bf16x8 a = *(const bf16x8*)(sK + (t2 * 32 + r) * KP + ks * 16 + h * 8);
;         s[t2] = MFMA32(a, qf[ks], s[t2]);
;       }
;     }
;     float mx = s[0][0];
; #pragma unroll
;     for (int i = 0; i < 16; ++i) { mx = fmaxf(mx, s[0][i]); mx = fmaxf(mx, s[1][i]); }
;     mx = fmaxf(mx, __shfl_xor(mx, 32));
;     float mnew = fmaxf(mrun, mx);
;     float alpha = __builtin_amdgcn_exp2f(mrun - mnew);
;     mrun = mnew;
;     float ps = 0.f;
; #pragma unroll
;     for (int i = 0; i < 16; ++i) {
;       s[0][i] = __builtin_amdgcn_exp2f(s[0][i] - mnew); ps += s[0][i];
;       s[1][i] = __builtin_amdgcn_exp2f(s[1][i] - mnew); ps += s[1][i];
;     }
;     lsum = lsum * alpha + ps;
; #pragma unroll
;     for (int i = 0; i < 16; ++i) { accO[0][i] *= alpha; accO[1][i] *= alpha; }
.LBB0_400:
	s_bitcmp1_b32 s10, 0
	s_cselect_b32 s11, 0x4800, 0
	s_add_i32 s11, s11, 0
	v_add3_u32 v32, s11, v115, v90
	v_add_u32_e32 v121, s11, v114
	v_mov_b32_e32 v120, v113
	s_waitcnt vmcnt(1)
	ds_write_b128 v32, v[84:87]
	v_add3_u32 v32, s11, v117, v118
	v_add3_u32 v33, s11, v118, v117
	v_add_u32_e32 v113, v121, v152
	s_waitcnt vmcnt(0)
	ds_write_b16 v32, v80 offset:9216
	ds_write_b16_d16_hi v33, v80 offset:9360
	ds_write_b16 v32, v81 offset:9504
	ds_write_b16_d16_hi v33, v81 offset:9648
	ds_write_b16 v32, v82 offset:9792
	ds_write_b16_d16_hi v33, v82 offset:9936
	ds_write_b16 v32, v83 offset:10080
	ds_write_b16_d16_hi v33, v83 offset:10224
	s_waitcnt lgkmcnt(0)
	s_barrier
	global_load_dwordx4 v[84:87], v[92:93], off
	global_load_dwordx4 v[80:83], v[94:95], off
	ds_read_b128 v[32:35], v113
	ds_read_b128 v[48:51], v113 offset:32
	s_waitcnt lgkmcnt(1)
	v_mfma_f32_32x32x16_bf16 v[32:47], v[32:35], v[76:79], 0
	ds_read_b128 v[122:125], v113 offset:4640
	v_mov_b32_e32 v96, v119
	s_add_i32 s10, s10, 1
	v_lshl_add_u64 v[92:93], v[92:93], 0, s[12:13]
	v_lshl_add_u64 v[94:95], v[94:95], 0, s[12:13]
	s_cmp_lg_u32 s10, 3
	s_waitcnt lgkmcnt(1)
	v_mfma_f32_32x32x16_bf16 v[32:47], v[48:51], v[72:75], v[32:47]
	ds_read_b128 v[48:51], v113 offset:64
	s_waitcnt lgkmcnt(0)
	v_mfma_f32_32x32x16_bf16 v[32:47], v[48:51], v[68:71], v[32:47]
	ds_read_b128 v[48:51], v113 offset:96
	s_waitcnt lgkmcnt(0)
	v_mfma_f32_32x32x16_bf16 v[32:47], v[48:51], v[64:67], v[32:47]
	ds_read_b128 v[48:51], v113 offset:4608
	s_waitcnt lgkmcnt(0)
	v_mfma_f32_32x32x16_bf16 v[48:63], v[48:51], v[76:79], 0
	s_nop 8
	v_max_f32_e32 v119, v32, v32
	v_mfma_f32_32x32x16_bf16 v[48:63], v[122:125], v[72:75], v[48:63]
	ds_read_b128 v[122:125], v113 offset:4672
	s_waitcnt lgkmcnt(0)
	v_mfma_f32_32x32x16_bf16 v[48:63], v[122:125], v[68:71], v[48:63]
	ds_read_b128 v[122:125], v113 offset:4704
	s_waitcnt lgkmcnt(0)
	v_mfma_f32_32x32x16_bf16 v[48:63], v[122:125], v[64:67], v[48:63]
	s_nop 11
	v_max_f32_e32 v113, v48, v48
	v_max_f32_e32 v113, v119, v113
	v_max3_f32 v113, v113, v33, v49
	v_max3_f32 v113, v113, v34, v50
	v_max3_f32 v113, v113, v35, v51
	v_max3_f32 v113, v113, v36, v52
	v_max3_f32 v113, v113, v37, v53
	v_max3_f32 v113, v113, v38, v54
	v_max3_f32 v113, v113, v39, v55
	v_max3_f32 v113, v113, v40, v56
	v_max3_f32 v113, v113, v41, v57
	v_max3_f32 v113, v113, v42, v58
	v_max3_f32 v113, v113, v43, v59
	v_max3_f32 v113, v113, v44, v60
	v_max3_f32 v113, v113, v45, v61
	v_max3_f32 v113, v113, v46, v62
	v_max3_f32 v113, v113, v47, v63
	ds_bpermute_b32 v119, v91, v113
	s_waitcnt lgkmcnt(0)
	v_max3_f32 v119, v96, v113, v119
	v_pk_add_f32 v[32:33], v[32:33], v[118:119] op_sel:[0,1] op_sel_hi:[1,1] neg_lo:[0,1] neg_hi:[0,1]
	v_pk_add_f32 v[38:39], v[38:39], v[118:119] op_sel:[0,1] op_sel_hi:[1,1] neg_lo:[0,1] neg_hi:[0,1]
	v_exp_f32_e32 v32, v32
	v_pk_add_f32 v[48:49], v[48:49], v[118:119] op_sel:[0,1] op_sel_hi:[1,1] neg_lo:[0,1] neg_hi:[0,1]
	v_pk_add_f32 v[36:37], v[36:37], v[118:119] op_sel:[0,1] op_sel_hi:[1,1] neg_lo:[0,1] neg_hi:[0,1]
	v_exp_f32_e32 v124, v38
	v_pk_add_f32 v[54:55], v[54:55], v[118:119] op_sel:[0,1] op_sel_hi:[1,1] neg_lo:[0,1] neg_hi:[0,1]
	v_exp_f32_e32 v48, v48
	v_exp_f32_e32 v122, v36
	v_sub_f32_e32 v36, v52, v119
	v_exp_f32_e32 v52, v54
	v_exp_f32_e32 v33, v33
	v_exp_f32_e32 v125, v39
	v_exp_f32_e32 v49, v49
	v_pk_add_f32 v[34:35], v[34:35], v[118:119] op_sel:[0,1] op_sel_hi:[1,1] neg_lo:[0,1] neg_hi:[0,1]
	v_exp_f32_e32 v123, v37
	v_sub_f32_e32 v37, v53, v119
	v_exp_f32_e32 v53, v55
	v_pk_add_f32 v[40:41], v[40:41], v[118:119] op_sel:[0,1] op_sel_hi:[1,1] neg_lo:[0,1] neg_hi:[0,1]
	v_pk_add_f32 v[42:43], v[42:43], v[118:119] op_sel:[0,1] op_sel_hi:[1,1] neg_lo:[0,1] neg_hi:[0,1]
	v_pk_add_f32 v[44:45], v[44:45], v[118:119] op_sel:[0,1] op_sel_hi:[1,1] neg_lo:[0,1] neg_hi:[0,1]
	v_exp_f32_e32 v34, v34
	v_pk_add_f32 v[50:51], v[50:51], v[118:119] op_sel:[0,1] op_sel_hi:[1,1] neg_lo:[0,1] neg_hi:[0,1]
	v_exp_f32_e32 v54, v40
	v_sub_f32_e32 v38, v56, v119
	v_exp_f32_e32 v56, v42
	v_sub_f32_e32 v40, v58, v119
	v_exp_f32_e32 v58, v44
	v_sub_f32_e32 v42, v60, v119
	v_add_f32_e32 v60, 0, v32
	v_exp_f32_e32 v50, v50
	v_add_f32_e32 v60, v48, v60
	v_exp_f32_e32 v35, v35
	v_add_f32_e32 v60, v33, v60
	v_exp_f32_e32 v51, v51
	v_add_f32_e32 v60, v49, v60
	v_add_f32_e32 v60, v34, v60
	v_exp_f32_e32 v36, v36
	v_add_f32_e32 v60, v50, v60
	v_add_f32_e32 v60, v35, v60
	v_exp_f32_e32 v37, v37
	v_add_f32_e32 v60, v51, v60
	v_add_f32_e32 v60, v122, v60
	v_add_f32_e32 v60, v36, v60
	v_add_f32_e32 v60, v123, v60
	v_add_f32_e32 v60, v37, v60
	v_add_f32_e32 v60, v124, v60
	v_exp_f32_e32 v38, v38
	v_add_f32_e32 v60, v52, v60
	v_exp_f32_e32 v55, v41
	v_sub_f32_e32 v39, v57, v119
	v_add_f32_e32 v60, v125, v60
	v_exp_f32_e32 v39, v39
	v_add_f32_e32 v60, v53, v60
	v_add_f32_e32 v60, v54, v60
	v_exp_f32_e32 v40, v40
	v_add_f32_e32 v60, v38, v60
	v_exp_f32_e32 v57, v43
	v_sub_f32_e32 v41, v59, v119
	v_add_f32_e32 v60, v55, v60
	v_exp_f32_e32 v41, v41
	v_add_f32_e32 v60, v39, v60
	v_add_f32_e32 v60, v56, v60
	v_exp_f32_e32 v42, v42
	v_add_f32_e32 v60, v40, v60
	v_exp_f32_e32 v59, v45
	v_sub_f32_e32 v43, v61, v119
	v_add_f32_e32 v60, v57, v60
	v_exp_f32_e32 v43, v43
	v_pk_add_f32 v[46:47], v[46:47], v[118:119] op_sel:[0,1] op_sel_hi:[1,1] neg_lo:[0,1] neg_hi:[0,1]
	v_add_f32_e32 v60, v41, v60
	v_exp_f32_e32 v46, v46
	v_pk_add_f32 v[62:63], v[62:63], v[118:119] op_sel:[0,1] op_sel_hi:[1,1] neg_lo:[0,1] neg_hi:[0,1]
	v_add_f32_e32 v60, v58, v60
	v_exp_f32_e32 v44, v62
	v_add_f32_e32 v60, v42, v60
	v_exp_f32_e32 v47, v47
	v_add_f32_e32 v60, v59, v60
	v_exp_f32_e32 v45, v63
	v_add_f32_e32 v60, v43, v60
	v_add_f32_e32 v60, v46, v60
	v_add_f32_e32 v60, v44, v60
	v_add_f32_e32 v60, v47, v60
	v_add_f32_e32 v113, v45, v60
	v_lshl_add_u32 v60, v112, 1, v121
	v_lshl_add_u32 v61, v111, 1, v121
	v_cvt_pk_bf16_f32 v32, v32, v33
	v_cvt_pk_bf16_f32 v33, v34, v35
	v_cvt_pk_bf16_f32 v34, v122, v123
	v_cvt_pk_bf16_f32 v35, v124, v125
	ds_read_b64 v[122:123], v60 offset:9216
	ds_read_b64 v[124:125], v61 offset:9216
	v_sub_f32_e32 v96, v96, v119
	v_exp_f32_e32 v96, v96
	v_add_u32_e32 v61, s11, v116
	v_lshl_add_u32 v62, v110, 1, v61
	v_pk_mul_f32 v[30:31], v[30:31], v[96:97] op_sel_hi:[1,0]
	v_pk_mul_f32 v[28:29], v[28:29], v[96:97] op_sel_hi:[1,0]
	v_pk_mul_f32 v[26:27], v[26:27], v[96:97] op_sel_hi:[1,0]
	v_pk_mul_f32 v[24:25], v[24:25], v[96:97] op_sel_hi:[1,0]
	v_pk_mul_f32 v[22:23], v[22:23], v[96:97] op_sel_hi:[1,0]
	v_pk_mul_f32 v[20:21], v[20:21], v[96:97] op_sel_hi:[1,0]
	v_pk_mul_f32 v[18:19], v[18:19], v[96:97] op_sel_hi:[1,0]
	v_pk_mul_f32 v[16:17], v[16:17], v[96:97] op_sel_hi:[1,0]
	v_pk_mul_f32 v[14:15], v[14:15], v[96:97] op_sel_hi:[1,0]
	v_pk_mul_f32 v[12:13], v[12:13], v[96:97] op_sel_hi:[1,0]
	s_waitcnt lgkmcnt(0)
; template <int D>
; DI void attn_pass(const bfr* __restrict__ P, int b, int tq_wave, int qcol, int kcol, int vcol, int key0, int nkt, char* smem, f32x16 (&o)[2]) {
;     ...
;   for (int kt = 0; kt < nkt; ++kt) {
;     bfr* sK = sbase + (kt & 1) * 9216;
;     bfr* sV = sK + 64 * 72;
;     { int c = gt, row = c >> 3, kc = c & 7; *(u32x4*)(sK + row * KP + kc * 8) = kreg[0]; }
;     for (int i = 0; i < 1; ++i) {
;       int c = gt, row = c >> 3, kc = c & 7;
;       unsigned wds[4] = {vreg[i].x, vreg[i].y, vreg[i].z, vreg[i].w};
; #pragma unroll
;       for (int e = 0; e < 4; ++e) {
;         sV[(kc * 8 + 2 * e) * 72 + (row ^ (kc << 3))] = (bfr)(wds[e] & 0xffffu);
;         sV[(kc * 8 + 2 * e + 1) * 72 + (row ^ (kc << 3))] = (bfr)(wds[e] >> 16);
;       }
;     }
;     __syncthreads();
;     if (kt + 1 < nkt) {
;       const bfr* Pn = Pb + (size_t)(kt + 1) * 64 * PW;
;       { int c = gt, row = c >> 3, kc = c & 7; kreg[0] = *(const u32x4*)(Pn + (size_t)row * PW + kcol + kc * 8); vreg[0] = *(const u32x4*)(Pn + (size_t)row * PW + vcol + kc * 8); }
;     }
;     f32x16 s[2];
; #pragma unroll
;     for (int t2 = 0; t2 < 2; ++t2) {
; #pragma unroll
;       for (int i = 0; i < 16; ++i) s[t2][i] = 0.f;
; #pragma unroll
;       for (int ks = 0; ks < KS; ++ks) {
;         bf16x8 a = *(const bf16x8*)(sK + (t2 * 32 + r) * KP + ks * 16 + h * 8);
;         s[t2] = MFMA32(a, qf[ks], s[t2]);
;       }
;     }
;     float mx = s[0][0];
; #pragma unroll
;     ...
;     for (int i = 0; i < 16; ++i) { accO[0][i] *= alpha; accO[1][i] *= alpha; }
; #pragma unroll
;     for (int t2 = 0; t2 < 2; ++t2)
; #pragma unroll
;       for (int j = 0; j < 2; ++j) {
;         unsigned pk[4];
; #pragma unroll
;         for (int e = 0; e < 4; ++e) pk[e] = pack2(s[t2][8 * j + 2 * e], s[t2][8 * j + 2 * e + 1]);
;         u32x4 pku = {pk[0], pk[1], pk[2], pk[3]};
;         bf16x8 pf = __builtin_bit_cast(bf16x8, pku);
; #pragma unroll
;         for (int dt = 0; dt < 2; ++dt) {
;           const int vsw = (((dt * 32 + r) >> 3) & 7) << 3;
;           const bfr* vrow = sV + (dt * 32 + r) * 72;
;           s16x4 lo = *(const s16x4*)(vrow + ((t2 * 32 + 16 * j + 4 * h) ^ vsw));
;           s16x4 hi = *(const s16x4*)(vrow + ((t2 * 32 + 16 * j + 4 * h + 8) ^ vsw));
;           bf16x8 vf = __builtin_shufflevector(lo, hi, 0, 1, 2, 3, 4, 5, 6, 7);
;           accO[dt] = MFMA32(vf, pf, accO[dt]);
;         }
;       }
;   }
	v_mfma_f32_32x32x16_bf16 v[16:31], v[122:125], v[32:35], v[16:31]
	ds_read_b64 v[122:123], v62 offset:9216
	v_lshl_add_u32 v62, v109, 1, v61
	ds_read_b64 v[124:125], v62 offset:9216
	v_mul_f32_e64 v10, v10, v96
	v_mul_f32_e64 v11, v11, v96
	v_pk_mul_f32 v[8:9], v[8:9], v[96:97] op_sel_hi:[1,0]
	v_pk_mul_f32 v[6:7], v[6:7], v[96:97] op_sel_hi:[1,0]
	v_pk_mul_f32 v[4:5], v[4:5], v[96:97] op_sel_hi:[1,0]
	v_pk_mul_f32 v[2:3], v[2:3], v[96:97] op_sel_hi:[1,0]
	v_pk_mul_f32 v[0:1], v[0:1], v[96:97] op_sel_hi:[1,0]
	v_fmac_f32_e32 v113, v120, v96
	s_waitcnt lgkmcnt(0)
	v_mfma_f32_32x32x16_bf16 v[0:15], v[122:125], v[32:35], v[0:15]
	v_cvt_pk_bf16_f32 v32, v54, v55
	v_cvt_pk_bf16_f32 v33, v56, v57
	v_cvt_pk_bf16_f32 v34, v58, v59
	v_cvt_pk_bf16_f32 v35, v46, v47
	v_lshl_add_u32 v46, v108, 1, v121
	ds_read_b64 v[54:55], v46 offset:9216
	v_lshl_add_u32 v46, v107, 1, v121
	ds_read_b64 v[56:57], v46 offset:9216
	v_lshl_add_u32 v46, v106, 1, v61
	s_waitcnt lgkmcnt(0)
	v_mfma_f32_32x32x16_bf16 v[16:31], v[54:57], v[32:35], v[16:31]
	ds_read_b64 v[54:55], v46 offset:9216
	v_lshl_add_u32 v46, v105, 1, v61
	ds_read_b64 v[56:57], v46 offset:9216
	s_waitcnt lgkmcnt(0)
	v_mfma_f32_32x32x16_bf16 v[0:15], v[54:57], v[32:35], v[0:15]
	v_cvt_pk_bf16_f32 v32, v48, v49
	v_cvt_pk_bf16_f32 v33, v50, v51
	v_cvt_pk_bf16_f32 v34, v36, v37
	v_lshl_add_u32 v36, v104, 1, v121
	v_cvt_pk_bf16_f32 v35, v52, v53
	ds_read_b64 v[46:47], v60 offset:9280
	ds_read_b64 v[48:49], v36 offset:9216
	v_lshl_add_u32 v36, v103, 1, v61
	s_waitcnt lgkmcnt(0)
	v_mfma_f32_32x32x16_bf16 v[16:31], v[46:49], v[32:35], v[16:31]
	ds_read_b64 v[46:47], v36 offset:9216
	v_lshl_add_u32 v36, v102, 1, v61
	ds_read_b64 v[48:49], v36 offset:9216
	v_lshl_add_u32 v36, v100, 1, v121
	s_waitcnt lgkmcnt(0)
	v_mfma_f32_32x32x16_bf16 v[0:15], v[46:49], v[32:35], v[0:15]
	v_cvt_pk_bf16_f32 v32, v38, v39
	v_lshl_add_u32 v38, v101, 1, v121
	v_cvt_pk_bf16_f32 v33, v40, v41
	v_cvt_pk_bf16_f32 v34, v42, v43
	v_cvt_pk_bf16_f32 v35, v44, v45
	ds_read_b64 v[36:37], v36 offset:9216
	ds_read_b64 v[38:39], v38 offset:9216
	s_waitcnt lgkmcnt(0)
	v_mfma_f32_32x32x16_bf16 v[16:31], v[36:39], v[32:35], v[16:31]
	v_lshl_add_u32 v36, v99, 1, v61
	v_lshl_add_u32 v38, v98, 1, v61
	ds_read_b64 v[36:37], v36 offset:9216
	ds_read_b64 v[38:39], v38 offset:9216
	s_waitcnt lgkmcnt(0)
	v_mfma_f32_32x32x16_bf16 v[0:15], v[36:39], v[32:35], v[0:15]
	s_cbranch_scc1 .LBB0_400
	v_add3_u32 v32, 0, v115, v90
	s_waitcnt vmcnt(1)
	ds_write_b128 v32, v[84:87] offset:18432
	v_add3_u32 v32, 0, v117, v118
	v_add3_u32 v33, 0, v118, v117
	s_waitcnt vmcnt(0)
	ds_write_b16 v32, v80 offset:27648
	ds_write_b16_d16_hi v33, v80 offset:27792
	ds_write_b16 v32, v81 offset:27936
	ds_write_b16_d16_hi v33, v81 offset:28080
	ds_write_b16 v32, v82 offset:28224
	ds_write_b16_d16_hi v33, v82 offset:28368
	ds_write_b16 v32, v83 offset:28512
	ds_write_b16_d16_hi v33, v83 offset:28656
	v_add_u32_e32 v80, 0, v114
	v_add_u32_e32 v81, v80, v152
	s_waitcnt lgkmcnt(0)
	s_barrier
	ds_read_b128 v[32:35], v81 offset:18432
	ds_read_b128 v[48:51], v81 offset:18464
	s_waitcnt lgkmcnt(1)
	v_mfma_f32_32x32x16_bf16 v[32:47], v[32:35], v[76:79], 0
	v_lshlrev_b32_e32 v152, 1, v88
	s_waitcnt lgkmcnt(0)
	v_mfma_f32_32x32x16_bf16 v[32:47], v[48:51], v[72:75], v[32:47]
	ds_read_b128 v[48:51], v81 offset:18496
	s_waitcnt lgkmcnt(0)
	v_mfma_f32_32x32x16_bf16 v[32:47], v[48:51], v[68:71], v[32:47]
	ds_read_b128 v[48:51], v81 offset:18528
	s_waitcnt lgkmcnt(0)
	v_mfma_f32_32x32x16_bf16 v[32:47], v[48:51], v[64:67], v[32:47]
	ds_read_b128 v[48:51], v81 offset:23040
	s_waitcnt lgkmcnt(0)
	v_mfma_f32_32x32x16_bf16 v[48:63], v[48:51], v[76:79], 0
	ds_read_b128 v[76:79], v81 offset:23072
	s_waitcnt lgkmcnt(0)
	v_mfma_f32_32x32x16_bf16 v[48:63], v[76:79], v[72:75], v[48:63]
	ds_read_b128 v[72:75], v81 offset:23104
	s_waitcnt lgkmcnt(0)
	v_mfma_f32_32x32x16_bf16 v[48:63], v[72:75], v[68:71], v[48:63]
	ds_read_b128 v[68:71], v81 offset:23136
	s_waitcnt lgkmcnt(0)
	v_mfma_f32_32x32x16_bf16 v[48:63], v[68:71], v[64:67], v[48:63]
	v_max_f32_e32 v65, v32, v32
	v_lshl_add_u32 v66, v112, 1, v80
	v_add_u32_e32 v67, 0x1200, v80
	s_nop 8
	v_max_f32_e32 v64, v48, v48
	v_max_f32_e32 v64, v65, v64
	v_max3_f32 v64, v64, v33, v49
	v_max3_f32 v64, v64, v34, v50
	v_max3_f32 v64, v64, v35, v51
	v_max3_f32 v64, v64, v36, v52
	v_max3_f32 v64, v64, v37, v53
	v_max3_f32 v64, v64, v38, v54
	v_max3_f32 v64, v64, v39, v55
	v_max3_f32 v64, v64, v40, v56
	v_max3_f32 v64, v64, v41, v57
	v_max3_f32 v64, v64, v42, v58
	v_max3_f32 v64, v64, v43, v59
	v_max3_f32 v64, v64, v44, v60
	v_max3_f32 v64, v64, v45, v61
	v_max3_f32 v64, v64, v46, v62
	v_max3_f32 v64, v64, v47, v63
	ds_bpermute_b32 v65, v91, v64
	s_waitcnt lgkmcnt(0)
; #define MFMA32(a, b, c) __builtin_amdgcn_mfma_f32_32x32x16_bf16((a), (b), (c), 0, 0, 0)
; DI unsigned pack2(float a, float b) { unsigned r; asm volatile("v_cvt_pk_bf16_f32 %0, %1, %2" : "=v"(r) : "v"(a), "v"(b)); return r; }
; template <int D>
; DI void attn_pass(const bfr* __restrict__ P, int b, int tq_wave, int qcol, int kcol, int vcol, int key0, int nkt, char* smem, f32x16 (&o)[2]) {
;     ...
;     mx = fmaxf(mx, __shfl_xor(mx, 32));
;     float mnew = fmaxf(mrun, mx);
;     float alpha = __builtin_amdgcn_exp2f(mrun - mnew);
;     mrun = mnew;
;     float ps = 0.f;
; #pragma unroll
;     for (int i = 0; i < 16; ++i) {
;       s[0][i] = __builtin_amdgcn_exp2f(s[0][i] - mnew); ps += s[0][i];
;       s[1][i] = __builtin_amdgcn_exp2f(s[1][i] - mnew); ps += s[1][i];
;     }
;     lsum = lsum * alpha + ps;
; #pragma unroll
;     for (int i = 0; i < 16; ++i) { accO[0][i] *= alpha; accO[1][i] *= alpha; }
; #pragma unroll
;     for (int t2 = 0; t2 < 2; ++t2)
; #pragma unroll
;       for (int j = 0; j < 2; ++j) {
;         unsigned pk[4];
; #pragma unroll
;         for (int e = 0; e < 4; ++e) pk[e] = pack2(s[t2][8 * j + 2 * e], s[t2][8 * j + 2 * e + 1]);
;         u32x4 pku = {pk[0], pk[1], pk[2], pk[3]};
;         bf16x8 pf = __builtin_bit_cast(bf16x8, pku);
; #pragma unroll
;         for (int dt = 0; dt < 2; ++dt) {
;           const int vsw = (((dt * 32 + r) >> 3) & 7) << 3;
;           const bfr* vrow = sV + (dt * 32 + r) * 72;
;           s16x4 lo = *(const s16x4*)(vrow + ((t2 * 32 + 16 * j + 4 * h) ^ vsw));
;           s16x4 hi = *(const s16x4*)(vrow + ((t2 * 32 + 16 * j + 4 * h + 8) ^ vsw));
;           bf16x8 vf = __builtin_shufflevector(lo, hi, 0, 1, 2, 3, 4, 5, 6, 7);
;           accO[dt] = MFMA32(vf, pf, accO[dt]);
	v_max3_f32 v65, v119, v64, v65
	v_sub_f32_e32 v64, v119, v65
	v_sub_f32_e32 v32, v32, v65
	v_exp_f32_e32 v64, v64
	v_exp_f32_e32 v32, v32
	v_sub_f32_e32 v48, v48, v65
	v_exp_f32_e32 v48, v48
	v_sub_f32_e32 v33, v33, v65
	v_exp_f32_e32 v33, v33
	v_sub_f32_e32 v49, v49, v65
	v_exp_f32_e32 v49, v49
	v_sub_f32_e32 v34, v34, v65
	v_exp_f32_e32 v34, v34
	v_sub_f32_e32 v50, v50, v65
	v_sub_f32_e32 v35, v35, v65
	v_sub_f32_e32 v51, v51, v65
	v_sub_f32_e32 v36, v36, v65
	v_sub_f32_e32 v52, v52, v65
	v_sub_f32_e32 v37, v37, v65
	v_sub_f32_e32 v53, v53, v65
	v_sub_f32_e32 v38, v38, v65
	v_sub_f32_e32 v54, v54, v65
	v_sub_f32_e32 v39, v39, v65
	v_sub_f32_e32 v55, v55, v65
	v_sub_f32_e32 v40, v40, v65
	v_sub_f32_e32 v56, v56, v65
	v_sub_f32_e32 v41, v41, v65
	v_sub_f32_e32 v57, v57, v65
	v_sub_f32_e32 v42, v42, v65
	v_sub_f32_e32 v58, v58, v65
	v_sub_f32_e32 v43, v43, v65
	v_sub_f32_e32 v59, v59, v65
	v_sub_f32_e32 v44, v44, v65
	v_sub_f32_e32 v60, v60, v65
	v_sub_f32_e32 v45, v45, v65
	v_sub_f32_e32 v61, v61, v65
	v_sub_f32_e32 v46, v46, v65
	v_sub_f32_e32 v62, v62, v65
	v_sub_f32_e32 v47, v47, v65
	v_sub_f32_e32 v63, v63, v65
	v_pk_mul_f32 v[30:31], v[30:31], v[64:65] op_sel_hi:[1,0]
	v_pk_mul_f32 v[28:29], v[28:29], v[64:65] op_sel_hi:[1,0]
	v_pk_mul_f32 v[26:27], v[26:27], v[64:65] op_sel_hi:[1,0]
	v_pk_mul_f32 v[24:25], v[24:25], v[64:65] op_sel_hi:[1,0]
	v_pk_mul_f32 v[22:23], v[22:23], v[64:65] op_sel_hi:[1,0]
	v_pk_mul_f32 v[20:21], v[20:21], v[64:65] op_sel_hi:[1,0]
	v_pk_mul_f32 v[18:19], v[18:19], v[64:65] op_sel_hi:[1,0]
	v_pk_mul_f32 v[16:17], v[16:17], v[64:65] op_sel_hi:[1,0]
	v_pk_mul_f32 v[14:15], v[14:15], v[64:65] op_sel_hi:[1,0]
	v_pk_mul_f32 v[12:13], v[12:13], v[64:65] op_sel_hi:[1,0]
	v_pk_mul_f32 v[10:11], v[10:11], v[64:65] op_sel_hi:[1,0]
	v_pk_mul_f32 v[8:9], v[8:9], v[64:65] op_sel_hi:[1,0]
	v_pk_mul_f32 v[6:7], v[6:7], v[64:65] op_sel_hi:[1,0]
	v_pk_mul_f32 v[4:5], v[4:5], v[64:65] op_sel_hi:[1,0]
	v_pk_mul_f32 v[2:3], v[2:3], v[64:65] op_sel_hi:[1,0]
	v_pk_mul_f32 v[0:1], v[0:1], v[64:65] op_sel_hi:[1,0]
	v_add_f32_e32 v65, 0, v32
	v_exp_f32_e32 v50, v50
	v_add_f32_e32 v65, v48, v65
	v_exp_f32_e32 v35, v35
	v_add_f32_e32 v65, v33, v65
	v_exp_f32_e32 v51, v51
	v_add_f32_e32 v65, v49, v65
	v_exp_f32_e32 v36, v36
	v_add_f32_e32 v65, v34, v65
	v_exp_f32_e32 v52, v52
	v_add_f32_e32 v65, v50, v65
	v_exp_f32_e32 v37, v37
	v_add_f32_e32 v65, v35, v65
	v_exp_f32_e32 v53, v53
	v_add_f32_e32 v65, v51, v65
	v_exp_f32_e32 v38, v38
	v_add_f32_e32 v65, v36, v65
	v_exp_f32_e32 v54, v54
	v_add_f32_e32 v65, v52, v65
	v_exp_f32_e32 v39, v39
	v_add_f32_e32 v65, v37, v65
	v_add_f32_e32 v65, v53, v65
	v_add_f32_e32 v65, v38, v65
	v_add_f32_e32 v65, v54, v65
	v_cvt_pk_bf16_f32 v32, v32, v33
	v_cvt_pk_bf16_f32 v33, v34, v35
	v_cvt_pk_bf16_f32 v34, v36, v37
	v_cvt_pk_bf16_f32 v35, v38, v39
	v_lshl_add_u32 v38, v111, 1, v80
	v_add_f32_e32 v65, v39, v65
	ds_read_b64 v[36:37], v66 offset:27648
	ds_read_b64 v[38:39], v38 offset:27648
	s_waitcnt lgkmcnt(0)
	v_mfma_f32_32x32x16_bf16 v[16:31], v[36:39], v[32:35], v[16:31]
	v_lshl_add_u32 v36, v110, 1, v67
	v_lshl_add_u32 v38, v109, 1, v67
	ds_read_b64 v[36:37], v36 offset:27648
	ds_read_b64 v[38:39], v38 offset:27648
	v_exp_f32_e32 v40, v40
	v_exp_f32_e32 v41, v41
	v_exp_f32_e32 v42, v42
	s_waitcnt lgkmcnt(0)
	v_mfma_f32_32x32x16_bf16 v[0:15], v[36:39], v[32:35], v[0:15]
	v_lshl_add_u32 v36, v108, 1, v80
	v_lshl_add_u32 v38, v107, 1, v80
	v_exp_f32_e32 v43, v43
	v_exp_f32_e32 v44, v44
	v_exp_f32_e32 v45, v45
	v_exp_f32_e32 v46, v46
	v_exp_f32_e32 v47, v47
	v_cvt_pk_bf16_f32 v32, v40, v41
	v_cvt_pk_bf16_f32 v33, v42, v43
	v_cvt_pk_bf16_f32 v34, v44, v45
	v_cvt_pk_bf16_f32 v35, v46, v47
	ds_read_b64 v[36:37], v36 offset:27648
	ds_read_b64 v[38:39], v38 offset:27648
	s_waitcnt lgkmcnt(0)
	v_mfma_f32_32x32x16_bf16 v[16:31], v[36:39], v[32:35], v[16:31]
	v_lshl_add_u32 v36, v106, 1, v67
	v_lshl_add_u32 v38, v105, 1, v67
	ds_read_b64 v[36:37], v36 offset:27648
	ds_read_b64 v[38:39], v38 offset:27648
	v_exp_f32_e32 v55, v55
	v_exp_f32_e32 v56, v56
	v_exp_f32_e32 v57, v57
	s_waitcnt lgkmcnt(0)
	v_mfma_f32_32x32x16_bf16 v[0:15], v[36:39], v[32:35], v[0:15]
	v_lshl_add_u32 v38, v104, 1, v80
	v_cvt_pk_bf16_f32 v32, v48, v49
	v_cvt_pk_bf16_f32 v33, v50, v51
	v_cvt_pk_bf16_f32 v34, v52, v53
	v_cvt_pk_bf16_f32 v35, v54, v55
	ds_read_b64 v[36:37], v66 offset:27712
	ds_read_b64 v[38:39], v38 offset:27648
	s_waitcnt lgkmcnt(0)
; #define MFMA32(a, b, c) __builtin_amdgcn_mfma_f32_32x32x16_bf16((a), (b), (c), 0, 0, 0)
; DI unsigned pack2(float a, float b) { unsigned r; asm volatile("v_cvt_pk_bf16_f32 %0, %1, %2" : "=v"(r) : "v"(a), "v"(b)); return r; }
; template <int D>
; DI void attn_pass(const bfr* __restrict__ P, int b, int tq_wave, int qcol, int kcol, int vcol, int key0, int nkt, char* smem, f32x16 (&o)[2]) {
;     ...
; #pragma unroll
;         for (int dt = 0; dt < 2; ++dt) {
;           const int vsw = (((dt * 32 + r) >> 3) & 7) << 3;
;           const bfr* vrow = sV + (dt * 32 + r) * 72;
;           s16x4 lo = *(const s16x4*)(vrow + ((t2 * 32 + 16 * j + 4 * h) ^ vsw));
;           s16x4 hi = *(const s16x4*)(vrow + ((t2 * 32 + 16 * j + 4 * h + 8) ^ vsw));
;           bf16x8 vf = __builtin_shufflevector(lo, hi, 0, 1, 2, 3, 4, 5, 6, 7);
;           accO[dt] = MFMA32(vf, pf, accO[dt]);
;         }
;       }
;   }
;   lsum += __shfl_xor(lsum, 32);
;   float inv = 1.f / lsum;
; #pragma unroll
;   for (int i = 0; i < 16; ++i) { o[0][i] = accO[0][i] * inv; o[1][i] = accO[1][i] * inv; }
; }
; DI void attn_pass_da(const bfr* __restrict__ P, int b, int tq_wave, int qcol, int kcol, int vcol, int key0, int nkt, char* smem, f32x16 (&o0)[2], f32x16 (&o1)[2]) {
;   constexpr int KP = 72;
;   bfr* sbase = (bfr*)dynlds;
; DI void store_o(bfr* O, int m, int colbase, int h, const f32x16 (&o)[2]) {
; #pragma unroll
;   for (int dt = 0; dt < 2; ++dt)
; #pragma unroll
;     for (int g4 = 0; g4 < 4; ++g4) {
;       int dv = dt * 32 + 8 * g4 + 4 * h;
;       uint2 pk; pk.x = pack2(o[dt][4 * g4], o[dt][4 * g4 + 1]); pk.y = pack2(o[dt][4 * g4 + 2], o[dt][4 * g4 + 3]);
;       *(uint2*)(O + (size_t)m * DM + colbase + dv) = pk;
;     }
	v_mfma_f32_32x32x16_bf16 v[16:31], v[36:39], v[32:35], v[16:31]
	v_lshl_add_u32 v36, v103, 1, v67
	v_lshl_add_u32 v38, v102, 1, v67
	ds_read_b64 v[36:37], v36 offset:27648
	ds_read_b64 v[38:39], v38 offset:27648
	v_exp_f32_e32 v58, v58
	v_exp_f32_e32 v59, v59
	v_exp_f32_e32 v60, v60
	s_waitcnt lgkmcnt(0)
	v_mfma_f32_32x32x16_bf16 v[0:15], v[36:39], v[32:35], v[0:15]
	v_lshl_add_u32 v36, v100, 1, v80
	v_lshl_add_u32 v38, v101, 1, v80
	v_exp_f32_e32 v61, v61
	v_exp_f32_e32 v62, v62
	v_exp_f32_e32 v63, v63
	v_cvt_pk_bf16_f32 v32, v56, v57
	v_cvt_pk_bf16_f32 v33, v58, v59
	v_cvt_pk_bf16_f32 v34, v60, v61
	v_cvt_pk_bf16_f32 v35, v62, v63
	ds_read_b64 v[36:37], v36 offset:27648
	ds_read_b64 v[38:39], v38 offset:27648
	v_add_f32_e32 v65, v55, v65
	v_add_f32_e32 v65, v40, v65
	v_add_f32_e32 v65, v56, v65
	v_add_f32_e32 v65, v41, v65
	v_add_f32_e32 v65, v57, v65
	v_add_f32_e32 v65, v42, v65
	v_add_f32_e32 v65, v58, v65
	v_add_f32_e32 v65, v43, v65
	v_add_f32_e32 v65, v59, v65
	s_waitcnt lgkmcnt(0)
	v_mfma_f32_32x32x16_bf16 v[16:31], v[36:39], v[32:35], v[16:31]
	v_lshl_add_u32 v36, v99, 1, v67
	v_lshl_add_u32 v38, v98, 1, v67
	v_add_f32_e32 v65, v44, v65
	ds_read_b64 v[36:37], v36 offset:27648
	ds_read_b64 v[38:39], v38 offset:27648
	v_add_f32_e32 v65, v60, v65
	v_add_f32_e32 v65, v45, v65
	v_add_f32_e32 v65, v61, v65
	v_add_f32_e32 v65, v46, v65
	v_add_f32_e32 v65, v62, v65
	v_add_f32_e32 v65, v47, v65
	v_add_f32_e32 v65, v63, v65
	v_fmac_f32_e32 v65, v113, v64
	s_waitcnt lgkmcnt(0)
	v_mfma_f32_32x32x16_bf16 v[0:15], v[36:39], v[32:35], v[0:15]
	ds_bpermute_b32 v32, v91, v65
	s_load_dwordx4 s[12:15], s[0:1], 0x100
	s_waitcnt lgkmcnt(0)
	v_add_f32_e32 v32, v65, v32
	v_div_scale_f32 v33, s[10:11], v32, v32, 1.0
	v_rcp_f32_e32 v34, v33
	s_mov_b64 s[10:11], 0x2b7c700
	v_fma_f32 v35, -v33, v34, 1.0
	v_fmac_f32_e32 v34, v35, v34
	v_div_scale_f32 v35, vcc, 1.0, v32, 1.0
	v_mul_f32_e32 v36, v35, v34
	v_fma_f32 v37, -v33, v36, v35
	v_fmac_f32_e32 v36, v37, v34
	v_fma_f32 v33, -v33, v36, v35
	v_div_fmas_f32 v33, v33, v34, v36
	v_div_fixup_f32 v32, v33, v32, 1.0
	v_mul_f32_e32 v33, v0, v32
	v_and_or_b32 v0, v89, 31, v97
	v_mul_f32_e32 v34, v1, v32
	v_ashrrev_i32_e32 v1, 31, v0
	v_lshlrev_b64 v[0:1], 11, v[0:1]
	v_mul_f32_e32 v37, v4, v32
	v_lshl_add_u64 v[0:1], s[14:15], 0, v[0:1]
	v_lshrrev_b32_e32 v4, 2, v89
	v_lshl_add_u64 v[0:1], v[0:1], 0, v[152:153]
	v_and_b32_e32 v152, 8, v4
	v_lshl_add_u64 v[0:1], v[0:1], 0, v[152:153]
	v_mul_f32_e32 v38, v5, v32
	v_lshl_add_u64 v[4:5], v[0:1], 0, s[10:11]
	s_mov_b32 s10, 0x2b7c000
	v_add_co_u32_e32 v0, vcc, s10, v0
	v_mul_f32_e32 v16, v16, v32
	s_nop 0
	v_addc_co_u32_e32 v1, vcc, 0, v1, vcc
	v_mul_f32_e32 v17, v17, v32
	v_mul_f32_e32 v18, v18, v32
	v_mul_f32_e32 v35, v2, v32
	v_mul_f32_e32 v19, v19, v32
	v_mul_f32_e32 v36, v3, v32
	v_mul_f32_e32 v20, v20, v32
	v_mul_f32_e32 v21, v21, v32
	v_mul_f32_e32 v22, v22, v32
	v_mul_f32_e32 v23, v23, v32
	v_cvt_pk_bf16_f32 v2, v16, v17
	v_cvt_pk_bf16_f32 v3, v18, v19
	global_store_dwordx2 v[0:1], v[2:3], off offset:1792
	v_cvt_pk_bf16_f32 v0, v20, v21
	v_cvt_pk_bf16_f32 v1, v22, v23
	v_mul_f32_e32 v24, v24, v32
	v_mul_f32_e32 v25, v25, v32
	v_mul_f32_e32 v26, v26, v32
	v_mul_f32_e32 v27, v27, v32
	global_store_dwordx2 v[4:5], v[0:1], off offset:16
	v_cvt_pk_bf16_f32 v0, v24, v25
	v_cvt_pk_bf16_f32 v1, v26, v27
	v_mul_f32_e32 v28, v28, v32
	v_mul_f32_e32 v29, v29, v32
	v_mul_f32_e32 v30, v30, v32
	v_mul_f32_e32 v31, v31, v32
	global_store_dwordx2 v[4:5], v[0:1], off offset:32
	v_cvt_pk_bf16_f32 v0, v28, v29
	v_cvt_pk_bf16_f32 v1, v30, v31
	global_store_dwordx2 v[4:5], v[0:1], off offset:48
	v_cvt_pk_bf16_f32 v0, v33, v34
	v_cvt_pk_bf16_f32 v1, v35, v36
	v_mul_f32_e32 v6, v6, v32
	v_mul_f32_e32 v7, v7, v32
	global_store_dwordx2 v[4:5], v[0:1], off offset:64
	v_cvt_pk_bf16_f32 v0, v37, v38
	v_cvt_pk_bf16_f32 v1, v6, v7
	v_mul_f32_e32 v8, v8, v32
	v_mul_f32_e32 v9, v9, v32
	v_mul_f32_e32 v10, v10, v32
	v_mul_f32_e32 v11, v11, v32
	global_store_dwordx2 v[4:5], v[0:1], off offset:80
	v_cvt_pk_bf16_f32 v0, v8, v9
	v_cvt_pk_bf16_f32 v1, v10, v11
	v_mul_f32_e32 v12, v12, v32
	v_mul_f32_e32 v13, v13, v32
	v_mul_f32_e32 v14, v14, v32
	v_mul_f32_e32 v15, v15, v32
	global_store_dwordx2 v[4:5], v[0:1], off offset:96
	v_cvt_pk_bf16_f32 v0, v12, v13
	v_cvt_pk_bf16_f32 v1, v14, v15
	global_store_dwordx2 v[4:5], v[0:1], off offset:112

; DI void attn_pass_da(const bfr* __restrict__ P, int b, int tq_wave, int qcol, int kcol, int vcol, int key0, int nkt, char* smem, f32x16 (&o0)[2], f32x16 (&o1)[2]) {
;     ...
;   for (int kt = 0; kt < nkt; ++kt) {
;     bfr* sK = sbase + (kt & 1) * 9216;
;     bfr* sV = sK + 64 * 72;
;     { int c = gt, row = c >> 3, kc = c & 7; *(u32x4*)(sK + row * KP + kc * 8) = kreg[0]; }
;     for (int i = 0; i < 1; ++i) {
;       int c = gt, row = c >> 3, kc = c & 7;
;       unsigned wds[4] = {vreg[i].x, vreg[i].y, vreg[i].z, vreg[i].w};
; #pragma unroll
;       for (int e = 0; e < 4; ++e) {
;         sV[(kc * 8 + 2 * e) * 72 + (row ^ (kc << 3))] = (bfr)(wds[e] & 0xffffu);
;         sV[(kc * 8 + 2 * e + 1) * 72 + (row ^ (kc << 3))] = (bfr)(wds[e] >> 16);
;       }
;     }
;     __syncthreads();
;     if (kt + 1 < nkt) {
;       const bfr* Pn = Pb + (size_t)(kt + 1) * 64 * PW;
;       { int c = gt, row = c >> 3, kc = c & 7; kreg[0] = *(const u32x4*)(Pn + (size_t)row * PW + kcol + kc * 8); vreg[0] = *(const u32x4*)(Pn + (size_t)row * PW + vcol + kc * 8); }
;     }
;     f32x16 s0[2], s1[2];
; #pragma unroll
;     for (int t2 = 0; t2 < 2; ++t2) {
; #pragma unroll
;       for (int i = 0; i < 16; ++i) { s0[t2][i] = 0.f; s1[t2][i] = 0.f; }
; #pragma unroll
;       for (int ks = 0; ks < 2; ++ks) {
;         bf16x8 a0 = *(const bf16x8*)(sK + (t2 * 32 + r) * KP + ks * 16 + h * 8);
;         bf16x8 a1 = *(const bf16x8*)(sK + (t2 * 32 + r) * KP + 32 + ks * 16 + h * 8);
;         s0[t2] = MFMA32(a0, qf[ks], s0[t2]);
;         s1[t2] = MFMA32(a1, qf[2 + ks], s1[t2]);
;       }
;     }
;     float mx0 = s0[0][0], mx1 = s1[0][0];
; #pragma unroll
;     for (int i = 0; i < 16; ++i) { mx0 = fmaxf(mx0, fmaxf(s0[0][i], s0[1][i])); mx1 = fmaxf(mx1, fmaxf(s1[0][i], s1[1][i])); }
;     mx0 = fmaxf(mx0, __shfl_xor(mx0, 32)); mx1 = fmaxf(mx1, __shfl_xor(mx1, 32));
;     const float mn0 = fmaxf(m0, mx0), mn1 = fmaxf(m1, mx1);
;     const float al0 = __builtin_amdgcn_exp2f(m0 - mn0), al1 = __builtin_amdgcn_exp2f(m1 - mn1);
;     m0 = mn0; m1 = mn1;
;     float ps0 = 0.f, ps1 = 0.f;
; #pragma unroll
;     for (int i = 0; i < 16; ++i) {
;       s0[0][i] = __builtin_amdgcn_exp2f(s0[0][i] - mn0); ps0 += s0[0][i];
;       s0[1][i] = __builtin_amdgcn_exp2f(s0[1][i] - mn0); ps0 += s0[1][i];
;       s1[0][i] = __builtin_amdgcn_exp2f(s1[0][i] - mn1); ps1 += s1[0][i];
.LBB0_408:
	s_bitcmp1_b32 s14, 0
	s_cselect_b32 s15, 0x4800, 0
	s_add_i32 s15, s15, 0
	v_add3_u32 v64, s15, v206, v152
	v_add_u32_e32 v194, s15, v205
	s_waitcnt vmcnt(1)
	ds_write_b128 v64, v[148:151]
	v_add3_u32 v64, s15, v207, v208
	v_add3_u32 v65, s15, v208, v207
	v_add_u32_e32 v100, v194, v204
	s_waitcnt vmcnt(0)
	ds_write_b16 v64, v144 offset:9216
	ds_write_b16_d16_hi v65, v144 offset:9360
	ds_write_b16 v64, v145 offset:9504
	ds_write_b16_d16_hi v65, v145 offset:9648
	ds_write_b16 v64, v146 offset:9792
	ds_write_b16_d16_hi v65, v146 offset:9936
	ds_write_b16 v64, v147 offset:10080
	ds_write_b16_d16_hi v65, v147 offset:10224
	s_waitcnt lgkmcnt(0)
	s_barrier
	global_load_dwordx4 v[148:151], v[158:159], off
	global_load_dwordx4 v[144:147], v[158:159], off offset:512
	ds_read_b128 v[64:67], v100 offset:64
	ds_read_b128 v[68:71], v100
	ds_read_b128 v[96:99], v100 offset:32
	ds_read_b128 v[100:103], v100 offset:96
	s_waitcnt lgkmcnt(2)
	v_mfma_f32_32x32x16_bf16 v[80:95], v[68:71], v[140:143], 0
	v_add_u32_e32 v195, s15, v211
	v_add_u32_e32 v192, v195, v204
	v_mov_b32_e32 v160, v209
	v_mov_b32_e32 v161, v210
	s_add_i32 s14, s14, 1
	v_lshl_add_u64 v[158:159], v[158:159], 0, s[16:17]
	s_cmp_lg_u32 s14, 3
	v_mfma_f32_32x32x16_bf16 v[64:79], v[64:67], v[136:139], 0
	s_waitcnt lgkmcnt(1)
	v_mfma_f32_32x32x16_bf16 v[80:95], v[96:99], v[132:135], v[80:95]
	s_waitcnt lgkmcnt(0)
	v_mfma_f32_32x32x16_bf16 v[64:79], v[100:103], v[128:131], v[64:79]
	ds_read_b128 v[96:99], v192 offset:64
	ds_read_b128 v[100:103], v192
	ds_read_b128 v[212:215], v192 offset:32
	ds_read_b128 v[216:219], v192 offset:96
	s_nop 5
	v_max3_f32 v209, v80, v81, v82
	v_max3_f32 v209, v209, v83, v84
	v_max3_f32 v193, v64, v65, v66
	s_waitcnt lgkmcnt(2)
	v_mfma_f32_32x32x16_bf16 v[112:127], v[100:103], v[140:143], 0
	v_mfma_f32_32x32x16_bf16 v[96:111], v[96:99], v[136:139], 0
	s_waitcnt lgkmcnt(1)
	v_mfma_f32_32x32x16_bf16 v[112:127], v[212:215], v[132:135], v[112:127]
	v_max3_f32 v193, v193, v67, v68
	v_max3_f32 v209, v209, v85, v86
	s_waitcnt lgkmcnt(0)
	v_mfma_f32_32x32x16_bf16 v[96:111], v[216:219], v[128:131], v[96:111]
	v_max3_f32 v193, v193, v69, v70
	v_max3_f32 v209, v209, v87, v88
	v_max3_f32 v193, v193, v71, v72
	v_max3_f32 v209, v209, v89, v90
	v_max3_f32 v193, v193, v73, v74
	v_max3_f32 v209, v209, v91, v92
	v_max3_f32 v193, v193, v75, v76
	v_max3_f32 v209, v209, v93, v94
	v_max3_f32 v193, v193, v77, v78
	v_max3_f32 v209, v209, v95, v112
	v_max3_f32 v209, v209, v113, v114
	v_max3_f32 v209, v209, v115, v116
	v_max3_f32 v209, v209, v117, v118
	v_max3_f32 v209, v209, v119, v120
	v_max3_f32 v209, v209, v121, v122
	v_max3_f32 v209, v209, v123, v124
	v_max3_f32 v209, v209, v125, v126
	v_max_f32_e32 v192, v209, v127
	v_max3_f32 v193, v193, v79, v96
	v_max3_f32 v193, v193, v97, v98
	v_max3_f32 v193, v193, v99, v100
	v_max3_f32 v193, v193, v101, v102
	v_max3_f32 v193, v193, v103, v104
	v_max3_f32 v193, v193, v105, v106
	v_max3_f32 v193, v193, v107, v108
	v_max3_f32 v193, v193, v109, v110
	v_max_f32_e32 v193, v193, v111
	ds_bpermute_b32 v210, v166, v193
	ds_bpermute_b32 v209, v166, v192
	s_waitcnt lgkmcnt(1)
	v_max3_f32 v210, v161, v193, v210
	s_waitcnt lgkmcnt(0)
	v_max3_f32 v209, v160, v192, v209
	v_pk_add_f32 v[64:65], v[64:65], v[210:211] op_sel_hi:[1,0] neg_lo:[0,1] neg_hi:[0,1]
	v_pk_add_f32 v[80:81], v[80:81], v[208:209] op_sel:[0,1] op_sel_hi:[1,1] neg_lo:[0,1] neg_hi:[0,1]
	v_exp_f32_e32 v193, v64
	v_pk_add_f32 v[96:97], v[96:97], v[210:211] op_sel_hi:[1,0] neg_lo:[0,1] neg_hi:[0,1]
	v_exp_f32_e32 v192, v80
	v_pk_add_f32 v[112:113], v[112:113], v[208:209] op_sel:[0,1] op_sel_hi:[1,1] neg_lo:[0,1] neg_hi:[0,1]
	v_exp_f32_e32 v213, v96
	v_exp_f32_e32 v212, v112
	v_exp_f32_e32 v80, v81
	v_exp_f32_e32 v96, v113
	v_exp_f32_e32 v81, v65
	v_exp_f32_e32 v97, v97
	v_pk_add_f32 v[82:83], v[82:83], v[208:209] op_sel:[0,1] op_sel_hi:[1,1] neg_lo:[0,1] neg_hi:[0,1]
	v_exp_f32_e32 v112, v82
	v_pk_add_f32 v[114:115], v[114:115], v[208:209] op_sel:[0,1] op_sel_hi:[1,1] neg_lo:[0,1] neg_hi:[0,1]
	v_exp_f32_e32 v214, v114
	v_pk_add_f32 v[66:67], v[66:67], v[210:211] op_sel_hi:[1,0] neg_lo:[0,1] neg_hi:[0,1]
	v_exp_f32_e32 v113, v66
	v_pk_add_f32 v[98:99], v[98:99], v[210:211] op_sel_hi:[1,0] neg_lo:[0,1] neg_hi:[0,1]
	v_exp_f32_e32 v215, v98
	v_exp_f32_e32 v82, v83
	v_exp_f32_e32 v98, v115
	v_exp_f32_e32 v83, v67
	v_exp_f32_e32 v99, v99
	v_pk_add_f32 v[84:85], v[84:85], v[208:209] op_sel:[0,1] op_sel_hi:[1,1] neg_lo:[0,1] neg_hi:[0,1]
	v_exp_f32_e32 v114, v84
	v_pk_add_f32 v[116:117], v[116:117], v[208:209] op_sel:[0,1] op_sel_hi:[1,1] neg_lo:[0,1] neg_hi:[0,1]
	v_exp_f32_e32 v216, v116
	v_pk_add_f32 v[68:69], v[68:69], v[210:211] op_sel_hi:[1,0] neg_lo:[0,1] neg_hi:[0,1]
	v_exp_f32_e32 v115, v68
	v_pk_add_f32 v[100:101], v[100:101], v[210:211] op_sel_hi:[1,0] neg_lo:[0,1] neg_hi:[0,1]
	v_exp_f32_e32 v217, v100
	v_exp_f32_e32 v84, v85
	v_exp_f32_e32 v100, v117
	v_exp_f32_e32 v85, v69
	v_exp_f32_e32 v101, v101
	v_pk_add_f32 v[86:87], v[86:87], v[208:209] op_sel:[0,1] op_sel_hi:[1,1] neg_lo:[0,1] neg_hi:[0,1]
	v_exp_f32_e32 v116, v86
	v_pk_add_f32 v[118:119], v[118:119], v[208:209] op_sel:[0,1] op_sel_hi:[1,1] neg_lo:[0,1] neg_hi:[0,1]
	v_exp_f32_e32 v218, v118
	v_pk_add_f32 v[70:71], v[70:71], v[210:211] op_sel_hi:[1,0] neg_lo:[0,1] neg_hi:[0,1]
	v_exp_f32_e32 v117, v70
	v_pk_add_f32 v[102:103], v[102:103], v[210:211] op_sel_hi:[1,0] neg_lo:[0,1] neg_hi:[0,1]
	v_exp_f32_e32 v219, v102
	v_exp_f32_e32 v70, v87
	v_exp_f32_e32 v86, v119
	v_exp_f32_e32 v71, v71
	v_exp_f32_e32 v87, v103
	v_pk_add_f32 v[88:89], v[88:89], v[208:209] op_sel:[0,1] op_sel_hi:[1,1] neg_lo:[0,1] neg_hi:[0,1]
; DI void attn_pass_da(const bfr* __restrict__ P, int b, int tq_wave, int qcol, int kcol, int vcol, int key0, int nkt, char* smem, f32x16 (&o0)[2], f32x16 (&o1)[2]) {
;     ...
;     const float mn0 = fmaxf(m0, mx0), mn1 = fmaxf(m1, mx1);
;     const float al0 = __builtin_amdgcn_exp2f(m0 - mn0), al1 = __builtin_amdgcn_exp2f(m1 - mn1);
;     m0 = mn0; m1 = mn1;
;     float ps0 = 0.f, ps1 = 0.f;
; #pragma unroll
;     for (int i = 0; i < 16; ++i) {
;       s0[0][i] = __builtin_amdgcn_exp2f(s0[0][i] - mn0); ps0 += s0[0][i];
;       s0[1][i] = __builtin_amdgcn_exp2f(s0[1][i] - mn0); ps0 += s0[1][i];
;       s1[0][i] = __builtin_amdgcn_exp2f(s1[0][i] - mn1); ps1 += s1[0][i];
;       s1[1][i] = __builtin_amdgcn_exp2f(s1[1][i] - mn1); ps1 += s1[1][i];
;     }
;     l0 = l0 * al0 + ps0; l1 = l1 * al1 + ps1;
; #pragma unroll
;     for (int i = 0; i < 16; ++i) { acc0[0][i] *= al0; acc0[1][i] *= al0; acc1[0][i] *= al1; acc1[1][i] *= al1; }
	v_exp_f32_e32 v102, v88
	v_pk_add_f32 v[120:121], v[120:121], v[208:209] op_sel:[0,1] op_sel_hi:[1,1] neg_lo:[0,1] neg_hi:[0,1]
	v_exp_f32_e32 v118, v120
	v_pk_add_f32 v[72:73], v[72:73], v[210:211] op_sel_hi:[1,0] neg_lo:[0,1] neg_hi:[0,1]
	v_exp_f32_e32 v103, v72
	v_pk_add_f32 v[104:105], v[104:105], v[210:211] op_sel_hi:[1,0] neg_lo:[0,1] neg_hi:[0,1]
	v_exp_f32_e32 v119, v104
	v_exp_f32_e32 v88, v89
	v_exp_f32_e32 v104, v121
	v_exp_f32_e32 v89, v73
	v_exp_f32_e32 v105, v105
	v_pk_add_f32 v[90:91], v[90:91], v[208:209] op_sel:[0,1] op_sel_hi:[1,1] neg_lo:[0,1] neg_hi:[0,1]
	v_exp_f32_e32 v120, v90
	v_pk_add_f32 v[122:123], v[122:123], v[208:209] op_sel:[0,1] op_sel_hi:[1,1] neg_lo:[0,1] neg_hi:[0,1]
	v_exp_f32_e32 v220, v122
	v_pk_add_f32 v[74:75], v[74:75], v[210:211] op_sel_hi:[1,0] neg_lo:[0,1] neg_hi:[0,1]
	v_exp_f32_e32 v121, v74
	v_pk_add_f32 v[106:107], v[106:107], v[210:211] op_sel_hi:[1,0] neg_lo:[0,1] neg_hi:[0,1]
	v_exp_f32_e32 v221, v106
	v_exp_f32_e32 v90, v91
	v_exp_f32_e32 v106, v123
	v_exp_f32_e32 v91, v75
	v_exp_f32_e32 v107, v107
	v_pk_add_f32 v[92:93], v[92:93], v[208:209] op_sel:[0,1] op_sel_hi:[1,1] neg_lo:[0,1] neg_hi:[0,1]
	v_exp_f32_e32 v122, v92
	v_pk_add_f32 v[124:125], v[124:125], v[208:209] op_sel:[0,1] op_sel_hi:[1,1] neg_lo:[0,1] neg_hi:[0,1]
	v_exp_f32_e32 v222, v124
	v_pk_add_f32 v[76:77], v[76:77], v[210:211] op_sel_hi:[1,0] neg_lo:[0,1] neg_hi:[0,1]
	v_exp_f32_e32 v123, v76
	v_pk_add_f32 v[108:109], v[108:109], v[210:211] op_sel_hi:[1,0] neg_lo:[0,1] neg_hi:[0,1]
	v_exp_f32_e32 v223, v108
	v_exp_f32_e32 v92, v93
	v_exp_f32_e32 v108, v125
	v_exp_f32_e32 v93, v77
	v_exp_f32_e32 v109, v109
	v_pk_add_f32 v[94:95], v[94:95], v[208:209] op_sel:[0,1] op_sel_hi:[1,1] neg_lo:[0,1] neg_hi:[0,1]
	v_exp_f32_e32 v124, v94
	v_pk_add_f32 v[126:127], v[126:127], v[208:209] op_sel:[0,1] op_sel_hi:[1,1] neg_lo:[0,1] neg_hi:[0,1]
	v_exp_f32_e32 v224, v126
	v_pk_add_f32 v[78:79], v[78:79], v[210:211] op_sel_hi:[1,0] neg_lo:[0,1] neg_hi:[0,1]
	v_exp_f32_e32 v125, v78
	v_pk_add_f32 v[110:111], v[110:111], v[210:211] op_sel_hi:[1,0] neg_lo:[0,1] neg_hi:[0,1]
	v_exp_f32_e32 v225, v110
	v_exp_f32_e32 v94, v95
	v_exp_f32_e32 v110, v127
	v_exp_f32_e32 v95, v79
	v_exp_f32_e32 v111, v111
	v_pk_add_f32 v[64:65], v[192:193], 0 op_sel_hi:[1,0]
	v_sub_f32_e32 v161, v161, v210
	v_pk_add_f32 v[64:65], v[212:213], v[64:65]
	v_exp_f32_e32 v161, v161
	v_pk_add_f32 v[64:65], v[80:81], v[64:65]
	v_lshl_add_u32 v74, v180, 1, v194
	v_pk_add_f32 v[64:65], v[96:97], v[64:65]
	v_lshl_add_u32 v76, v179, 1, v195
	v_pk_add_f32 v[64:65], v[112:113], v[64:65]
	v_lshl_add_u32 v78, v178, 1, v195
	v_pk_add_f32 v[64:65], v[214:215], v[64:65]
	v_sub_f32_e32 v160, v160, v209
	v_pk_add_f32 v[64:65], v[82:83], v[64:65]
	v_exp_f32_e32 v160, v160
	v_pk_add_f32 v[64:65], v[98:99], v[64:65]
	v_pk_mul_f32 v[62:63], v[62:63], v[160:161] op_sel_hi:[1,0]
	v_pk_add_f32 v[64:65], v[114:115], v[64:65]
	v_pk_mul_f32 v[60:61], v[60:61], v[160:161] op_sel_hi:[1,0]
	v_pk_add_f32 v[64:65], v[216:217], v[64:65]
	v_pk_mul_f32 v[58:59], v[58:59], v[160:161] op_sel_hi:[1,0]
	v_pk_add_f32 v[64:65], v[84:85], v[64:65]
	v_pk_mul_f32 v[56:57], v[56:57], v[160:161] op_sel_hi:[1,0]
	v_pk_add_f32 v[64:65], v[100:101], v[64:65]
	v_pk_mul_f32 v[54:55], v[54:55], v[160:161] op_sel_hi:[1,0]
	v_pk_add_f32 v[64:65], v[116:117], v[64:65]
	v_pk_mul_f32 v[52:53], v[52:53], v[160:161] op_sel_hi:[1,0]
	v_pk_add_f32 v[64:65], v[218:219], v[64:65]
	v_pk_mul_f32 v[50:51], v[50:51], v[160:161] op_sel_hi:[1,0]
	v_pk_add_f32 v[64:65], v[70:71], v[64:65]
	v_pk_mul_f32 v[48:49], v[48:49], v[160:161] op_sel_hi:[1,0]
	v_pk_add_f32 v[64:65], v[86:87], v[64:65]
	v_pk_mul_f32 v[30:31], v[30:31], v[160:161] op_sel_hi:[1,0]
	v_pk_add_f32 v[64:65], v[102:103], v[64:65]
	v_pk_mul_f32 v[28:29], v[28:29], v[160:161] op_sel_hi:[1,0]
	v_pk_add_f32 v[64:65], v[118:119], v[64:65]
	v_pk_mul_f32 v[26:27], v[26:27], v[160:161] op_sel_hi:[1,0]
	v_pk_add_f32 v[64:65], v[88:89], v[64:65]
	v_pk_mul_f32 v[24:25], v[24:25], v[160:161] op_sel_hi:[1,0]
	v_pk_add_f32 v[64:65], v[104:105], v[64:65]
	v_pk_mul_f32 v[22:23], v[22:23], v[160:161] op_sel_hi:[1,0]
	v_pk_add_f32 v[64:65], v[120:121], v[64:65]
	v_pk_mul_f32 v[20:21], v[20:21], v[160:161] op_sel_hi:[1,0]
	v_pk_add_f32 v[126:127], v[220:221], v[64:65]
	v_cvt_pk_bf16_f32 v64, v192, v80
	v_cvt_pk_bf16_f32 v65, v112, v82
	v_lshl_add_u32 v112, v181, 1, v194
	v_cvt_pk_bf16_f32 v66, v114, v84
	v_cvt_pk_bf16_f32 v67, v116, v70
	v_cvt_pk_bf16_f32 v68, v193, v81
	v_cvt_pk_bf16_f32 v69, v113, v83
	v_cvt_pk_bf16_f32 v70, v115, v85
	v_cvt_pk_bf16_f32 v71, v117, v71
	ds_read_b64 v[72:73], v112 offset:9216
	ds_read_b64 v[74:75], v74 offset:9216
	ds_read_b64 v[76:77], v76 offset:9216
	ds_read_b64 v[78:79], v78 offset:9216
	v_mov_b32_e32 v82, v161
	v_pk_mul_f32 v[46:47], v[46:47], v[82:83] op_sel_hi:[1,0]
	v_pk_mul_f32 v[44:45], v[44:45], v[82:83] op_sel_hi:[1,0]
	v_pk_mul_f32 v[42:43], v[42:43], v[82:83] op_sel_hi:[1,0]
	v_pk_mul_f32 v[40:41], v[40:41], v[82:83] op_sel_hi:[1,0]
	v_pk_mul_f32 v[38:39], v[38:39], v[82:83] op_sel_hi:[1,0]
	v_pk_mul_f32 v[36:37], v[36:37], v[82:83] op_sel_hi:[1,0]
	v_pk_mul_f32 v[34:35], v[34:35], v[82:83] op_sel_hi:[1,0]
	v_pk_mul_f32 v[32:33], v[32:33], v[82:83] op_sel_hi:[1,0]
	v_pk_mul_f32 v[14:15], v[14:15], v[82:83] op_sel_hi:[1,0]
	v_pk_mul_f32 v[12:13], v[12:13], v[82:83] op_sel_hi:[1,0]
	v_pk_mul_f32 v[10:11], v[10:11], v[82:83] op_sel_hi:[1,0]
	v_pk_mul_f32 v[8:9], v[8:9], v[82:83] op_sel_hi:[1,0]
	v_pk_mul_f32 v[6:7], v[6:7], v[82:83] op_sel_hi:[1,0]
	v_pk_mul_f32 v[4:5], v[4:5], v[82:83] op_sel_hi:[1,0]
	v_pk_mul_f32 v[2:3], v[2:3], v[82:83] op_sel_hi:[1,0]
	v_pk_mul_f32 v[0:1], v[0:1], v[82:83] op_sel_hi:[1,0]
	v_pk_add_f32 v[82:83], v[90:91], v[126:127]
	s_waitcnt lgkmcnt(2)
; #define MFMA32(a, b, c) __builtin_amdgcn_mfma_f32_32x32x16_bf16((a), (b), (c), 0, 0, 0)
; DI void attn_pass_da(const bfr* __restrict__ P, int b, int tq_wave, int qcol, int kcol, int vcol, int key0, int nkt, char* smem, f32x16 (&o0)[2], f32x16 (&o1)[2]) {
;     ...
;   for (int kt = 0; kt < nkt; ++kt) {
;     bfr* sK = sbase + (kt & 1) * 9216;
;     bfr* sV = sK + 64 * 72;
;     { int c = gt, row = c >> 3, kc = c & 7; *(u32x4*)(sK + row * KP + kc * 8) = kreg[0]; }
;     for (int i = 0; i < 1; ++i) {
;       int c = gt, row = c >> 3, kc = c & 7;
;       unsigned wds[4] = {vreg[i].x, vreg[i].y, vreg[i].z, vreg[i].w};
; #pragma unroll
;       for (int e = 0; e < 4; ++e) {
;         sV[(kc * 8 + 2 * e) * 72 + (row ^ (kc << 3))] = (bfr)(wds[e] & 0xffffu);
;         sV[(kc * 8 + 2 * e + 1) * 72 + (row ^ (kc << 3))] = (bfr)(wds[e] >> 16);
;       }
;     }
;     __syncthreads();
;     if (kt + 1 < nkt) {
;       const bfr* Pn = Pb + (size_t)(kt + 1) * 64 * PW;
;     ...
;     l0 = l0 * al0 + ps0; l1 = l1 * al1 + ps1;
; #pragma unroll
;     for (int i = 0; i < 16; ++i) { acc0[0][i] *= al0; acc0[1][i] *= al0; acc1[0][i] *= al1; acc1[1][i] *= al1; }
; #pragma unroll
;     for (int t2 = 0; t2 < 2; ++t2)
; #pragma unroll
;       for (int j = 0; j < 2; ++j) {
;         u32x4 pk0, pk1;
;         pk0.x = pack2(s0[t2][8 * j + 0], s0[t2][8 * j + 1]); pk0.y = pack2(s0[t2][8 * j + 2], s0[t2][8 * j + 3]);
;         pk0.z = pack2(s0[t2][8 * j + 4], s0[t2][8 * j + 5]); pk0.w = pack2(s0[t2][8 * j + 6], s0[t2][8 * j + 7]);
;         pk1.x = pack2(s1[t2][8 * j + 0], s1[t2][8 * j + 1]); pk1.y = pack2(s1[t2][8 * j + 2], s1[t2][8 * j + 3]);
;         pk1.z = pack2(s1[t2][8 * j + 4], s1[t2][8 * j + 5]); pk1.w = pack2(s1[t2][8 * j + 6], s1[t2][8 * j + 7]);
;         const bf16x8 pf0 = __builtin_bit_cast(bf16x8, pk0), pf1 = __builtin_bit_cast(bf16x8, pk1);
; #pragma unroll
;         for (int dt = 0; dt < 2; ++dt) {
;           const int vsw = (((dt * 32 + r) >> 3) & 7) << 3;
;           const bfr* vrow = sV + (dt * 32 + r) * 72;
;           s16x4 lo = *(const s16x4*)(vrow + ((t2 * 32 + 16 * j + 4 * h) ^ vsw));
;           s16x4 hi = *(const s16x4*)(vrow + ((t2 * 32 + 16 * j + 4 * h + 8) ^ vsw));
;           bf16x8 vf = __builtin_shufflevector(lo, hi, 0, 1, 2, 3, 4, 5, 6, 7);
;           acc0[dt] = MFMA32(vf, pf0, acc0[dt]);
;           acc1[dt] = MFMA32(vf, pf1, acc1[dt]);
;         }
;       }
;   }
	v_mfma_f32_32x32x16_bf16 v[48:63], v[72:75], v[64:67], v[48:63]
	v_add_f32_e64 v82, v106, v82
	v_add_f32_e64 v83, v107, v83
	v_cvt_pk_bf16_f32 v80, v102, v88
	v_lshl_add_u32 v88, v177, 1, v194
	v_add_f32_e64 v82, v122, v82
	v_add_f32_e64 v83, v123, v83
	v_pk_mul_f32 v[18:19], v[18:19], v[160:161] op_sel_hi:[1,0]
	v_pk_add_f32 v[82:83], v[222:223], v[82:83]
	v_pk_mul_f32 v[16:17], v[16:17], v[160:161] op_sel_hi:[1,0]
	v_pk_add_f32 v[82:83], v[92:93], v[82:83]
	v_mfma_f32_32x32x16_bf16 v[32:47], v[72:75], v[68:71], v[32:47]
	v_add_f32_e64 v82, v108, v82
	v_add_f32_e64 v83, v109, v83
	v_cvt_pk_bf16_f32 v81, v120, v90
	v_lshl_add_u32 v102, v176, 1, v194
	v_add_f32_e64 v82, v124, v82
	v_add_f32_e64 v83, v125, v83
	v_lshl_add_u32 v113, v175, 1, v195
	v_pk_add_f32 v[82:83], v[224:225], v[82:83]
	v_lshl_add_u32 v114, v174, 1, v195
	v_pk_add_f32 v[82:83], v[94:95], v[82:83]
	s_waitcnt lgkmcnt(0)
	v_mfma_f32_32x32x16_bf16 v[16:31], v[76:79], v[64:67], v[16:31]
	v_add_f32_e64 v84, v110, v82
	v_add_f32_e64 v85, v111, v83
	v_cvt_pk_bf16_f32 v82, v122, v92
	v_cvt_pk_bf16_f32 v83, v124, v94
	v_cvt_pk_bf16_f32 v64, v103, v89
	v_cvt_pk_bf16_f32 v65, v121, v91
	v_cvt_pk_bf16_f32 v66, v123, v93
	v_cvt_pk_bf16_f32 v67, v125, v95
	v_mfma_f32_32x32x16_bf16 v[0:15], v[76:79], v[68:71], v[0:15]
	ds_read_b64 v[68:69], v88 offset:9216
	ds_read_b64 v[70:71], v102 offset:9216
	v_lshl_add_u32 v115, v173, 1, v194
	v_lshl_add_u32 v116, v172, 1, v195
	v_lshl_add_u32 v117, v171, 1, v195
	v_lshl_add_u32 v120, v169, 1, v194
	v_lshl_add_u32 v192, v170, 1, v194
	v_lshl_add_u32 v193, v168, 1, v195
	s_waitcnt lgkmcnt(0)
	v_mfma_f32_32x32x16_bf16 v[48:63], v[68:71], v[80:83], v[48:63]
	v_lshl_add_u32 v194, v167, 1, v195
	v_fma_f32 v156, v156, v160, v84
	v_fma_f32 v157, v157, v161, v85
	v_mfma_f32_32x32x16_bf16 v[32:47], v[68:71], v[64:67], v[32:47]
	ds_read_b64 v[68:69], v113 offset:9216
	ds_read_b64 v[70:71], v114 offset:9216
	s_waitcnt lgkmcnt(0)
	v_mfma_f32_32x32x16_bf16 v[16:31], v[68:71], v[80:83], v[16:31]
	v_mfma_f32_32x32x16_bf16 v[0:15], v[68:71], v[64:67], v[0:15]
	v_cvt_pk_bf16_f32 v64, v212, v96
	v_cvt_pk_bf16_f32 v65, v214, v98
	v_cvt_pk_bf16_f32 v66, v216, v100
	v_cvt_pk_bf16_f32 v67, v218, v86
	v_cvt_pk_bf16_f32 v68, v213, v97
	v_cvt_pk_bf16_f32 v69, v215, v99
	v_cvt_pk_bf16_f32 v70, v217, v101
	v_cvt_pk_bf16_f32 v71, v219, v87
	ds_read_b64 v[72:73], v112 offset:9280
	ds_read_b64 v[74:75], v115 offset:9216
	s_waitcnt lgkmcnt(0)
	v_mfma_f32_32x32x16_bf16 v[48:63], v[72:75], v[64:67], v[48:63]
	v_mfma_f32_32x32x16_bf16 v[32:47], v[72:75], v[68:71], v[32:47]
	ds_read_b64 v[72:73], v116 offset:9216
	ds_read_b64 v[74:75], v117 offset:9216
	s_waitcnt lgkmcnt(0)
	v_mfma_f32_32x32x16_bf16 v[16:31], v[72:75], v[64:67], v[16:31]
	v_cvt_pk_bf16_f32 v64, v118, v104
	v_cvt_pk_bf16_f32 v65, v220, v106
	v_cvt_pk_bf16_f32 v66, v222, v108
	v_cvt_pk_bf16_f32 v67, v224, v110
	v_mfma_f32_32x32x16_bf16 v[0:15], v[72:75], v[68:71], v[0:15]
	v_cvt_pk_bf16_f32 v68, v119, v105
	v_cvt_pk_bf16_f32 v69, v221, v107
	v_cvt_pk_bf16_f32 v70, v223, v109
	v_cvt_pk_bf16_f32 v71, v225, v111
	ds_read_b64 v[72:73], v120 offset:9216
	ds_read_b64 v[74:75], v192 offset:9216
	s_waitcnt lgkmcnt(0)
	v_mfma_f32_32x32x16_bf16 v[48:63], v[72:75], v[64:67], v[48:63]
	v_mfma_f32_32x32x16_bf16 v[32:47], v[72:75], v[68:71], v[32:47]
	ds_read_b64 v[72:73], v193 offset:9216
	ds_read_b64 v[74:75], v194 offset:9216
	s_waitcnt lgkmcnt(0)
	v_mfma_f32_32x32x16_bf16 v[16:31], v[72:75], v[64:67], v[16:31]
	v_mfma_f32_32x32x16_bf16 v[0:15], v[72:75], v[68:71], v[0:15]
	s_cbranch_scc1 .LBB0_408
	v_add3_u32 v64, 0, v206, v152
	s_waitcnt vmcnt(1)
	ds_write_b128 v64, v[148:151] offset:18432
	v_add3_u32 v64, 0, v207, v208
	v_add3_u32 v65, 0, v208, v207
	s_waitcnt vmcnt(0)
	ds_write_b16 v64, v144 offset:27648
	ds_write_b16_d16_hi v65, v144 offset:27792
	ds_write_b16 v64, v145 offset:27936
	ds_write_b16_d16_hi v65, v145 offset:28080
	ds_write_b16 v64, v146 offset:28224
	ds_write_b16_d16_hi v65, v146 offset:28368
	ds_write_b16 v64, v147 offset:28512
	ds_write_b16_d16_hi v65, v147 offset:28656
	v_add_u32_e32 v144, 0, v205
	v_add_u32_e32 v102, v144, v204
	s_waitcnt lgkmcnt(0)
	s_barrier
	ds_read_b128 v[64:67], v102 offset:18432
	ds_read_b128 v[96:99], v102 offset:18464
	s_waitcnt lgkmcnt(1)
	v_mfma_f32_32x32x16_bf16 v[64:79], v[64:67], v[140:143], 0
	ds_read_b128 v[80:83], v102 offset:18496
	v_readlane_b32 s14, v203, 16
	v_readlane_b32 s15, v203, 48
	v_add_u32_e32 v145, 0x1200, v144
	v_mov_b32_e32 v100, s14
	v_mov_b32_e32 v101, s15
	v_pk_add_f32 v[100:101], s[12:13], v[100:101]
	s_mov_b32 s14, 0x3fb8aa3b
	v_add_f32_e32 v146, v100, v101
	v_mul_f32_e32 v104, 0x3fb8aa3b, v146
	v_fma_f32 v105, v146, s14, -v104
	v_rndne_f32_e32 v106, v104
	s_waitcnt lgkmcnt(1)
	v_mfma_f32_32x32x16_bf16 v[64:79], v[96:99], v[132:135], v[64:79]
	v_fmac_f32_e32 v105, 0x32a5705f, v146
	v_sub_f32_e32 v96, v104, v106
	v_add_u32_e32 v147, v145, v204
	v_add_f32_e32 v104, v96, v105
	ds_read_b128 v[96:99], v147 offset:18432
	ds_read_b128 v[100:103], v102 offset:18528
	ds_read_b128 v[112:115], v147 offset:18496
	s_waitcnt lgkmcnt(3)
	v_mfma_f32_32x32x16_bf16 v[80:95], v[80:83], v[136:139], 0
	v_readlane_b32 s12, v202, 16
	v_readlane_b32 s13, v202, 48
	s_mov_b32 s15, 0xc2ce8ed0
	v_mov_b32_e32 v116, s12
	v_mov_b32_e32 v117, s13
	v_pk_add_f32 v[116:117], s[10:11], v[116:117]
	v_cmp_ngt_f32_e32 vcc, s15, v146
	s_waitcnt lgkmcnt(1)
	v_mfma_f32_32x32x16_bf16 v[80:95], v[100:103], v[128:131], v[80:95]
	v_exp_f32_e32 v100, v104
	v_cvt_i32_f32_e32 v101, v106
	v_add_f32_e32 v149, v116, v117
	v_mul_f32_e32 v150, 0x3fb8aa3b, v149
	v_rndne_f32_e32 v151, v150
	v_ldexp_f32 v148, v100, v101
	s_mov_b32 s10, 0x42b17218
	s_waitcnt lgkmcnt(0)
; #define MFMA32(a, b, c) __builtin_amdgcn_mfma_f32_32x32x16_bf16((a), (b), (c), 0, 0, 0)
; DI void attn_pass_da(const bfr* __restrict__ P, int b, int tq_wave, int qcol, int kcol, int vcol, int key0, int nkt, char* smem, f32x16 (&o0)[2], f32x16 (&o1)[2]) {
;     ...
;     for (int t2 = 0; t2 < 2; ++t2) {
; #pragma unroll
;       for (int i = 0; i < 16; ++i) { s0[t2][i] = 0.f; s1[t2][i] = 0.f; }
; #pragma unroll
;       for (int ks = 0; ks < 2; ++ks) {
;         bf16x8 a0 = *(const bf16x8*)(sK + (t2 * 32 + r) * KP + ks * 16 + h * 8);
;         bf16x8 a1 = *(const bf16x8*)(sK + (t2 * 32 + r) * KP + 32 + ks * 16 + h * 8);
;         s0[t2] = MFMA32(a0, qf[ks], s0[t2]);
;         s1[t2] = MFMA32(a1, qf[2 + ks], s1[t2]);
;       }
;     }
;     float mx0 = s0[0][0], mx1 = s1[0][0];
; #pragma unroll
;     for (int i = 0; i < 16; ++i) { mx0 = fmaxf(mx0, fmaxf(s0[0][i], s0[1][i])); mx1 = fmaxf(mx1, fmaxf(s1[0][i], s1[1][i])); }
;     mx0 = fmaxf(mx0, __shfl_xor(mx0, 32)); mx1 = fmaxf(mx1, __shfl_xor(mx1, 32));
	v_mfma_f32_32x32x16_bf16 v[112:127], v[112:115], v[136:139], 0
	v_fma_f32 v136, v149, s14, -v150
	v_fmac_f32_e32 v136, 0x32a5705f, v149
	v_sub_f32_e32 v137, v150, v151
	v_add_f32_e32 v136, v137, v136
	v_exp_f32_e32 v150, v136
	ds_read_b128 v[136:139], v147 offset:18528
	v_readlane_b32 s12, v253, 28
	v_mfma_f32_32x32x16_bf16 v[96:111], v[96:99], v[140:143], 0
	ds_read_b128 v[140:143], v147 offset:18464
	v_readlane_b32 s13, v253, 29
	s_waitcnt lgkmcnt(0)
	v_mfma_f32_32x32x16_bf16 v[96:111], v[140:143], v[132:135], v[96:111]
	v_max_f32_e32 v134, v82, v82
	v_max_f32_e32 v135, v67, v67
	v_cvt_i32_f32_e32 v132, v151
	v_cndmask_b32_e32 v133, 0, v148, vcc
	v_cmp_nlt_f32_e32 vcc, s10, v146
	v_ldexp_f32 v132, v150, v132
	v_mfma_f32_32x32x16_bf16 v[112:127], v[136:139], v[128:131], v[112:127]
	s_nop 4
	v_max_f32_e32 v128, v97, v97
	v_max_f32_e32 v129, v65, v65
	v_max_f32_e32 v128, v129, v128
	v_max_f32_e32 v130, v81, v81
	v_max_f32_e32 v131, v66, v66
	v_max3_f32 v128, v64, v96, v128
	v_cndmask_b32_e32 v133, v201, v133, vcc
	v_max_f32_e32 v129, v113, v113
	v_max_f32_e32 v129, v130, v129
	v_max_f32_e32 v130, v98, v98
	v_max_f32_e32 v130, v131, v130
	v_max_f32_e32 v131, v114, v114
	v_max_f32_e32 v131, v134, v131
	v_max_f32_e32 v134, v99, v99
	v_max_f32_e32 v134, v135, v134
	v_max3_f32 v128, v128, v130, v134
	v_max_f32_e32 v130, v115, v115
	v_max_f32_e32 v134, v83, v83
	v_max3_f32 v129, v80, v112, v129
	v_max_f32_e32 v130, v134, v130
	v_max3_f32 v129, v129, v131, v130
	v_max_f32_e32 v130, v100, v100
	v_max_f32_e32 v131, v68, v68
	v_max_f32_e32 v130, v131, v130
	v_max_f32_e32 v131, v116, v116
	v_max_f32_e32 v134, v84, v84
	v_max_f32_e32 v131, v134, v131
	v_max_f32_e32 v134, v101, v101
	v_max_f32_e32 v135, v69, v69
	v_max_f32_e32 v134, v135, v134
	v_max3_f32 v128, v128, v130, v134
	v_max_f32_e32 v130, v117, v117
	v_max_f32_e32 v134, v85, v85
	v_max_f32_e32 v130, v134, v130
	v_max3_f32 v129, v129, v131, v130
	v_max_f32_e32 v130, v102, v102
	v_max_f32_e32 v131, v70, v70
	v_max_f32_e32 v130, v131, v130
	v_max_f32_e32 v131, v118, v118
	v_max_f32_e32 v134, v86, v86
	v_max_f32_e32 v131, v134, v131
	v_max_f32_e32 v134, v103, v103
	v_max_f32_e32 v135, v71, v71
	v_max_f32_e32 v134, v135, v134
	v_max3_f32 v128, v128, v130, v134
	v_max_f32_e32 v130, v119, v119
	v_max_f32_e32 v134, v87, v87
	v_max_f32_e32 v130, v134, v130
	v_max3_f32 v129, v129, v131, v130
	v_max_f32_e32 v130, v104, v104
	v_max_f32_e32 v131, v72, v72
	v_max_f32_e32 v130, v131, v130
	v_max_f32_e32 v131, v120, v120
	v_max_f32_e32 v134, v88, v88
	v_max_f32_e32 v131, v134, v131
	v_max_f32_e32 v134, v105, v105
	v_max_f32_e32 v135, v73, v73
	v_max_f32_e32 v134, v135, v134
	v_max3_f32 v128, v128, v130, v134
	v_max_f32_e32 v130, v121, v121
	v_max_f32_e32 v134, v89, v89
	v_max_f32_e32 v130, v134, v130
	v_max3_f32 v129, v129, v131, v130
	v_max_f32_e32 v130, v106, v106
	v_max_f32_e32 v131, v74, v74
	v_max_f32_e32 v130, v131, v130
	v_max_f32_e32 v131, v122, v122
	v_max_f32_e32 v134, v90, v90
	v_max_f32_e32 v131, v134, v131
	v_max_f32_e32 v134, v107, v107
	v_max_f32_e32 v135, v75, v75
	v_max_f32_e32 v134, v135, v134
	v_max3_f32 v128, v128, v130, v134
	v_max_f32_e32 v130, v123, v123
	v_max_f32_e32 v134, v91, v91
	v_max_f32_e32 v130, v134, v130
	v_max3_f32 v129, v129, v131, v130
	v_max_f32_e32 v130, v108, v108
	v_max_f32_e32 v131, v76, v76
	v_max_f32_e32 v130, v131, v130
	v_max_f32_e32 v131, v124, v124
	v_max_f32_e32 v134, v92, v92
	v_max_f32_e32 v131, v134, v131
	v_max_f32_e32 v134, v109, v109
	v_max_f32_e32 v135, v77, v77
	v_max_f32_e32 v134, v135, v134
	v_max3_f32 v128, v128, v130, v134
	v_max_f32_e32 v130, v125, v125
	v_max_f32_e32 v134, v93, v93
	v_max_f32_e32 v130, v134, v130
	v_max3_f32 v129, v129, v131, v130
	v_max_f32_e32 v130, v110, v110
	v_max_f32_e32 v131, v78, v78
	v_max_f32_e32 v130, v131, v130
	v_max_f32_e32 v131, v126, v126
	v_max_f32_e32 v134, v94, v94
	v_max_f32_e32 v131, v134, v131
	v_max_f32_e32 v134, v111, v111
	v_max_f32_e32 v135, v79, v79
	v_max_f32_e32 v134, v135, v134
	v_max3_f32 v128, v128, v130, v134
	v_max_f32_e32 v130, v127, v127
	v_max_f32_e32 v134, v95, v95
	v_max_f32_e32 v130, v134, v130
	v_max3_f32 v130, v129, v131, v130
	ds_bpermute_b32 v131, v166, v128
	ds_bpermute_b32 v134, v166, v130
	v_cmp_ngt_f32_e32 vcc, s15, v149
	s_waitcnt lgkmcnt(0)
; DI void attn_pass_da(const bfr* __restrict__ P, int b, int tq_wave, int qcol, int kcol, int vcol, int key0, int nkt, char* smem, f32x16 (&o0)[2], f32x16 (&o1)[2]) {
;     ...
;     const float mn0 = fmaxf(m0, mx0), mn1 = fmaxf(m1, mx1);
;     const float al0 = __builtin_amdgcn_exp2f(m0 - mn0), al1 = __builtin_amdgcn_exp2f(m1 - mn1);
;     m0 = mn0; m1 = mn1;
;     float ps0 = 0.f, ps1 = 0.f;
; #pragma unroll
;     for (int i = 0; i < 16; ++i) {
;       s0[0][i] = __builtin_amdgcn_exp2f(s0[0][i] - mn0); ps0 += s0[0][i];
;       s0[1][i] = __builtin_amdgcn_exp2f(s0[1][i] - mn0); ps0 += s0[1][i];
;       s1[0][i] = __builtin_amdgcn_exp2f(s1[0][i] - mn1); ps1 += s1[0][i];
;       s1[1][i] = __builtin_amdgcn_exp2f(s1[1][i] - mn1); ps1 += s1[1][i];
;     }
;     l0 = l0 * al0 + ps0; l1 = l1 * al1 + ps1;
; #pragma unroll
;     for (int i = 0; i < 16; ++i) { acc0[0][i] *= al0; acc0[1][i] *= al0; acc1[0][i] *= al1; acc1[1][i] *= al1; }
	v_max3_f32 v150, v210, v130, v134
	v_cndmask_b32_e32 v132, 0, v132, vcc
	v_cmp_nlt_f32_e32 vcc, s10, v149
	v_max3_f32 v149, v209, v128, v131
	v_sub_f32_e32 v64, v64, v149
	v_exp_f32_e32 v148, v64
	v_sub_f32_e32 v64, v96, v149
	v_exp_f32_e32 v131, v64
	v_sub_f32_e32 v64, v80, v150
	v_exp_f32_e32 v151, v64
	v_sub_f32_e32 v64, v112, v150
	v_exp_f32_e32 v96, v64
	v_sub_f32_e32 v64, v65, v149
	v_exp_f32_e32 v152, v64
	v_sub_f32_e32 v64, v97, v149
	v_exp_f32_e32 v112, v64
	v_sub_f32_e32 v64, v81, v150
	v_exp_f32_e32 v158, v64
	v_sub_f32_e32 v64, v113, v150
	v_exp_f32_e32 v97, v64
	v_sub_f32_e32 v64, v66, v149
	v_exp_f32_e32 v143, v64
	v_sub_f32_e32 v64, v98, v149
	v_exp_f32_e32 v113, v64
	v_sub_f32_e32 v64, v82, v150
	v_exp_f32_e32 v146, v64
	v_sub_f32_e32 v64, v114, v150
	v_exp_f32_e32 v98, v64
	v_sub_f32_e32 v64, v67, v149
	v_exp_f32_e32 v147, v64
	v_sub_f32_e32 v64, v99, v149
	v_exp_f32_e32 v114, v64
	v_sub_f32_e32 v64, v83, v150
	v_exp_f32_e32 v138, v64
	v_sub_f32_e32 v64, v115, v150
	v_exp_f32_e32 v99, v64
	v_sub_f32_e32 v64, v68, v149
	v_exp_f32_e32 v139, v64
	v_sub_f32_e32 v64, v100, v149
	v_exp_f32_e32 v115, v64
	v_sub_f32_e32 v64, v84, v150
	v_exp_f32_e32 v140, v64
	v_sub_f32_e32 v64, v116, v150
	v_exp_f32_e32 v100, v64
	v_sub_f32_e32 v64, v69, v149
	v_exp_f32_e32 v141, v64
	v_sub_f32_e32 v64, v101, v149
	v_exp_f32_e32 v116, v64
	v_sub_f32_e32 v64, v85, v150
	v_exp_f32_e32 v142, v64
	v_sub_f32_e32 v64, v117, v150
	v_exp_f32_e32 v101, v64
	v_sub_f32_e32 v64, v70, v149
	v_exp_f32_e32 v134, v64
	v_sub_f32_e32 v64, v102, v149
	v_cndmask_b32_e32 v129, v201, v132, vcc
	v_exp_f32_e32 v132, v64
	v_sub_f32_e32 v64, v86, v150
	v_exp_f32_e32 v135, v64
	v_sub_f32_e32 v64, v118, v150
	v_exp_f32_e32 v117, v64
	v_sub_f32_e32 v64, v71, v149
	v_exp_f32_e32 v136, v64
	v_sub_f32_e32 v64, v103, v149
	v_sub_f32_e32 v129, v133, v129
	v_exp_f32_e32 v133, v64
	v_sub_f32_e32 v64, v87, v150
	v_exp_f32_e32 v137, v64
	v_sub_f32_e32 v64, v119, v150
	v_exp_f32_e32 v102, v64
	v_sub_f32_e32 v64, v72, v149
	v_exp_f32_e32 v103, v64
	v_sub_f32_e32 v64, v104, v149
	v_exp_f32_e32 v71, v64
	v_sub_f32_e32 v64, v88, v150
	v_exp_f32_e32 v104, v64
	v_sub_f32_e32 v64, v120, v150
	v_exp_f32_e32 v70, v64
	v_sub_f32_e32 v64, v73, v149
	v_exp_f32_e32 v118, v64
	v_sub_f32_e32 v64, v105, v149
	v_exp_f32_e32 v73, v64
	v_sub_f32_e32 v64, v89, v150
	v_exp_f32_e32 v105, v64
	v_sub_f32_e32 v64, v121, v150
	v_exp_f32_e32 v72, v64
	v_sub_f32_e32 v64, v74, v149
	v_exp_f32_e32 v119, v64
	v_sub_f32_e32 v64, v106, v149
	v_exp_f32_e32 v81, v64
	v_sub_f32_e32 v64, v90, v150
	v_exp_f32_e32 v89, v64
	v_sub_f32_e32 v64, v122, v150
	v_exp_f32_e32 v80, v64
	v_sub_f32_e32 v64, v75, v149
	v_exp_f32_e32 v90, v64
	v_sub_f32_e32 v64, v107, v149
	v_exp_f32_e32 v87, v64
	v_sub_f32_e32 v64, v91, v150
	v_exp_f32_e32 v91, v64
	v_sub_f32_e32 v64, v123, v150
	v_exp_f32_e32 v86, v64
	v_sub_f32_e32 v64, v76, v149
	v_exp_f32_e32 v74, v64
	v_sub_f32_e32 v64, v108, v149
	v_exp_f32_e32 v75, v64
	v_sub_f32_e32 v64, v92, v150
	v_exp_f32_e32 v76, v64
	v_sub_f32_e32 v64, v124, v150
	v_exp_f32_e32 v82, v64
	v_sub_f32_e32 v64, v77, v149
	v_exp_f32_e32 v77, v64
	v_sub_f32_e32 v64, v109, v149
	v_exp_f32_e32 v83, v64
	v_sub_f32_e32 v64, v93, v150
	v_exp_f32_e32 v84, v64
	v_sub_f32_e32 v64, v125, v150
	v_exp_f32_e32 v85, v64
	v_sub_f32_e32 v64, v78, v149
	v_exp_f32_e32 v78, v64
	v_sub_f32_e32 v64, v110, v149
	v_exp_f32_e32 v88, v64
	v_sub_f32_e32 v64, v94, v150
	v_exp_f32_e32 v66, v64
	v_sub_f32_e32 v64, v126, v150
	v_exp_f32_e32 v67, v64
	v_sub_f32_e32 v64, v79, v149
	v_exp_f32_e32 v68, v64
	v_sub_f32_e32 v64, v111, v149
	v_lshl_add_u32 v79, v181, 1, v144
	v_lshl_add_u32 v110, v180, 1, v144
	v_lshl_add_u32 v124, v179, 1, v145
	v_lshl_add_u32 v126, v178, 1, v145
	v_exp_f32_e32 v69, v64
	v_sub_f32_e32 v64, v95, v150
	v_sub_f32_e32 v65, v127, v150
	v_cvt_pk_bf16_f32 v92, v148, v152
	v_cvt_pk_bf16_f32 v93, v143, v147
	v_cvt_pk_bf16_f32 v94, v139, v141
	v_cvt_pk_bf16_f32 v95, v134, v136
	v_cvt_pk_bf16_f32 v106, v151, v158
	v_cvt_pk_bf16_f32 v107, v146, v138
	v_cvt_pk_bf16_f32 v108, v140, v142
	v_cvt_pk_bf16_f32 v109, v135, v137
	ds_read_b64 v[120:121], v79 offset:27648
	ds_read_b64 v[122:123], v110 offset:27648
	ds_read_b64 v[124:125], v124 offset:27648
	ds_read_b64 v[126:127], v126 offset:27648
	v_sub_f32_e32 v128, v209, v149
	v_exp_f32_e32 v130, v128
	v_sub_f32_e32 v128, v210, v150
	v_add_f32_e32 v111, 0, v151
	v_exp_f32_e32 v128, v128
	v_add_f32_e32 v110, 0, v148
	v_add_f32_e32 v111, v96, v111
	v_add_f32_e32 v110, v131, v110
	v_add_f32_e32 v111, v158, v111
	v_add_f32_e32 v110, v152, v110
	v_add_f32_e32 v111, v97, v111
	v_add_f32_e32 v110, v112, v110
	v_add_f32_e32 v111, v146, v111
	v_pk_mul_f32 v[46:47], v[46:47], v[128:129] op_sel_hi:[1,0]
	v_pk_mul_f32 v[44:45], v[44:45], v[128:129] op_sel_hi:[1,0]
	v_pk_mul_f32 v[42:43], v[42:43], v[128:129] op_sel_hi:[1,0]
	v_pk_mul_f32 v[40:41], v[40:41], v[128:129] op_sel_hi:[1,0]
	v_pk_mul_f32 v[38:39], v[38:39], v[128:129] op_sel_hi:[1,0]
	v_pk_mul_f32 v[36:37], v[36:37], v[128:129] op_sel_hi:[1,0]
	v_pk_mul_f32 v[34:35], v[34:35], v[128:129] op_sel_hi:[1,0]
	v_pk_mul_f32 v[32:33], v[32:33], v[128:129] op_sel_hi:[1,0]
	v_pk_mul_f32 v[14:15], v[14:15], v[128:129] op_sel_hi:[1,0]
	v_pk_mul_f32 v[12:13], v[12:13], v[128:129] op_sel_hi:[1,0]
	v_pk_mul_f32 v[10:11], v[10:11], v[128:129] op_sel_hi:[1,0]
	v_pk_mul_f32 v[8:9], v[8:9], v[128:129] op_sel_hi:[1,0]
	v_pk_mul_f32 v[6:7], v[6:7], v[128:129] op_sel_hi:[1,0]
	v_pk_mul_f32 v[4:5], v[4:5], v[128:129] op_sel_hi:[1,0]
	v_pk_mul_f32 v[2:3], v[2:3], v[128:129] op_sel_hi:[1,0]
	v_pk_mul_f32 v[0:1], v[0:1], v[128:129] op_sel_hi:[1,0]
	v_add_f32_e32 v110, v143, v110
	v_add_f32_e32 v111, v98, v111
	s_waitcnt lgkmcnt(2)
; #define MFMA32(a, b, c) __builtin_amdgcn_mfma_f32_32x32x16_bf16((a), (b), (c), 0, 0, 0)
; DI unsigned pack2(float a, float b) { unsigned r; asm volatile("v_cvt_pk_bf16_f32 %0, %1, %2" : "=v"(r) : "v"(a), "v"(b)); return r; }
; DI void attn_pass_da(const bfr* __restrict__ P, int b, int tq_wave, int qcol, int kcol, int vcol, int key0, int nkt, char* smem, f32x16 (&o0)[2], f32x16 (&o1)[2]) {
;     ...
;     float ps0 = 0.f, ps1 = 0.f;
; #pragma unroll
;     for (int i = 0; i < 16; ++i) {
;       s0[0][i] = __builtin_amdgcn_exp2f(s0[0][i] - mn0); ps0 += s0[0][i];
;       s0[1][i] = __builtin_amdgcn_exp2f(s0[1][i] - mn0); ps0 += s0[1][i];
;       s1[0][i] = __builtin_amdgcn_exp2f(s1[0][i] - mn1); ps1 += s1[0][i];
;       s1[1][i] = __builtin_amdgcn_exp2f(s1[1][i] - mn1); ps1 += s1[1][i];
;     }
;     l0 = l0 * al0 + ps0; l1 = l1 * al1 + ps1;
; #pragma unroll
;     for (int i = 0; i < 16; ++i) { acc0[0][i] *= al0; acc0[1][i] *= al0; acc1[0][i] *= al1; acc1[1][i] *= al1; }
; #pragma unroll
;     for (int t2 = 0; t2 < 2; ++t2)
; #pragma unroll
;       for (int j = 0; j < 2; ++j) {
;         u32x4 pk0, pk1;
;         pk0.x = pack2(s0[t2][8 * j + 0], s0[t2][8 * j + 1]); pk0.y = pack2(s0[t2][8 * j + 2], s0[t2][8 * j + 3]);
;         pk0.z = pack2(s0[t2][8 * j + 4], s0[t2][8 * j + 5]); pk0.w = pack2(s0[t2][8 * j + 6], s0[t2][8 * j + 7]);
;         pk1.x = pack2(s1[t2][8 * j + 0], s1[t2][8 * j + 1]); pk1.y = pack2(s1[t2][8 * j + 2], s1[t2][8 * j + 3]);
;         pk1.z = pack2(s1[t2][8 * j + 4], s1[t2][8 * j + 5]); pk1.w = pack2(s1[t2][8 * j + 6], s1[t2][8 * j + 7]);
;         const bf16x8 pf0 = __builtin_bit_cast(bf16x8, pk0), pf1 = __builtin_bit_cast(bf16x8, pk1);
; #pragma unroll
;         for (int dt = 0; dt < 2; ++dt) {
;           const int vsw = (((dt * 32 + r) >> 3) & 7) << 3;
;           const bfr* vrow = sV + (dt * 32 + r) * 72;
;           s16x4 lo = *(const s16x4*)(vrow + ((t2 * 32 + 16 * j + 4 * h) ^ vsw));
;           s16x4 hi = *(const s16x4*)(vrow + ((t2 * 32 + 16 * j + 4 * h + 8) ^ vsw));
;           bf16x8 vf = __builtin_shufflevector(lo, hi, 0, 1, 2, 3, 4, 5, 6, 7);
;           acc0[dt] = MFMA32(vf, pf0, acc0[dt]);
;           acc1[dt] = MFMA32(vf, pf1, acc1[dt]);
;         }
;       }
	v_mfma_f32_32x32x16_bf16 v[32:47], v[120:123], v[106:109], v[32:47]
	v_add_f32_e32 v110, v113, v110
	v_add_f32_e32 v110, v147, v110
	v_add_f32_e32 v110, v114, v110
	v_mul_f32_e64 v62, v62, v130
	v_mul_f32_e64 v63, v63, v130
	v_pk_mul_f32 v[60:61], v[60:61], v[130:131] op_sel_hi:[1,0]
	v_pk_mul_f32 v[58:59], v[58:59], v[130:131] op_sel_hi:[1,0]
	v_pk_mul_f32 v[56:57], v[56:57], v[130:131] op_sel_hi:[1,0]
	s_waitcnt lgkmcnt(0)
	v_mfma_f32_32x32x16_bf16 v[0:15], v[124:127], v[106:109], v[0:15]
	v_add_f32_e32 v106, v138, v111
	v_add_f32_e32 v106, v99, v106
	v_add_f32_e32 v106, v140, v106
	v_add_f32_e32 v107, v139, v110
	v_add_f32_e32 v106, v100, v106
	v_add_f32_e32 v107, v115, v107
	v_add_f32_e32 v106, v142, v106
	v_pk_mul_f32 v[54:55], v[54:55], v[130:131] op_sel_hi:[1,0]
	v_pk_mul_f32 v[52:53], v[52:53], v[130:131] op_sel_hi:[1,0]
	v_pk_mul_f32 v[50:51], v[50:51], v[130:131] op_sel_hi:[1,0]
	v_pk_mul_f32 v[48:49], v[48:49], v[130:131] op_sel_hi:[1,0]
	v_pk_mul_f32 v[30:31], v[30:31], v[130:131] op_sel_hi:[1,0]
	v_pk_mul_f32 v[28:29], v[28:29], v[130:131] op_sel_hi:[1,0]
	v_pk_mul_f32 v[26:27], v[26:27], v[130:131] op_sel_hi:[1,0]
	v_pk_mul_f32 v[24:25], v[24:25], v[130:131] op_sel_hi:[1,0]
	v_pk_mul_f32 v[22:23], v[22:23], v[130:131] op_sel_hi:[1,0]
	v_pk_mul_f32 v[20:21], v[20:21], v[130:131] op_sel_hi:[1,0]
	v_pk_mul_f32 v[18:19], v[18:19], v[130:131] op_sel_hi:[1,0]
	v_pk_mul_f32 v[16:17], v[16:17], v[130:131] op_sel_hi:[1,0]
	v_lshl_add_u32 v143, v177, 1, v144
	v_add_f32_e32 v107, v141, v107
	v_add_f32_e32 v111, v101, v106
	v_lshl_add_u32 v106, v175, 1, v145
	v_lshl_add_u32 v108, v174, 1, v145
	v_exp_f32_e32 v64, v64
	v_mfma_f32_32x32x16_bf16 v[48:63], v[120:123], v[92:95], v[48:63]
	v_add_f32_e32 v110, v116, v107
	v_add_f32_e32 v110, v134, v110
	v_add_f32_e32 v110, v132, v110
	v_add_f32_e32 v110, v136, v110
	v_add_f32_e32 v111, v135, v111
	v_add_f32_e32 v111, v117, v111
	v_exp_f32_e32 v65, v65
	v_mfma_f32_32x32x16_bf16 v[16:31], v[124:127], v[92:95], v[16:31]
	v_cvt_pk_bf16_f32 v92, v103, v118
	v_cvt_pk_bf16_f32 v93, v119, v90
	v_cvt_pk_bf16_f32 v94, v74, v77
	v_cvt_pk_bf16_f32 v95, v78, v68
	v_cvt_pk_bf16_f32 v120, v104, v105
	v_cvt_pk_bf16_f32 v121, v89, v91
	v_cvt_pk_bf16_f32 v122, v76, v84
	v_cvt_pk_bf16_f32 v123, v66, v64
	ds_read_b64 v[146:147], v143 offset:27648
	ds_read_b64 v[106:107], v106 offset:27648
	ds_read_b64 v[108:109], v108 offset:27648
	v_lshl_add_u32 v143, v176, 1, v144
	ds_read_b64 v[148:149], v143 offset:27648
	v_add_f32_e32 v124, v133, v110
	s_waitcnt lgkmcnt(0)
	v_mfma_f32_32x32x16_bf16 v[48:63], v[146:149], v[92:95], v[48:63]
	v_add_f32_e32 v125, v137, v111
	v_lshlrev_b32_e32 v152, 1, v154
	v_mfma_f32_32x32x16_bf16 v[16:31], v[106:109], v[92:95], v[16:31]
	v_cvt_pk_bf16_f32 v92, v131, v112
	v_cvt_pk_bf16_f32 v93, v113, v114
	v_cvt_pk_bf16_f32 v94, v115, v116
	v_cvt_pk_bf16_f32 v95, v132, v133
	v_cvt_pk_bf16_f32 v96, v96, v97
	v_cvt_pk_bf16_f32 v97, v98, v99
	v_cvt_pk_bf16_f32 v98, v100, v101
	v_add_f32_e32 v100, v103, v124
	v_add_f32_e32 v100, v71, v100
	v_cvt_pk_bf16_f32 v99, v117, v102
	ds_read_b64 v[110:111], v79 offset:27712
	v_lshl_add_u32 v79, v173, 1, v144
	v_add_f32_e32 v100, v118, v100
	ds_read_b64 v[112:113], v79 offset:27648
	v_add_f32_e32 v79, v102, v125
	v_add_f32_e32 v100, v73, v100
	v_add_f32_e32 v79, v104, v79
	v_add_f32_e32 v104, v119, v100
	v_lshl_add_u32 v100, v172, 1, v145
	v_lshl_add_u32 v102, v171, 1, v145
	ds_read_b64 v[100:101], v100 offset:27648
	ds_read_b64 v[102:103], v102 offset:27648
	v_add_f32_e32 v79, v70, v79
	v_add_f32_e32 v79, v105, v79
	v_add_f32_e32 v79, v72, v79
	v_add_f32_e32 v104, v81, v104
	v_add_f32_e32 v79, v89, v79
	v_add_f32_e32 v79, v80, v79
	v_add_f32_e32 v89, v90, v104
	v_add_f32_e32 v89, v87, v89
	v_add_f32_e32 v79, v91, v79
	v_add_f32_e32 v79, v86, v79
	v_add_f32_e32 v74, v74, v89
	s_waitcnt lgkmcnt(2)
	v_mfma_f32_32x32x16_bf16 v[48:63], v[110:113], v[92:95], v[48:63]
	v_cvt_pk_bf16_f32 v90, v71, v73
	v_cvt_pk_bf16_f32 v91, v81, v87
	v_add_f32_e32 v74, v75, v74
	v_add_f32_e32 v74, v77, v74
	v_add_f32_e32 v74, v83, v74
	v_add_f32_e32 v74, v78, v74
	v_add_f32_e32 v78, v88, v74
	s_waitcnt lgkmcnt(0)
	v_mfma_f32_32x32x16_bf16 v[16:31], v[100:103], v[92:95], v[16:31]
	v_cvt_pk_bf16_f32 v92, v75, v83
	v_add_f32_e32 v75, v76, v79
	v_add_f32_e32 v75, v82, v75
	v_add_f32_e32 v75, v84, v75
	v_add_f32_e32 v79, v85, v75
	v_add_f32_e32 v66, v66, v79
	v_cvt_pk_bf16_f32 v93, v88, v69
	v_mfma_f32_32x32x16_bf16 v[32:47], v[146:149], v[120:123], v[32:47]
	v_cvt_pk_bf16_f32 v70, v70, v72
	v_cvt_pk_bf16_f32 v71, v80, v86
	v_cvt_pk_bf16_f32 v72, v82, v85
	v_cvt_pk_bf16_f32 v73, v67, v65
	v_add_f32_e32 v66, v67, v66
	v_add_f32_e32 v67, v68, v78
	v_add_f32_e32 v67, v69, v67
	v_mfma_f32_32x32x16_bf16 v[0:15], v[106:109], v[120:123], v[0:15]
	v_fmac_f32_e32 v67, v156, v130
	ds_bpermute_b32 v68, v166, v67
	v_lshl_add_u32 v80, v169, 1, v144
	v_lshl_add_u32 v74, v168, 1, v145
	v_lshl_add_u32 v76, v167, 1, v145
	ds_read_b64 v[104:105], v80 offset:27648
	ds_read_b64 v[74:75], v74 offset:27648
	ds_read_b64 v[76:77], v76 offset:27648
	v_lshl_add_u32 v80, v170, 1, v144
	v_add_f32_e32 v64, v64, v66
	ds_read_b64 v[106:107], v80 offset:27648
	v_add_f32_e32 v65, v65, v64
	v_mfma_f32_32x32x16_bf16 v[32:47], v[110:113], v[96:99], v[32:47]
	v_fmac_f32_e32 v65, v157, v128
	s_waitcnt lgkmcnt(4)
	v_add_f32_e32 v66, v67, v68
	ds_bpermute_b32 v67, v166, v65
	v_div_scale_f32 v68, s[10:11], v66, v66, 1.0
	v_rcp_f32_e32 v69, v68
	v_add_f32_e32 v64, v155, v129
	v_mfma_f32_32x32x16_bf16 v[0:15], v[100:103], v[96:99], v[0:15]
	s_waitcnt lgkmcnt(0)
; DI int oidx(int i) { asm volatile("" : "+s"(i)); return i; }
; DI void attn_pass_da(const bfr* __restrict__ P, int b, int tq_wave, int qcol, int kcol, int vcol, int key0, int nkt, char* smem, f32x16 (&o0)[2], f32x16 (&o1)[2]) {
;     ...
;   l0 += __shfl_xor(l0, 32); l1 += __shfl_xor(l1, 32);
;   const float i0 = 1.f / l0, i1 = 1.f / l1;
; #pragma unroll
;   for (int i = 0; i < 16; ++i) { o0[0][i] = acc0[0][i] * i0; o0[1][i] = acc0[1][i] * i0; o1[0][i] = acc1[0][i] * i1; o1[1][i] = acc1[1][i] * i1; }
; DN void da_item(const Params& p, int l, int b, int hd, int tq0, int key0, int nkt, char* smem) {
;     ...
;   float ss = 0.f;
; #pragma unroll
;   for (int dt = 0; dt < 2; ++dt)
; #pragma unroll
;     for (int i = 0; i < 16; ++i) { float v = o0[dt][i] - lam * o1[dt][i]; o0[dt][i] = v; ss += v * v; }
;   ss += __shfl_xor(ss, 32);
;   float rstd = rsqrtf(ss * (1.f / 64.f) + 1e-6f) * (1.f - lam_init);
;   const float* sg = p.in[oidx(23)] + l * 64;
; #pragma unroll
;   for (int dt = 0; dt < 2; ++dt)
; #pragma unroll
;     for (int i = 0; i < 16; ++i) { int dv = dt * 32 + 8 * (i >> 2) + 4 * h + (i & 3); o0[dt][i] = o0[dt][i] * rstd * sg[dv]; }
	v_add_f32_e32 v65, v65, v67
	v_fma_f32 v67, -v68, v69, 1.0
	v_fmac_f32_e32 v69, v67, v69
	v_div_scale_f32 v67, vcc, 1.0, v66, 1.0
	v_mfma_f32_32x32x16_bf16 v[32:47], v[104:107], v[70:73], v[32:47]
	v_mfma_f32_32x32x16_bf16 v[0:15], v[74:77], v[70:73], v[0:15]
	v_mul_f32_e32 v70, v67, v69
	v_fma_f32 v71, -v68, v70, v67
	v_fmac_f32_e32 v70, v71, v69
	v_fma_f32 v67, -v68, v70, v67
	v_div_scale_f32 v68, s[10:11], v65, v65, 1.0
	v_rcp_f32_e32 v71, v68
	v_div_fmas_f32 v67, v67, v69, v70
	v_div_fixup_f32 v66, v67, v66, 1.0
	v_mfma_f32_32x32x16_bf16 v[48:63], v[104:107], v[90:93], v[48:63]
	v_fma_f32 v67, -v68, v71, 1.0
	v_fmac_f32_e32 v71, v67, v71
	v_div_scale_f32 v67, vcc, 1.0, v65, 1.0
	v_mul_f32_e32 v69, v67, v71
	v_fma_f32 v70, -v68, v69, v67
	v_fmac_f32_e32 v69, v70, v71
	v_fma_f32 v67, -v68, v69, v67
	v_div_fmas_f32 v67, v67, v71, v69
	v_div_fixup_f32 v68, v67, v65, 1.0
	v_mul_f32_e32 v65, v0, v68
	v_mul_f32_e32 v0, v33, v68
	v_mul_f32_e32 v67, v1, v68
	v_mul_f32_e32 v1, v34, v68
	v_mul_f32_e32 v0, v64, v0
	v_mul_f32_e32 v32, v32, v68
	v_mul_f32_e32 v69, v2, v68
	v_mul_f32_e32 v2, v35, v68
	v_mul_f32_e32 v33, v37, v68
	v_mul_f32_e32 v37, v41, v68
	v_mul_f32_e32 v41, v45, v68
	v_fma_f32 v45, v49, v66, -v0
	v_mul_f32_e32 v0, v64, v1
	v_mul_f32_e32 v70, v3, v68
	v_mul_f32_e32 v3, v36, v68
	v_mul_f32_e32 v35, v39, v68
	v_mul_f32_e32 v39, v43, v68
	v_mul_f32_e32 v43, v47, v68
	v_mul_f32_e32 v32, v64, v32
	v_fma_f32 v47, v50, v66, -v0
	v_mul_f32_e32 v0, v64, v2
	v_mul_f32_e32 v36, v40, v68
	v_mul_f32_e32 v40, v44, v68
	v_fma_f32 v44, v48, v66, -v32
	v_fma_f32 v48, v51, v66, -v0
	v_mul_f32_e32 v0, v64, v3
	v_mul_f32_e32 v34, v38, v68
	v_fma_f32 v49, v52, v66, -v0
	v_mul_f32_e32 v0, v64, v33
	s_mov_b32 s10, 23
	v_fma_f32 v50, v53, v66, -v0
	v_mul_f32_e32 v0, v64, v34
	s_ashr_i32 s11, s10, 31
	v_fma_f32 v51, v54, v66, -v0
	v_mul_f32_e32 v0, v64, v35
	s_lshl_b64 s[10:11], s[10:11], 3
	v_fma_f32 v52, v55, v66, -v0
	v_mul_f32_e32 v0, v64, v36
	s_add_u32 s10, s0, s10
	v_mul_f32_e32 v38, v42, v68
	v_fma_f32 v53, v56, v66, -v0
	v_mul_f32_e32 v0, v64, v37
	s_addc_u32 s11, s1, s11
	v_fma_f32 v54, v57, v66, -v0
	v_mul_f32_e32 v0, v64, v38
	s_load_dwordx2 s[10:11], s[10:11], 0x0
	v_mul_f32_e32 v42, v46, v68
	v_mul_f32_e32 v46, v45, v45
	v_fma_f32 v55, v58, v66, -v0
	v_mul_f32_e32 v0, v64, v39
	v_fmac_f32_e32 v46, v44, v44
	v_fma_f32 v56, v59, v66, -v0
	v_mul_f32_e32 v0, v64, v40
	v_fmac_f32_e32 v46, v47, v47
	v_fma_f32 v57, v60, v66, -v0
	v_mul_f32_e32 v0, v64, v41
	v_fmac_f32_e32 v46, v48, v48
	v_fma_f32 v58, v61, v66, -v0
	s_lshl_b64 s[12:13], s[12:13], 2
	v_lshrrev_b32_e32 v0, 3, v164
	v_fmac_f32_e32 v46, v49, v49
	s_waitcnt lgkmcnt(0)
	s_add_u32 s10, s10, s12
	v_and_b32_e32 v59, 4, v0
	v_fmac_f32_e32 v46, v50, v50
	s_addc_u32 s11, s11, s13
	v_lshlrev_b32_e32 v60, 2, v59
	v_mfma_f32_32x32x16_bf16 v[16:31], v[74:77], v[90:93], v[16:31]
	v_fmac_f32_e32 v46, v51, v51
	global_load_dwordx4 v[0:3], v60, s[10:11]
	v_fmac_f32_e32 v46, v52, v52
	v_fmac_f32_e32 v46, v53, v53
	v_mul_f32_e32 v32, v64, v42
	v_fmac_f32_e32 v46, v54, v54
	v_fma_f32 v61, v62, v66, -v32
	v_mul_f32_e32 v32, v64, v43
	v_fmac_f32_e32 v46, v55, v55
	v_fma_f32 v62, v63, v66, -v32
	global_load_dwordx4 v[32:35], v60, s[10:11] offset:32
	v_fmac_f32_e32 v46, v56, v56
	v_fmac_f32_e32 v46, v57, v57
	v_fmac_f32_e32 v46, v58, v58
	v_mul_f32_e32 v36, v64, v65
	v_fmac_f32_e32 v46, v61, v61
	v_fma_f32 v63, v16, v66, -v36
	v_mul_f32_e32 v16, v64, v67
	global_load_dwordx4 v[36:39], v60, s[10:11] offset:64
	v_mul_f32_e32 v4, v4, v68
	v_fmac_f32_e32 v46, v62, v62
	v_fma_f32 v65, v17, v66, -v16
	v_mul_f32_e32 v16, v64, v69
	v_mul_f32_e32 v5, v5, v68
	v_fmac_f32_e32 v46, v63, v63
	v_fma_f32 v67, v18, v66, -v16
	v_mul_f32_e32 v16, v64, v70
	v_mul_f32_e32 v4, v64, v4
	v_fmac_f32_e32 v46, v65, v65
	v_fma_f32 v69, v19, v66, -v16
	v_fma_f32 v70, v20, v66, -v4
	v_mul_f32_e32 v4, v64, v5
	v_fmac_f32_e32 v46, v67, v67
	global_load_dwordx4 v[16:19], v60, s[10:11] offset:96
	v_fma_f32 v71, v21, v66, -v4
	v_pk_mul_f32 v[4:5], v[6:7], v[68:69] op_sel_hi:[1,0]
	v_fmac_f32_e32 v46, v69, v69
	v_pk_mul_f32 v[4:5], v[64:65], v[4:5] op_sel_hi:[0,1]
	v_fmac_f32_e32 v46, v70, v70
	v_pk_fma_f32 v[40:41], v[22:23], v[66:67], v[4:5] op_sel_hi:[1,0,1] neg_lo:[0,0,1] neg_hi:[0,0,1]
	v_pk_mul_f32 v[8:9], v[8:9], v[68:69] op_sel_hi:[1,0]
	v_fmac_f32_e32 v46, v71, v71
	v_pk_mul_f32 v[20:21], v[40:41], v[40:41]
	v_pk_mul_f32 v[8:9], v[64:65], v[8:9] op_sel_hi:[0,1]
	global_load_dwordx4 v[4:7], v60, s[10:11] offset:128
	v_add_f32_e32 v20, v20, v46
	v_pk_fma_f32 v[24:25], v[24:25], v[66:67], v[8:9] op_sel_hi:[1,0,1] neg_lo:[0,0,1] neg_hi:[0,0,1]
	v_add_f32_e32 v20, v21, v20
	v_pk_mul_f32 v[8:9], v[24:25], v[24:25]
	v_pk_mul_f32 v[12:13], v[12:13], v[68:69] op_sel_hi:[1,0]
	v_add_f32_e32 v8, v8, v20
	v_add_f32_e32 v42, v9, v8
	v_pk_mul_f32 v[8:9], v[10:11], v[68:69] op_sel_hi:[1,0]
	global_load_dwordx4 v[20:23], v60, s[10:11] offset:160
	v_pk_mul_f32 v[8:9], v[64:65], v[8:9] op_sel_hi:[0,1]
	v_pk_fma_f32 v[26:27], v[26:27], v[66:67], v[8:9] op_sel_hi:[1,0,1] neg_lo:[0,0,1] neg_hi:[0,0,1]
	v_pk_mul_f32 v[12:13], v[64:65], v[12:13] op_sel_hi:[0,1]
	v_pk_mul_f32 v[8:9], v[26:27], v[26:27]
	v_pk_fma_f32 v[28:29], v[28:29], v[66:67], v[12:13] op_sel_hi:[1,0,1] neg_lo:[0,0,1] neg_hi:[0,0,1]
	v_add_f32_e32 v8, v8, v42
	v_add_f32_e32 v42, v9, v8
	global_load_dwordx4 v[8:11], v60, s[10:11] offset:192
	v_pk_mul_f32 v[12:13], v[28:29], v[28:29]
	s_load_dwordx4 s[12:15], s[0:1], 0x100
	v_add_f32_e32 v12, v12, v42
	v_add_f32_e32 v46, v13, v12
	v_pk_mul_f32 v[42:43], v[14:15], v[68:69] op_sel_hi:[1,0]
	global_load_dwordx4 v[12:15], v60, s[10:11] offset:224
	v_pk_mul_f32 v[42:43], v[64:65], v[42:43] op_sel_hi:[0,1]
	v_pk_fma_f32 v[30:31], v[30:31], v[66:67], v[42:43] op_sel_hi:[1,0,1] neg_lo:[0,0,1] neg_hi:[0,0,1]
	s_mov_b64 s[10:11], 0x2b7c300
	v_pk_mul_f32 v[42:43], v[30:31], v[30:31]
	s_nop 0
	v_add_f32_e32 v42, v42, v46
	v_add_f32_e32 v42, v43, v42
	ds_bpermute_b32 v43, v166, v42
	s_waitcnt lgkmcnt(0)
; DI int oidx(int i) { asm volatile("" : "+s"(i)); return i; }
; DI unsigned pack2(float a, float b) { unsigned r; asm volatile("v_cvt_pk_bf16_f32 %0, %1, %2" : "=v"(r) : "v"(a), "v"(b)); return r; }
; DI void store_o(bfr* O, int m, int colbase, int h, const f32x16 (&o)[2]) {
; #pragma unroll
;   for (int dt = 0; dt < 2; ++dt)
; #pragma unroll
;     for (int g4 = 0; g4 < 4; ++g4) {
;       int dv = dt * 32 + 8 * g4 + 4 * h;
;       uint2 pk; pk.x = pack2(o[dt][4 * g4], o[dt][4 * g4 + 1]); pk.y = pack2(o[dt][4 * g4 + 2], o[dt][4 * g4 + 3]);
;       *(uint2*)(O + (size_t)m * DM + colbase + dv) = pk;
;     }
; }
; DN void da_item(const Params& p, int l, int b, int hd, int tq0, int key0, int nkt, char* smem) {
;     ...
;   ss += __shfl_xor(ss, 32);
;   float rstd = rsqrtf(ss * (1.f / 64.f) + 1e-6f) * (1.f - lam_init);
;   const float* sg = p.in[oidx(23)] + l * 64;
; #pragma unroll
;   for (int dt = 0; dt < 2; ++dt)
; #pragma unroll
;     for (int i = 0; i < 16; ++i) { int dv = dt * 32 + 8 * (i >> 2) + 4 * h + (i & 3); o0[dt][i] = o0[dt][i] * rstd * sg[dv]; }
;   store_o(O, b * TT + tqw + r, 256 + hd * 64, h, o0);
	v_add_f32_e32 v42, v42, v43
	v_fmamk_f32 v42, v42, 0x3c800000, v186
	v_cmp_gt_f32_e32 vcc, s33, v42
	v_mul_f32_e32 v43, 0x4b800000, v42
	s_nop 0
	v_cndmask_b32_e32 v42, v42, v43, vcc
	v_rsq_f32_e32 v42, v42
	s_nop 0
	v_mul_f32_e32 v43, 0x45800000, v42
	v_cndmask_b32_e32 v42, v42, v43, vcc
	v_mul_f32_e32 v42, v162, v42
	v_mul_f32_e32 v43, v44, v42
	s_waitcnt vmcnt(7)
	v_mul_f32_e32 v43, v0, v43
	v_mul_f32_e32 v0, v45, v42
	v_mul_f32_e32 v44, v1, v0
	v_mul_f32_e32 v0, v47, v42
	v_mul_f32_e32 v45, v2, v0
	v_mul_f32_e32 v0, v48, v42
	v_mul_f32_e32 v3, v3, v0
	v_mul_f32_e32 v0, v49, v42
	s_waitcnt vmcnt(6)
	v_mul_f32_e32 v32, v32, v0
	v_mul_f32_e32 v0, v50, v42
	v_mul_f32_e32 v33, v33, v0
	v_mul_f32_e32 v0, v51, v42
	v_mul_f32_e32 v34, v34, v0
	v_mul_f32_e32 v0, v52, v42
	v_mul_f32_e32 v35, v35, v0
	v_mul_f32_e32 v0, v53, v42
	s_waitcnt vmcnt(5)
	v_mul_f32_e32 v36, v36, v0
	v_mul_f32_e32 v0, v54, v42
	v_mul_f32_e32 v37, v37, v0
	v_mul_f32_e32 v0, v55, v42
	v_mul_f32_e32 v38, v38, v0
	v_mul_f32_e32 v0, v56, v42
	v_mul_f32_e32 v39, v39, v0
	v_mul_f32_e32 v0, v57, v42
	s_waitcnt vmcnt(4)
	v_mul_f32_e32 v16, v16, v0
	v_mul_f32_e32 v0, v58, v42
	v_mul_f32_e32 v17, v17, v0
	v_mul_f32_e32 v0, v61, v42
	v_mul_f32_e32 v18, v18, v0
	v_mul_f32_e32 v0, v62, v42
	v_mul_f32_e32 v19, v19, v0
	v_mul_f32_e32 v0, v63, v42
	s_waitcnt vmcnt(3)
	v_mul_f32_e32 v46, v4, v0
	v_mul_f32_e32 v0, v65, v42
	v_mul_f32_e32 v47, v5, v0
	v_mul_f32_e32 v0, v67, v42
	v_mul_f32_e32 v6, v6, v0
	v_mul_f32_e32 v0, v69, v42
	v_mul_f32_e32 v7, v7, v0
	v_mul_f32_e32 v0, v70, v42
	s_waitcnt vmcnt(2)
	v_mul_f32_e32 v20, v20, v0
	v_mul_f32_e32 v0, v71, v42
	v_mul_f32_e32 v21, v21, v0
	v_mul_f32_e32 v0, v40, v42
	v_mul_f32_e32 v22, v22, v0
	v_mul_f32_e32 v0, v41, v42
	v_mul_f32_e32 v23, v23, v0
	v_mul_f32_e32 v0, v24, v42
	s_waitcnt vmcnt(1)
	v_mul_f32_e32 v8, v8, v0
	v_mul_f32_e32 v0, v25, v42
	v_mul_f32_e32 v9, v9, v0
	v_mul_f32_e32 v0, v26, v42
	v_mul_f32_e32 v10, v10, v0
	v_mul_f32_e32 v0, v27, v42
	v_mul_f32_e32 v11, v11, v0
	v_mul_f32_e32 v0, v28, v42
	s_waitcnt vmcnt(0)
	v_mul_f32_e32 v12, v12, v0
	v_mul_f32_e32 v0, v29, v42
	v_mul_f32_e32 v13, v13, v0
	v_mul_f32_e32 v0, v30, v42
	v_mul_f32_e32 v14, v14, v0
	v_mul_f32_e32 v0, v31, v42
	v_mul_f32_e32 v15, v15, v0
	v_and_or_b32 v0, v164, 31, v165
	v_ashrrev_i32_e32 v1, 31, v0
	v_lshlrev_b64 v[0:1], 11, v[0:1]
	v_lshl_add_u64 v[0:1], s[14:15], 0, v[0:1]
	v_lshl_add_u64 v[0:1], v[0:1], 0, v[152:153]
	v_lshlrev_b32_e32 v152, 1, v59
	v_lshl_add_u64 v[0:1], v[0:1], 0, v[152:153]
	v_lshl_add_u64 v[4:5], v[0:1], 0, s[10:11]
	s_mov_b32 s10, 0x2b7c000
	v_add_co_u32_e32 v0, vcc, s10, v0
	v_cvt_pk_bf16_f32 v2, v43, v44
	v_cvt_pk_bf16_f32 v3, v45, v3
	s_nop 1
	v_addc_co_u32_e32 v1, vcc, 0, v1, vcc
	global_store_dwordx2 v[0:1], v[2:3], off offset:768
	v_cvt_pk_bf16_f32 v0, v32, v33
	v_cvt_pk_bf16_f32 v1, v34, v35
	global_store_dwordx2 v[4:5], v[0:1], off offset:16
	v_cvt_pk_bf16_f32 v0, v36, v37
	v_cvt_pk_bf16_f32 v1, v38, v39
	global_store_dwordx2 v[4:5], v[0:1], off offset:32
	v_cvt_pk_bf16_f32 v0, v16, v17
	v_cvt_pk_bf16_f32 v1, v18, v19
	global_store_dwordx2 v[4:5], v[0:1], off offset:48
	v_cvt_pk_bf16_f32 v0, v46, v47
	v_cvt_pk_bf16_f32 v1, v6, v7
	global_store_dwordx2 v[4:5], v[0:1], off offset:64
	v_cvt_pk_bf16_f32 v0, v20, v21
	v_cvt_pk_bf16_f32 v1, v22, v23
	global_store_dwordx2 v[4:5], v[0:1], off offset:80
	v_cvt_pk_bf16_f32 v0, v8, v9
	v_cvt_pk_bf16_f32 v1, v10, v11
	global_store_dwordx2 v[4:5], v[0:1], off offset:96
	v_cvt_pk_bf16_f32 v0, v12, v13
	v_cvt_pk_bf16_f32 v1, v14, v15
	global_store_dwordx2 v[4:5], v[0:1], off offset:112
	s_or_b64 exec, exec, s[8:9]

; #define MFMA32(a, b, c) __builtin_amdgcn_mfma_f32_32x32x16_bf16((a), (b), (c), 0, 0, 0)
; template <int D>
; DI void attn_pass(const bfr* __restrict__ P, int b, int tq_wave, int qcol, int kcol, int vcol, int key0, int nkt, char* smem, f32x16 (&o)[2]) {
;     ...
;   for (int kt = 0; kt < nkt; ++kt) {
;     bfr* sK = sbase + (kt & 1) * 9216;
;     bfr* sV = sK + 64 * 72;
;     { int c = gt, row = c >> 3, kc = c & 7; *(u32x4*)(sK + row * KP + kc * 8) = kreg[0]; }
;     for (int i = 0; i < 1; ++i) {
;       int c = gt, row = c >> 3, kc = c & 7;
;       unsigned wds[4] = {vreg[i].x, vreg[i].y, vreg[i].z, vreg[i].w};
; #pragma unroll
;       for (int e = 0; e < 4; ++e) {
;         sV[(kc * 8 + 2 * e) * 72 + (row ^ (kc << 3))] = (bfr)(wds[e] & 0xffffu);
;         sV[(kc * 8 + 2 * e + 1) * 72 + (row ^ (kc << 3))] = (bfr)(wds[e] >> 16);
;       }
;     }
;     __syncthreads();
;     if (kt + 1 < nkt) {
;       const bfr* Pn = Pb + (size_t)(kt + 1) * 64 * PW;
;       { int c = gt, row = c >> 3, kc = c & 7; kreg[0] = *(const u32x4*)(Pn + (size_t)row * PW + kcol + kc * 8); vreg[0] = *(const u32x4*)(Pn + (size_t)row * PW + vcol + kc * 8); }
;     }
;     f32x16 s[2];
; #pragma unroll
;     for (int t2 = 0; t2 < 2; ++t2) {
; #pragma unroll
;       for (int i = 0; i < 16; ++i) s[t2][i] = 0.f;
; #pragma unroll
;       for (int ks = 0; ks < KS; ++ks) {
;         bf16x8 a = *(const bf16x8*)(sK + (t2 * 32 + r) * KP + ks * 16 + h * 8);
;         s[t2] = MFMA32(a, qf[ks], s[t2]);
;       }
;     }
;     float mx = s[0][0];
; #pragma unroll
;     for (int i = 0; i < 16; ++i) { mx = fmaxf(mx, s[0][i]); mx = fmaxf(mx, s[1][i]); }
;     mx = fmaxf(mx, __shfl_xor(mx, 32));
;     float mnew = fmaxf(mrun, mx);
;     float alpha = __builtin_amdgcn_exp2f(mrun - mnew);
;     mrun = mnew;
;     float ps = 0.f;
; #pragma unroll
;     for (int i = 0; i < 16; ++i) {
;       s[0][i] = __builtin_amdgcn_exp2f(s[0][i] - mnew); ps += s[0][i];
;       s[1][i] = __builtin_amdgcn_exp2f(s[1][i] - mnew); ps += s[1][i];
.LBB0_412:
	s_bitcmp1_b32 s8, 0
	s_cselect_b32 s9, 0x4800, 0
	s_add_i32 s9, s9, 0
	v_add3_u32 v32, s9, v115, v90
	v_add_u32_e32 v121, s9, v114
	v_mov_b32_e32 v120, v113
	s_waitcnt vmcnt(1)
	ds_write_b128 v32, v[84:87]
	v_add3_u32 v32, s9, v117, v118
	v_add3_u32 v33, s9, v118, v117
	v_add_u32_e32 v113, v121, v152
	s_waitcnt vmcnt(0)
	ds_write_b16 v32, v80 offset:9216
	ds_write_b16_d16_hi v33, v80 offset:9360
	ds_write_b16 v32, v81 offset:9504
	ds_write_b16_d16_hi v33, v81 offset:9648
	ds_write_b16 v32, v82 offset:9792
	ds_write_b16_d16_hi v33, v82 offset:9936
	ds_write_b16 v32, v83 offset:10080
	ds_write_b16_d16_hi v33, v83 offset:10224
	s_waitcnt lgkmcnt(0)
	s_barrier
	global_load_dwordx4 v[84:87], v[92:93], off
	global_load_dwordx4 v[80:83], v[94:95], off
	ds_read_b128 v[126:129], v113
	ds_read_b128 v[130:133], v113 offset:32
	ds_read_b128 v[134:137], v113 offset:64
	ds_read_b128 v[138:141], v113 offset:96
	ds_read_b128 v[142:145], v113 offset:4608
	ds_read_b128 v[146:149], v113 offset:4640
	ds_read_b128 v[156:159], v113 offset:4672
	ds_read_b128 v[164:167], v113 offset:4704
	v_mov_b32_e32 v96, v119
	s_waitcnt lgkmcnt(7)
	v_mfma_f32_32x32x16_bf16 v[32:47], v[126:129], v[76:79], 0
	s_add_i32 s8, s8, 1
	s_waitcnt lgkmcnt(6)
	v_mfma_f32_32x32x16_bf16 v[32:47], v[130:133], v[72:75], v[32:47]
	v_lshl_add_u64 v[92:93], v[92:93], 0, s[10:11]
	s_waitcnt lgkmcnt(5)
	v_mfma_f32_32x32x16_bf16 v[32:47], v[134:137], v[68:71], v[32:47]
	v_lshl_add_u64 v[94:95], v[94:95], 0, s[10:11]
	s_waitcnt lgkmcnt(4)
	v_mfma_f32_32x32x16_bf16 v[32:47], v[138:141], v[64:67], v[32:47]
	s_cmp_lg_u32 s8, 35
	s_waitcnt lgkmcnt(3)
	v_mfma_f32_32x32x16_bf16 v[48:63], v[142:145], v[76:79], 0
	s_waitcnt lgkmcnt(2)
	v_mfma_f32_32x32x16_bf16 v[48:63], v[146:149], v[72:75], v[48:63]
	s_waitcnt lgkmcnt(1)
	v_mfma_f32_32x32x16_bf16 v[48:63], v[156:159], v[68:71], v[48:63]
	s_waitcnt lgkmcnt(0)
	v_mfma_f32_32x32x16_bf16 v[48:63], v[164:167], v[64:67], v[48:63]
	v_add_u32_e32 v154, s9, v116
	v_lshl_add_u32 v168, v112, 1, v121
	v_lshl_add_u32 v169, v111, 1, v121
	v_lshl_add_u32 v170, v110, 1, v154
	v_lshl_add_u32 v171, v109, 1, v154
	v_lshl_add_u32 v172, v108, 1, v121
	v_lshl_add_u32 v173, v107, 1, v121
	v_lshl_add_u32 v174, v106, 1, v154
	v_lshl_add_u32 v175, v105, 1, v154
	v_lshl_add_u32 v176, v104, 1, v121
	v_lshl_add_u32 v177, v103, 1, v154
	v_lshl_add_u32 v178, v102, 1, v154
	v_lshl_add_u32 v179, v100, 1, v121
	v_lshl_add_u32 v180, v101, 1, v121
	v_lshl_add_u32 v181, v99, 1, v154
	v_lshl_add_u32 v160, v98, 1, v154
	v_max_f32_e32 v119, v32, v32
	v_max_f32_e32 v113, v48, v48
	v_max_f32_e32 v113, v119, v113
	v_max3_f32 v113, v113, v33, v49
	v_max3_f32 v113, v113, v34, v50
	v_max3_f32 v113, v113, v35, v51
	v_max3_f32 v113, v113, v36, v52
	v_max3_f32 v113, v113, v37, v53
	v_max3_f32 v113, v113, v38, v54
	v_max3_f32 v113, v113, v39, v55
	v_max3_f32 v113, v113, v40, v56
	v_max3_f32 v113, v113, v41, v57
	v_max3_f32 v113, v113, v42, v58
	v_max3_f32 v113, v113, v43, v59
	v_max3_f32 v113, v113, v44, v60
	v_max3_f32 v113, v113, v45, v61
	v_max3_f32 v113, v113, v46, v62
	v_max3_f32 v113, v113, v47, v63
	ds_bpermute_b32 v119, v91, v113
	s_waitcnt lgkmcnt(0)
	ds_read_b64 v[126:127], v168 offset:9216
	ds_read_b64 v[128:129], v169 offset:9216
	ds_read_b64 v[130:131], v170 offset:9216
	ds_read_b64 v[132:133], v171 offset:9216
	ds_read_b64 v[134:135], v172 offset:9216
	ds_read_b64 v[136:137], v173 offset:9216
	ds_read_b64 v[138:139], v174 offset:9216
	ds_read_b64 v[140:141], v175 offset:9216
	v_max3_f32 v119, v96, v113, v119
	v_pk_add_f32 v[32:33], v[32:33], v[118:119] op_sel:[0,1] op_sel_hi:[1,1] neg_lo:[0,1] neg_hi:[0,1]
	v_pk_add_f32 v[38:39], v[38:39], v[118:119] op_sel:[0,1] op_sel_hi:[1,1] neg_lo:[0,1] neg_hi:[0,1]
	v_exp_f32_e32 v32, v32
	v_pk_add_f32 v[48:49], v[48:49], v[118:119] op_sel:[0,1] op_sel_hi:[1,1] neg_lo:[0,1] neg_hi:[0,1]
	v_pk_add_f32 v[36:37], v[36:37], v[118:119] op_sel:[0,1] op_sel_hi:[1,1] neg_lo:[0,1] neg_hi:[0,1]
	v_exp_f32_e32 v124, v38
	v_pk_add_f32 v[54:55], v[54:55], v[118:119] op_sel:[0,1] op_sel_hi:[1,1] neg_lo:[0,1] neg_hi:[0,1]
	v_exp_f32_e32 v48, v48
	v_exp_f32_e32 v122, v36
	v_sub_f32_e32 v36, v52, v119
	v_exp_f32_e32 v52, v54
	v_exp_f32_e32 v33, v33
	v_exp_f32_e32 v125, v39
	v_exp_f32_e32 v49, v49
	v_pk_add_f32 v[34:35], v[34:35], v[118:119] op_sel:[0,1] op_sel_hi:[1,1] neg_lo:[0,1] neg_hi:[0,1]
	v_exp_f32_e32 v123, v37
	v_sub_f32_e32 v37, v53, v119
	v_exp_f32_e32 v53, v55
	v_pk_add_f32 v[40:41], v[40:41], v[118:119] op_sel:[0,1] op_sel_hi:[1,1] neg_lo:[0,1] neg_hi:[0,1]
	v_pk_add_f32 v[42:43], v[42:43], v[118:119] op_sel:[0,1] op_sel_hi:[1,1] neg_lo:[0,1] neg_hi:[0,1]
	v_pk_add_f32 v[44:45], v[44:45], v[118:119] op_sel:[0,1] op_sel_hi:[1,1] neg_lo:[0,1] neg_hi:[0,1]
	v_exp_f32_e32 v34, v34
	v_pk_add_f32 v[50:51], v[50:51], v[118:119] op_sel:[0,1] op_sel_hi:[1,1] neg_lo:[0,1] neg_hi:[0,1]
	v_exp_f32_e32 v54, v40
	v_sub_f32_e32 v38, v56, v119
	v_exp_f32_e32 v56, v42
	v_sub_f32_e32 v40, v58, v119
	v_exp_f32_e32 v58, v44
	v_sub_f32_e32 v42, v60, v119
	s_waitcnt lgkmcnt(4)
; #define MFMA32(a, b, c) __builtin_amdgcn_mfma_f32_32x32x16_bf16((a), (b), (c), 0, 0, 0)
; DI unsigned pack2(float a, float b) { unsigned r; asm volatile("v_cvt_pk_bf16_f32 %0, %1, %2" : "=v"(r) : "v"(a), "v"(b)); return r; }
; template <int D>
; DI void attn_pass(const bfr* __restrict__ P, int b, int tq_wave, int qcol, int kcol, int vcol, int key0, int nkt, char* smem, f32x16 (&o)[2]) {
;     ...
; #pragma unroll
;     for (int i = 0; i < 16; ++i) {
;       s[0][i] = __builtin_amdgcn_exp2f(s[0][i] - mnew); ps += s[0][i];
;       s[1][i] = __builtin_amdgcn_exp2f(s[1][i] - mnew); ps += s[1][i];
;     }
;     lsum = lsum * alpha + ps;
; #pragma unroll
;     for (int i = 0; i < 16; ++i) { accO[0][i] *= alpha; accO[1][i] *= alpha; }
; #pragma unroll
;     for (int t2 = 0; t2 < 2; ++t2)
; #pragma unroll
;       for (int j = 0; j < 2; ++j) {
;         unsigned pk[4];
; #pragma unroll
;         for (int e = 0; e < 4; ++e) pk[e] = pack2(s[t2][8 * j + 2 * e], s[t2][8 * j + 2 * e + 1]);
;         u32x4 pku = {pk[0], pk[1], pk[2], pk[3]};
;         bf16x8 pf = __builtin_bit_cast(bf16x8, pku);
; #pragma unroll
;         for (int dt = 0; dt < 2; ++dt) {
;           const int vsw = (((dt * 32 + r) >> 3) & 7) << 3;
;           const bfr* vrow = sV + (dt * 32 + r) * 72;
;           s16x4 lo = *(const s16x4*)(vrow + ((t2 * 32 + 16 * j + 4 * h) ^ vsw));
;           s16x4 hi = *(const s16x4*)(vrow + ((t2 * 32 + 16 * j + 4 * h + 8) ^ vsw));
;           bf16x8 vf = __builtin_shufflevector(lo, hi, 0, 1, 2, 3, 4, 5, 6, 7);
;           accO[dt] = MFMA32(vf, pf, accO[dt]);
;         }
;       }
	ds_read_b64 v[142:143], v168 offset:9280
	ds_read_b64 v[144:145], v176 offset:9216
	ds_read_b64 v[146:147], v177 offset:9216
	ds_read_b64 v[148:149], v178 offset:9216
	ds_read_b64 v[156:157], v179 offset:9216
	ds_read_b64 v[158:159], v180 offset:9216
	ds_read_b64 v[164:165], v181 offset:9216
	ds_read_b64 v[166:167], v160 offset:9216
	v_add_f32_e32 v60, 0, v32
	v_exp_f32_e32 v50, v50
	v_add_f32_e32 v60, v48, v60
	v_exp_f32_e32 v35, v35
	v_add_f32_e32 v60, v33, v60
	v_exp_f32_e32 v51, v51
	v_add_f32_e32 v60, v49, v60
	v_add_f32_e32 v60, v34, v60
	v_exp_f32_e32 v36, v36
	v_add_f32_e32 v60, v50, v60
	v_add_f32_e32 v60, v35, v60
	v_exp_f32_e32 v37, v37
	v_add_f32_e32 v60, v51, v60
	v_add_f32_e32 v60, v122, v60
	v_add_f32_e32 v60, v36, v60
	v_add_f32_e32 v60, v123, v60
	v_add_f32_e32 v60, v37, v60
	v_add_f32_e32 v60, v124, v60
	v_exp_f32_e32 v38, v38
	v_add_f32_e32 v60, v52, v60
	v_exp_f32_e32 v55, v41
	v_sub_f32_e32 v39, v57, v119
	v_add_f32_e32 v60, v125, v60
	v_exp_f32_e32 v39, v39
	v_add_f32_e32 v60, v53, v60
	v_add_f32_e32 v60, v54, v60
	v_exp_f32_e32 v40, v40
	v_add_f32_e32 v60, v38, v60
	v_exp_f32_e32 v57, v43
	v_sub_f32_e32 v41, v59, v119
	v_add_f32_e32 v60, v55, v60
	v_exp_f32_e32 v41, v41
	v_add_f32_e32 v60, v39, v60
	v_add_f32_e32 v60, v56, v60
	v_exp_f32_e32 v42, v42
	v_add_f32_e32 v60, v40, v60
	v_exp_f32_e32 v59, v45
	v_sub_f32_e32 v43, v61, v119
	v_add_f32_e32 v60, v57, v60
	v_exp_f32_e32 v43, v43
	v_pk_add_f32 v[46:47], v[46:47], v[118:119] op_sel:[0,1] op_sel_hi:[1,1] neg_lo:[0,1] neg_hi:[0,1]
	v_add_f32_e32 v60, v41, v60
	v_exp_f32_e32 v46, v46
	v_pk_add_f32 v[62:63], v[62:63], v[118:119] op_sel:[0,1] op_sel_hi:[1,1] neg_lo:[0,1] neg_hi:[0,1]
	v_add_f32_e32 v60, v58, v60
	v_exp_f32_e32 v44, v62
	v_add_f32_e32 v60, v42, v60
	v_exp_f32_e32 v47, v47
	v_add_f32_e32 v60, v59, v60
	v_exp_f32_e32 v45, v63
	v_add_f32_e32 v60, v43, v60
	v_add_f32_e32 v60, v46, v60
	v_add_f32_e32 v60, v44, v60
	v_add_f32_e32 v60, v47, v60
	v_add_f32_e32 v113, v45, v60
	v_cvt_pk_bf16_f32 v32, v32, v33
	v_cvt_pk_bf16_f32 v33, v34, v35
	v_cvt_pk_bf16_f32 v34, v122, v123
	v_cvt_pk_bf16_f32 v35, v124, v125
	v_sub_f32_e32 v96, v96, v119
	v_exp_f32_e32 v96, v96
	s_nop 1
	v_pk_mul_f32 v[30:31], v[30:31], v[96:97] op_sel_hi:[1,0]
	v_pk_mul_f32 v[28:29], v[28:29], v[96:97] op_sel_hi:[1,0]
	v_pk_mul_f32 v[26:27], v[26:27], v[96:97] op_sel_hi:[1,0]
	v_pk_mul_f32 v[24:25], v[24:25], v[96:97] op_sel_hi:[1,0]
	v_pk_mul_f32 v[22:23], v[22:23], v[96:97] op_sel_hi:[1,0]
	v_pk_mul_f32 v[20:21], v[20:21], v[96:97] op_sel_hi:[1,0]
	v_pk_mul_f32 v[18:19], v[18:19], v[96:97] op_sel_hi:[1,0]
	v_pk_mul_f32 v[16:17], v[16:17], v[96:97] op_sel_hi:[1,0]
	v_pk_mul_f32 v[14:15], v[14:15], v[96:97] op_sel_hi:[1,0]
	v_pk_mul_f32 v[12:13], v[12:13], v[96:97] op_sel_hi:[1,0]
	s_waitcnt lgkmcnt(0)
	v_mfma_f32_32x32x16_bf16 v[16:31], v[126:129], v[32:35], v[16:31]
	v_mul_f32_e64 v10, v10, v96
	v_mul_f32_e64 v11, v11, v96
	v_pk_mul_f32 v[8:9], v[8:9], v[96:97] op_sel_hi:[1,0]
	v_pk_mul_f32 v[6:7], v[6:7], v[96:97] op_sel_hi:[1,0]
	v_pk_mul_f32 v[4:5], v[4:5], v[96:97] op_sel_hi:[1,0]
	v_pk_mul_f32 v[2:3], v[2:3], v[96:97] op_sel_hi:[1,0]
	v_pk_mul_f32 v[0:1], v[0:1], v[96:97] op_sel_hi:[1,0]
	v_fmac_f32_e32 v113, v120, v96
	s_nop 1
	v_mfma_f32_32x32x16_bf16 v[0:15], v[130:133], v[32:35], v[0:15]
	v_cvt_pk_bf16_f32 v32, v54, v55
	v_cvt_pk_bf16_f32 v33, v56, v57
	v_cvt_pk_bf16_f32 v34, v58, v59
	v_cvt_pk_bf16_f32 v35, v46, v47
	s_nop 1
	v_mfma_f32_32x32x16_bf16 v[16:31], v[134:137], v[32:35], v[16:31]
	s_nop 1
	v_mfma_f32_32x32x16_bf16 v[0:15], v[138:141], v[32:35], v[0:15]
	v_cvt_pk_bf16_f32 v32, v48, v49
	v_cvt_pk_bf16_f32 v33, v50, v51
	v_cvt_pk_bf16_f32 v34, v36, v37
	v_cvt_pk_bf16_f32 v35, v52, v53
	s_nop 1
	v_mfma_f32_32x32x16_bf16 v[16:31], v[142:145], v[32:35], v[16:31]
	s_nop 1
	v_mfma_f32_32x32x16_bf16 v[0:15], v[146:149], v[32:35], v[0:15]
	v_cvt_pk_bf16_f32 v32, v38, v39
	v_cvt_pk_bf16_f32 v33, v40, v41
	v_cvt_pk_bf16_f32 v34, v42, v43
	v_cvt_pk_bf16_f32 v35, v44, v45
	s_nop 1
	v_mfma_f32_32x32x16_bf16 v[16:31], v[156:159], v[32:35], v[16:31]
	s_nop 1
	v_mfma_f32_32x32x16_bf16 v[0:15], v[164:167], v[32:35], v[0:15]
	s_cbranch_scc1 .LBB0_412
	v_add3_u32 v32, 0, v115, v90
	s_waitcnt vmcnt(1)
	ds_write_b128 v32, v[84:87] offset:18432
	v_add3_u32 v32, 0, v117, v118
	v_add3_u32 v33, 0, v118, v117
	s_waitcnt vmcnt(0)
	ds_write_b16 v32, v80 offset:27648
	ds_write_b16_d16_hi v33, v80 offset:27792
	ds_write_b16 v32, v81 offset:27936
	ds_write_b16_d16_hi v33, v81 offset:28080
	ds_write_b16 v32, v82 offset:28224
	ds_write_b16_d16_hi v33, v82 offset:28368
	ds_write_b16 v32, v83 offset:28512
	ds_write_b16_d16_hi v33, v83 offset:28656
	v_add_u32_e32 v80, 0, v114
	v_add_u32_e32 v81, v80, v152
	s_waitcnt lgkmcnt(0)
	s_barrier
; #define MFMA32(a, b, c) __builtin_amdgcn_mfma_f32_32x32x16_bf16((a), (b), (c), 0, 0, 0)
; DI unsigned pack2(float a, float b) { unsigned r; asm volatile("v_cvt_pk_bf16_f32 %0, %1, %2" : "=v"(r) : "v"(a), "v"(b)); return r; }
; template <int D>
; DI void attn_pass(const bfr* __restrict__ P, int b, int tq_wave, int qcol, int kcol, int vcol, int key0, int nkt, char* smem, f32x16 (&o)[2]) {
;     ...
;     f32x16 s[2];
; #pragma unroll
;     for (int t2 = 0; t2 < 2; ++t2) {
; #pragma unroll
;       for (int i = 0; i < 16; ++i) s[t2][i] = 0.f;
; #pragma unroll
;       for (int ks = 0; ks < KS; ++ks) {
;         bf16x8 a = *(const bf16x8*)(sK + (t2 * 32 + r) * KP + ks * 16 + h * 8);
;         s[t2] = MFMA32(a, qf[ks], s[t2]);
;       }
;     }
;     float mx = s[0][0];
; #pragma unroll
;     for (int i = 0; i < 16; ++i) { mx = fmaxf(mx, s[0][i]); mx = fmaxf(mx, s[1][i]); }
;     mx = fmaxf(mx, __shfl_xor(mx, 32));
;     float mnew = fmaxf(mrun, mx);
;     float alpha = __builtin_amdgcn_exp2f(mrun - mnew);
;     mrun = mnew;
;     float ps = 0.f;
; #pragma unroll
;     for (int i = 0; i < 16; ++i) {
;       s[0][i] = __builtin_amdgcn_exp2f(s[0][i] - mnew); ps += s[0][i];
;       s[1][i] = __builtin_amdgcn_exp2f(s[1][i] - mnew); ps += s[1][i];
;     }
;     lsum = lsum * alpha + ps;
; #pragma unroll
;     for (int i = 0; i < 16; ++i) { accO[0][i] *= alpha; accO[1][i] *= alpha; }
; #pragma unroll
;     for (int t2 = 0; t2 < 2; ++t2)
; #pragma unroll
;       for (int j = 0; j < 2; ++j) {
;         unsigned pk[4];
; #pragma unroll
;         for (int e = 0; e < 4; ++e) pk[e] = pack2(s[t2][8 * j + 2 * e], s[t2][8 * j + 2 * e + 1]);
	ds_read_b128 v[32:35], v81 offset:18432
	ds_read_b128 v[48:51], v81 offset:18464
	s_waitcnt lgkmcnt(1)
	v_mfma_f32_32x32x16_bf16 v[32:47], v[32:35], v[76:79], 0
	v_lshlrev_b32_e32 v152, 1, v88
	s_waitcnt lgkmcnt(0)
	v_mfma_f32_32x32x16_bf16 v[32:47], v[48:51], v[72:75], v[32:47]
	ds_read_b128 v[48:51], v81 offset:18496
	s_waitcnt lgkmcnt(0)
	v_mfma_f32_32x32x16_bf16 v[32:47], v[48:51], v[68:71], v[32:47]
	ds_read_b128 v[48:51], v81 offset:18528
	s_waitcnt lgkmcnt(0)
	v_mfma_f32_32x32x16_bf16 v[32:47], v[48:51], v[64:67], v[32:47]
	ds_read_b128 v[48:51], v81 offset:23040
	s_waitcnt lgkmcnt(0)
	v_mfma_f32_32x32x16_bf16 v[48:63], v[48:51], v[76:79], 0
	ds_read_b128 v[76:79], v81 offset:23072
	s_waitcnt lgkmcnt(0)
	v_mfma_f32_32x32x16_bf16 v[48:63], v[76:79], v[72:75], v[48:63]
	ds_read_b128 v[72:75], v81 offset:23104
	s_waitcnt lgkmcnt(0)
	v_mfma_f32_32x32x16_bf16 v[48:63], v[72:75], v[68:71], v[48:63]
	ds_read_b128 v[68:71], v81 offset:23136
	s_waitcnt lgkmcnt(0)
	v_mfma_f32_32x32x16_bf16 v[48:63], v[68:71], v[64:67], v[48:63]
	v_max_f32_e32 v65, v32, v32
	v_lshl_add_u32 v66, v112, 1, v80
	v_add_u32_e32 v67, 0x1200, v80
	s_nop 8
	v_max_f32_e32 v64, v48, v48
	v_max_f32_e32 v64, v65, v64
	v_max3_f32 v64, v64, v33, v49
	v_max3_f32 v64, v64, v34, v50
	v_max3_f32 v64, v64, v35, v51
	v_max3_f32 v64, v64, v36, v52
	v_max3_f32 v64, v64, v37, v53
	v_max3_f32 v64, v64, v38, v54
	v_max3_f32 v64, v64, v39, v55
	v_max3_f32 v64, v64, v40, v56
	v_max3_f32 v64, v64, v41, v57
	v_max3_f32 v64, v64, v42, v58
	v_max3_f32 v64, v64, v43, v59
	v_max3_f32 v64, v64, v44, v60
	v_max3_f32 v64, v64, v45, v61
	v_max3_f32 v64, v64, v46, v62
	v_max3_f32 v64, v64, v47, v63
	ds_bpermute_b32 v65, v91, v64
	s_waitcnt lgkmcnt(0)
	v_max3_f32 v65, v119, v64, v65
	v_sub_f32_e32 v64, v119, v65
	v_sub_f32_e32 v32, v32, v65
	v_exp_f32_e32 v64, v64
	v_exp_f32_e32 v32, v32
	v_sub_f32_e32 v48, v48, v65
	v_exp_f32_e32 v48, v48
	v_sub_f32_e32 v33, v33, v65
	v_exp_f32_e32 v33, v33
	v_sub_f32_e32 v49, v49, v65
	v_exp_f32_e32 v49, v49
	v_sub_f32_e32 v34, v34, v65
	v_exp_f32_e32 v34, v34
	v_sub_f32_e32 v50, v50, v65
	v_sub_f32_e32 v35, v35, v65
	v_sub_f32_e32 v51, v51, v65
	v_sub_f32_e32 v36, v36, v65
	v_sub_f32_e32 v52, v52, v65
	v_sub_f32_e32 v37, v37, v65
	v_sub_f32_e32 v53, v53, v65
	v_sub_f32_e32 v38, v38, v65
	v_sub_f32_e32 v54, v54, v65
	v_sub_f32_e32 v39, v39, v65
	v_sub_f32_e32 v55, v55, v65
	v_sub_f32_e32 v40, v40, v65
	v_sub_f32_e32 v56, v56, v65
	v_sub_f32_e32 v41, v41, v65
	v_sub_f32_e32 v57, v57, v65
	v_sub_f32_e32 v42, v42, v65
	v_sub_f32_e32 v58, v58, v65
	v_sub_f32_e32 v43, v43, v65
	v_sub_f32_e32 v59, v59, v65
	v_sub_f32_e32 v44, v44, v65
	v_sub_f32_e32 v60, v60, v65
	v_sub_f32_e32 v45, v45, v65
	v_sub_f32_e32 v61, v61, v65
	v_sub_f32_e32 v46, v46, v65
	v_sub_f32_e32 v62, v62, v65
	v_sub_f32_e32 v47, v47, v65
	v_sub_f32_e32 v63, v63, v65
	v_pk_mul_f32 v[30:31], v[30:31], v[64:65] op_sel_hi:[1,0]
	v_pk_mul_f32 v[28:29], v[28:29], v[64:65] op_sel_hi:[1,0]
	v_pk_mul_f32 v[26:27], v[26:27], v[64:65] op_sel_hi:[1,0]
	v_pk_mul_f32 v[24:25], v[24:25], v[64:65] op_sel_hi:[1,0]
	v_pk_mul_f32 v[22:23], v[22:23], v[64:65] op_sel_hi:[1,0]
	v_pk_mul_f32 v[20:21], v[20:21], v[64:65] op_sel_hi:[1,0]
	v_pk_mul_f32 v[18:19], v[18:19], v[64:65] op_sel_hi:[1,0]
	v_pk_mul_f32 v[16:17], v[16:17], v[64:65] op_sel_hi:[1,0]
	v_pk_mul_f32 v[14:15], v[14:15], v[64:65] op_sel_hi:[1,0]
	v_pk_mul_f32 v[12:13], v[12:13], v[64:65] op_sel_hi:[1,0]
	v_pk_mul_f32 v[10:11], v[10:11], v[64:65] op_sel_hi:[1,0]
	v_pk_mul_f32 v[8:9], v[8:9], v[64:65] op_sel_hi:[1,0]
	v_pk_mul_f32 v[6:7], v[6:7], v[64:65] op_sel_hi:[1,0]
	v_pk_mul_f32 v[4:5], v[4:5], v[64:65] op_sel_hi:[1,0]
	v_pk_mul_f32 v[2:3], v[2:3], v[64:65] op_sel_hi:[1,0]
	v_pk_mul_f32 v[0:1], v[0:1], v[64:65] op_sel_hi:[1,0]
	v_add_f32_e32 v65, 0, v32
	v_exp_f32_e32 v50, v50
	v_add_f32_e32 v65, v48, v65
	v_exp_f32_e32 v35, v35
	v_add_f32_e32 v65, v33, v65
	v_exp_f32_e32 v51, v51
	v_add_f32_e32 v65, v49, v65
	v_exp_f32_e32 v36, v36
	v_add_f32_e32 v65, v34, v65
	v_exp_f32_e32 v52, v52
	v_add_f32_e32 v65, v50, v65
	v_exp_f32_e32 v37, v37
	v_add_f32_e32 v65, v35, v65
	v_exp_f32_e32 v53, v53
	v_add_f32_e32 v65, v51, v65
	v_exp_f32_e32 v38, v38
	v_add_f32_e32 v65, v36, v65
	v_exp_f32_e32 v54, v54
	v_add_f32_e32 v65, v52, v65
	v_exp_f32_e32 v39, v39
	v_add_f32_e32 v65, v37, v65
	v_add_f32_e32 v65, v53, v65
	v_add_f32_e32 v65, v38, v65
	v_add_f32_e32 v65, v54, v65
	v_cvt_pk_bf16_f32 v32, v32, v33
	v_cvt_pk_bf16_f32 v33, v34, v35
	v_cvt_pk_bf16_f32 v34, v36, v37
	v_cvt_pk_bf16_f32 v35, v38, v39
	v_lshl_add_u32 v38, v111, 1, v80
	v_add_f32_e32 v65, v39, v65
	ds_read_b64 v[36:37], v66 offset:27648
	ds_read_b64 v[38:39], v38 offset:27648
	s_waitcnt lgkmcnt(0)
	v_mfma_f32_32x32x16_bf16 v[16:31], v[36:39], v[32:35], v[16:31]
	v_lshl_add_u32 v36, v110, 1, v67
	v_lshl_add_u32 v38, v109, 1, v67
	ds_read_b64 v[36:37], v36 offset:27648
	ds_read_b64 v[38:39], v38 offset:27648
	v_exp_f32_e32 v40, v40
	v_exp_f32_e32 v41, v41
	v_exp_f32_e32 v42, v42
	s_waitcnt lgkmcnt(0)
; #define MFMA32(a, b, c) __builtin_amdgcn_mfma_f32_32x32x16_bf16((a), (b), (c), 0, 0, 0)
; DI unsigned pack2(float a, float b) { unsigned r; asm volatile("v_cvt_pk_bf16_f32 %0, %1, %2" : "=v"(r) : "v"(a), "v"(b)); return r; }
; template <int D>
; DI void attn_pass(const bfr* __restrict__ P, int b, int tq_wave, int qcol, int kcol, int vcol, int key0, int nkt, char* smem, f32x16 (&o)[2]) {
;     ...
; #pragma unroll
;         for (int dt = 0; dt < 2; ++dt) {
;           const int vsw = (((dt * 32 + r) >> 3) & 7) << 3;
;           const bfr* vrow = sV + (dt * 32 + r) * 72;
;           s16x4 lo = *(const s16x4*)(vrow + ((t2 * 32 + 16 * j + 4 * h) ^ vsw));
;           s16x4 hi = *(const s16x4*)(vrow + ((t2 * 32 + 16 * j + 4 * h + 8) ^ vsw));
;           bf16x8 vf = __builtin_shufflevector(lo, hi, 0, 1, 2, 3, 4, 5, 6, 7);
;           accO[dt] = MFMA32(vf, pf, accO[dt]);
;         }
;       }
;   }
;   lsum += __shfl_xor(lsum, 32);
;   float inv = 1.f / lsum;
; #pragma unroll
;   for (int i = 0; i < 16; ++i) { o[0][i] = accO[0][i] * inv; o[1][i] = accO[1][i] * inv; }
; DI void store_o(bfr* O, int m, int colbase, int h, const f32x16 (&o)[2]) {
; #pragma unroll
;   for (int dt = 0; dt < 2; ++dt)
; #pragma unroll
;     for (int g4 = 0; g4 < 4; ++g4) {
;       int dv = dt * 32 + 8 * g4 + 4 * h;
;       uint2 pk; pk.x = pack2(o[dt][4 * g4], o[dt][4 * g4 + 1]); pk.y = pack2(o[dt][4 * g4 + 2], o[dt][4 * g4 + 3]);
;       *(uint2*)(O + (size_t)m * DM + colbase + dv) = pk;
;     }
; }
	v_mfma_f32_32x32x16_bf16 v[0:15], v[36:39], v[32:35], v[0:15]
	v_lshl_add_u32 v36, v108, 1, v80
	v_lshl_add_u32 v38, v107, 1, v80
	v_exp_f32_e32 v43, v43
	v_exp_f32_e32 v44, v44
	v_exp_f32_e32 v45, v45
	v_exp_f32_e32 v46, v46
	v_exp_f32_e32 v47, v47
	v_cvt_pk_bf16_f32 v32, v40, v41
	v_cvt_pk_bf16_f32 v33, v42, v43
	v_cvt_pk_bf16_f32 v34, v44, v45
	v_cvt_pk_bf16_f32 v35, v46, v47
	ds_read_b64 v[36:37], v36 offset:27648
	ds_read_b64 v[38:39], v38 offset:27648
	s_waitcnt lgkmcnt(0)
	v_mfma_f32_32x32x16_bf16 v[16:31], v[36:39], v[32:35], v[16:31]
	v_lshl_add_u32 v36, v106, 1, v67
	v_lshl_add_u32 v38, v105, 1, v67
	ds_read_b64 v[36:37], v36 offset:27648
	ds_read_b64 v[38:39], v38 offset:27648
	v_exp_f32_e32 v55, v55
	v_exp_f32_e32 v56, v56
	v_exp_f32_e32 v57, v57
	s_waitcnt lgkmcnt(0)
	v_mfma_f32_32x32x16_bf16 v[0:15], v[36:39], v[32:35], v[0:15]
	v_lshl_add_u32 v38, v104, 1, v80
	v_cvt_pk_bf16_f32 v32, v48, v49
	v_cvt_pk_bf16_f32 v33, v50, v51
	v_cvt_pk_bf16_f32 v34, v52, v53
	v_cvt_pk_bf16_f32 v35, v54, v55
	ds_read_b64 v[36:37], v66 offset:27712
	ds_read_b64 v[38:39], v38 offset:27648
	s_waitcnt lgkmcnt(0)
	v_mfma_f32_32x32x16_bf16 v[16:31], v[36:39], v[32:35], v[16:31]
	v_lshl_add_u32 v36, v103, 1, v67
	v_lshl_add_u32 v38, v102, 1, v67
	ds_read_b64 v[36:37], v36 offset:27648
	ds_read_b64 v[38:39], v38 offset:27648
	v_exp_f32_e32 v58, v58
	v_exp_f32_e32 v59, v59
	v_exp_f32_e32 v60, v60
	s_waitcnt lgkmcnt(0)
	v_mfma_f32_32x32x16_bf16 v[0:15], v[36:39], v[32:35], v[0:15]
	v_lshl_add_u32 v36, v100, 1, v80
	v_lshl_add_u32 v38, v101, 1, v80
	v_exp_f32_e32 v61, v61
	v_exp_f32_e32 v62, v62
	v_exp_f32_e32 v63, v63
	v_cvt_pk_bf16_f32 v32, v56, v57
	v_cvt_pk_bf16_f32 v33, v58, v59
	v_cvt_pk_bf16_f32 v34, v60, v61
	v_cvt_pk_bf16_f32 v35, v62, v63
	ds_read_b64 v[36:37], v36 offset:27648
	ds_read_b64 v[38:39], v38 offset:27648
	v_add_f32_e32 v65, v55, v65
	v_add_f32_e32 v65, v40, v65
	v_add_f32_e32 v65, v56, v65
	v_add_f32_e32 v65, v41, v65
	v_add_f32_e32 v65, v57, v65
	v_add_f32_e32 v65, v42, v65
	v_add_f32_e32 v65, v58, v65
	v_add_f32_e32 v65, v43, v65
	v_add_f32_e32 v65, v59, v65
	s_waitcnt lgkmcnt(0)
	v_mfma_f32_32x32x16_bf16 v[16:31], v[36:39], v[32:35], v[16:31]
	v_lshl_add_u32 v36, v99, 1, v67
	v_lshl_add_u32 v38, v98, 1, v67
	v_add_f32_e32 v65, v44, v65
	ds_read_b64 v[36:37], v36 offset:27648
	ds_read_b64 v[38:39], v38 offset:27648
	v_add_f32_e32 v65, v60, v65
	v_add_f32_e32 v65, v45, v65
	v_add_f32_e32 v65, v61, v65
	v_add_f32_e32 v65, v46, v65
	v_add_f32_e32 v65, v62, v65
	v_add_f32_e32 v65, v47, v65
	v_add_f32_e32 v65, v63, v65
	v_fmac_f32_e32 v65, v113, v64
	s_waitcnt lgkmcnt(0)
	v_mfma_f32_32x32x16_bf16 v[0:15], v[36:39], v[32:35], v[0:15]
	ds_bpermute_b32 v32, v91, v65
	s_waitcnt lgkmcnt(0)
	v_add_f32_e32 v32, v65, v32
	v_div_scale_f32 v33, s[8:9], v32, v32, 1.0
	v_rcp_f32_e32 v34, v33
	s_load_dwordx4 s[8:11], s[0:1], 0x100
	s_waitcnt lgkmcnt(0)
	s_mov_b64 s[8:9], 0x2b7c700
	v_fma_f32 v35, -v33, v34, 1.0
	v_fmac_f32_e32 v34, v35, v34
	v_div_scale_f32 v35, vcc, 1.0, v32, 1.0
	v_mul_f32_e32 v36, v35, v34
	v_fma_f32 v37, -v33, v36, v35
	v_fmac_f32_e32 v36, v37, v34
	v_fma_f32 v33, -v33, v36, v35
	v_div_fmas_f32 v33, v33, v34, v36
	v_div_fixup_f32 v32, v33, v32, 1.0
	v_mul_f32_e32 v33, v0, v32
	v_and_or_b32 v0, v89, 31, v97
	v_mul_f32_e32 v34, v1, v32
	v_ashrrev_i32_e32 v1, 31, v0
	v_lshlrev_b64 v[0:1], 11, v[0:1]
	v_mul_f32_e32 v37, v4, v32
	v_lshl_add_u64 v[0:1], s[10:11], 0, v[0:1]
	v_lshrrev_b32_e32 v4, 2, v89
	v_lshl_add_u64 v[0:1], v[0:1], 0, v[152:153]
	v_and_b32_e32 v152, 8, v4
	v_lshl_add_u64 v[0:1], v[0:1], 0, v[152:153]
	v_mul_f32_e32 v38, v5, v32
	v_lshl_add_u64 v[4:5], v[0:1], 0, s[8:9]
	s_mov_b32 s8, 0x2b7c000
	v_add_co_u32_e32 v0, vcc, s8, v0
	v_mul_f32_e32 v16, v16, v32
	s_nop 0
	v_addc_co_u32_e32 v1, vcc, 0, v1, vcc
	v_mul_f32_e32 v17, v17, v32
	v_mul_f32_e32 v18, v18, v32
	v_mul_f32_e32 v35, v2, v32
	v_mul_f32_e32 v19, v19, v32
	v_mul_f32_e32 v36, v3, v32
	v_mul_f32_e32 v20, v20, v32
	v_mul_f32_e32 v21, v21, v32
	v_mul_f32_e32 v22, v22, v32
	v_mul_f32_e32 v23, v23, v32
	v_cvt_pk_bf16_f32 v2, v16, v17
	v_cvt_pk_bf16_f32 v3, v18, v19
	global_store_dwordx2 v[0:1], v[2:3], off offset:1792
	v_cvt_pk_bf16_f32 v0, v20, v21
	v_cvt_pk_bf16_f32 v1, v22, v23
	v_mul_f32_e32 v24, v24, v32
	v_mul_f32_e32 v25, v25, v32
	v_mul_f32_e32 v26, v26, v32
	v_mul_f32_e32 v27, v27, v32
	global_store_dwordx2 v[4:5], v[0:1], off offset:16
	v_cvt_pk_bf16_f32 v0, v24, v25
	v_cvt_pk_bf16_f32 v1, v26, v27
	v_mul_f32_e32 v28, v28, v32
	v_mul_f32_e32 v29, v29, v32
	v_mul_f32_e32 v30, v30, v32
	v_mul_f32_e32 v31, v31, v32
	global_store_dwordx2 v[4:5], v[0:1], off offset:32
	v_cvt_pk_bf16_f32 v0, v28, v29
	v_cvt_pk_bf16_f32 v1, v30, v31
	global_store_dwordx2 v[4:5], v[0:1], off offset:48
	v_cvt_pk_bf16_f32 v0, v33, v34
	v_cvt_pk_bf16_f32 v1, v35, v36
	v_mul_f32_e32 v6, v6, v32
	v_mul_f32_e32 v7, v7, v32
	global_store_dwordx2 v[4:5], v[0:1], off offset:64
	v_cvt_pk_bf16_f32 v0, v37, v38
	v_cvt_pk_bf16_f32 v1, v6, v7
	v_mul_f32_e32 v8, v8, v32
	v_mul_f32_e32 v9, v9, v32
	v_mul_f32_e32 v10, v10, v32
	v_mul_f32_e32 v11, v11, v32
	global_store_dwordx2 v[4:5], v[0:1], off offset:80
	v_cvt_pk_bf16_f32 v0, v8, v9
	v_cvt_pk_bf16_f32 v1, v10, v11
	v_mul_f32_e32 v12, v12, v32
	v_mul_f32_e32 v13, v13, v32
	v_mul_f32_e32 v14, v14, v32
	v_mul_f32_e32 v15, v15, v32
	global_store_dwordx2 v[4:5], v[0:1], off offset:96
	v_cvt_pk_bf16_f32 v0, v12, v13
	v_cvt_pk_bf16_f32 v1, v14, v15
	global_store_dwordx2 v[4:5], v[0:1], off offset:112

; DI void attn_pass_da(const bfr* __restrict__ P, int b, int tq_wave, int qcol, int kcol, int vcol, int key0, int nkt, char* smem, f32x16 (&o0)[2], f32x16 (&o1)[2]) {
;     ...
;   for (int kt = 0; kt < nkt; ++kt) {
;     bfr* sK = sbase + (kt & 1) * 9216;
;     bfr* sV = sK + 64 * 72;
;     { int c = gt, row = c >> 3, kc = c & 7; *(u32x4*)(sK + row * KP + kc * 8) = kreg[0]; }
;     for (int i = 0; i < 1; ++i) {
;       int c = gt, row = c >> 3, kc = c & 7;
;       unsigned wds[4] = {vreg[i].x, vreg[i].y, vreg[i].z, vreg[i].w};
; #pragma unroll
;       for (int e = 0; e < 4; ++e) {
;         sV[(kc * 8 + 2 * e) * 72 + (row ^ (kc << 3))] = (bfr)(wds[e] & 0xffffu);
;         sV[(kc * 8 + 2 * e + 1) * 72 + (row ^ (kc << 3))] = (bfr)(wds[e] >> 16);
;       }
;     }
;     __syncthreads();
;     if (kt + 1 < nkt) {
;       const bfr* Pn = Pb + (size_t)(kt + 1) * 64 * PW;
;       { int c = gt, row = c >> 3, kc = c & 7; kreg[0] = *(const u32x4*)(Pn + (size_t)row * PW + kcol + kc * 8); vreg[0] = *(const u32x4*)(Pn + (size_t)row * PW + vcol + kc * 8); }
;     }
;     f32x16 s0[2], s1[2];
; #pragma unroll
;     for (int t2 = 0; t2 < 2; ++t2) {
; #pragma unroll
;       for (int i = 0; i < 16; ++i) { s0[t2][i] = 0.f; s1[t2][i] = 0.f; }
; #pragma unroll
;       for (int ks = 0; ks < 2; ++ks) {
;         bf16x8 a0 = *(const bf16x8*)(sK + (t2 * 32 + r) * KP + ks * 16 + h * 8);
;         bf16x8 a1 = *(const bf16x8*)(sK + (t2 * 32 + r) * KP + 32 + ks * 16 + h * 8);
;         s0[t2] = MFMA32(a0, qf[ks], s0[t2]);
;         s1[t2] = MFMA32(a1, qf[2 + ks], s1[t2]);
;       }
;     }
;     float mx0 = s0[0][0], mx1 = s1[0][0];
; #pragma unroll
;     for (int i = 0; i < 16; ++i) { mx0 = fmaxf(mx0, fmaxf(s0[0][i], s0[1][i])); mx1 = fmaxf(mx1, fmaxf(s1[0][i], s1[1][i])); }
;     mx0 = fmaxf(mx0, __shfl_xor(mx0, 32)); mx1 = fmaxf(mx1, __shfl_xor(mx1, 32));
;     const float mn0 = fmaxf(m0, mx0), mn1 = fmaxf(m1, mx1);
;     const float al0 = __builtin_amdgcn_exp2f(m0 - mn0), al1 = __builtin_amdgcn_exp2f(m1 - mn1);
;     m0 = mn0; m1 = mn1;
;     float ps0 = 0.f, ps1 = 0.f;
; #pragma unroll
;     for (int i = 0; i < 16; ++i) {
;       s0[0][i] = __builtin_amdgcn_exp2f(s0[0][i] - mn0); ps0 += s0[0][i];
;       s0[1][i] = __builtin_amdgcn_exp2f(s0[1][i] - mn0); ps0 += s0[1][i];
;       s1[0][i] = __builtin_amdgcn_exp2f(s1[0][i] - mn1); ps1 += s1[0][i];
.LBB0_421:
	s_bitcmp1_b32 s10, 0
	s_cselect_b32 s11, 0x4800, 0
	s_add_i32 s11, s11, 0
	v_add3_u32 v64, s11, v206, v152
	v_add_u32_e32 v194, s11, v205
	s_waitcnt vmcnt(1)
	ds_write_b128 v64, v[148:151]
	v_add3_u32 v64, s11, v207, v208
	v_add3_u32 v65, s11, v208, v207
	v_add_u32_e32 v100, v194, v204
	s_waitcnt vmcnt(0)
	ds_write_b16 v64, v144 offset:9216
	ds_write_b16_d16_hi v65, v144 offset:9360
	ds_write_b16 v64, v145 offset:9504
	ds_write_b16_d16_hi v65, v145 offset:9648
	ds_write_b16 v64, v146 offset:9792
	ds_write_b16_d16_hi v65, v146 offset:9936
	ds_write_b16 v64, v147 offset:10080
	ds_write_b16_d16_hi v65, v147 offset:10224
	s_waitcnt lgkmcnt(0)
	s_barrier
	global_load_dwordx4 v[148:151], v[158:159], off
	global_load_dwordx4 v[144:147], v[158:159], off offset:512
	ds_read_b128 v[64:67], v100 offset:64
	ds_read_b128 v[68:71], v100
	ds_read_b128 v[96:99], v100 offset:32
	ds_read_b128 v[100:103], v100 offset:96
	s_waitcnt lgkmcnt(2)
	v_mfma_f32_32x32x16_bf16 v[80:95], v[68:71], v[140:143], 0
	v_add_u32_e32 v195, s11, v211
	v_add_u32_e32 v192, v195, v204
	v_mov_b32_e32 v160, v209
	v_mov_b32_e32 v161, v210
	s_add_i32 s10, s10, 1
	v_lshl_add_u64 v[158:159], v[158:159], 0, s[12:13]
	s_cmp_lg_u32 s10, 35
	v_mfma_f32_32x32x16_bf16 v[64:79], v[64:67], v[136:139], 0
	s_waitcnt lgkmcnt(1)
	v_mfma_f32_32x32x16_bf16 v[80:95], v[96:99], v[132:135], v[80:95]
	s_waitcnt lgkmcnt(0)
	v_mfma_f32_32x32x16_bf16 v[64:79], v[100:103], v[128:131], v[64:79]
	ds_read_b128 v[96:99], v192 offset:64
	ds_read_b128 v[100:103], v192
	ds_read_b128 v[212:215], v192 offset:32
	ds_read_b128 v[216:219], v192 offset:96
	s_nop 5
	v_max3_f32 v209, v80, v81, v82
	v_max3_f32 v209, v209, v83, v84
	v_max3_f32 v193, v64, v65, v66
	s_waitcnt lgkmcnt(2)
	v_mfma_f32_32x32x16_bf16 v[112:127], v[100:103], v[140:143], 0
	v_mfma_f32_32x32x16_bf16 v[96:111], v[96:99], v[136:139], 0
	s_waitcnt lgkmcnt(1)
	v_mfma_f32_32x32x16_bf16 v[112:127], v[212:215], v[132:135], v[112:127]
	v_max3_f32 v193, v193, v67, v68
	v_max3_f32 v209, v209, v85, v86
	s_waitcnt lgkmcnt(0)
	v_mfma_f32_32x32x16_bf16 v[96:111], v[216:219], v[128:131], v[96:111]
	v_max3_f32 v193, v193, v69, v70
	v_max3_f32 v209, v209, v87, v88
	v_max3_f32 v193, v193, v71, v72
	v_max3_f32 v209, v209, v89, v90
	v_max3_f32 v193, v193, v73, v74
	v_max3_f32 v209, v209, v91, v92
	v_max3_f32 v193, v193, v75, v76
	v_max3_f32 v209, v209, v93, v94
	v_max3_f32 v193, v193, v77, v78
	v_max3_f32 v209, v209, v95, v112
	v_max3_f32 v209, v209, v113, v114
	v_max3_f32 v209, v209, v115, v116
	v_max3_f32 v209, v209, v117, v118
	v_max3_f32 v209, v209, v119, v120
	v_max3_f32 v209, v209, v121, v122
	v_max3_f32 v209, v209, v123, v124
	v_max3_f32 v209, v209, v125, v126
	v_max_f32_e32 v192, v209, v127
	v_max3_f32 v193, v193, v79, v96
	v_max3_f32 v193, v193, v97, v98
	v_max3_f32 v193, v193, v99, v100
	v_max3_f32 v193, v193, v101, v102
	v_max3_f32 v193, v193, v103, v104
	v_max3_f32 v193, v193, v105, v106
	v_max3_f32 v193, v193, v107, v108
	v_max3_f32 v193, v193, v109, v110
	v_max_f32_e32 v193, v193, v111
	ds_bpermute_b32 v210, v166, v193
	ds_bpermute_b32 v209, v166, v192
	s_waitcnt lgkmcnt(1)
	v_max3_f32 v210, v161, v193, v210
	s_waitcnt lgkmcnt(0)
	v_max3_f32 v209, v160, v192, v209
	v_pk_add_f32 v[64:65], v[64:65], v[210:211] op_sel_hi:[1,0] neg_lo:[0,1] neg_hi:[0,1]
	v_pk_add_f32 v[80:81], v[80:81], v[208:209] op_sel:[0,1] op_sel_hi:[1,1] neg_lo:[0,1] neg_hi:[0,1]
	v_exp_f32_e32 v193, v64
	v_pk_add_f32 v[96:97], v[96:97], v[210:211] op_sel_hi:[1,0] neg_lo:[0,1] neg_hi:[0,1]
	v_exp_f32_e32 v192, v80
	v_pk_add_f32 v[112:113], v[112:113], v[208:209] op_sel:[0,1] op_sel_hi:[1,1] neg_lo:[0,1] neg_hi:[0,1]
	v_exp_f32_e32 v213, v96
	v_exp_f32_e32 v212, v112
	v_exp_f32_e32 v80, v81
	v_exp_f32_e32 v96, v113
	v_exp_f32_e32 v81, v65
	v_exp_f32_e32 v97, v97
	v_pk_add_f32 v[82:83], v[82:83], v[208:209] op_sel:[0,1] op_sel_hi:[1,1] neg_lo:[0,1] neg_hi:[0,1]
	v_exp_f32_e32 v112, v82
	v_pk_add_f32 v[114:115], v[114:115], v[208:209] op_sel:[0,1] op_sel_hi:[1,1] neg_lo:[0,1] neg_hi:[0,1]
	v_exp_f32_e32 v214, v114
	v_pk_add_f32 v[66:67], v[66:67], v[210:211] op_sel_hi:[1,0] neg_lo:[0,1] neg_hi:[0,1]
	v_exp_f32_e32 v113, v66
	v_pk_add_f32 v[98:99], v[98:99], v[210:211] op_sel_hi:[1,0] neg_lo:[0,1] neg_hi:[0,1]
	v_exp_f32_e32 v215, v98
	v_exp_f32_e32 v82, v83
	v_exp_f32_e32 v98, v115
	v_exp_f32_e32 v83, v67
	v_exp_f32_e32 v99, v99
	v_pk_add_f32 v[84:85], v[84:85], v[208:209] op_sel:[0,1] op_sel_hi:[1,1] neg_lo:[0,1] neg_hi:[0,1]
	v_exp_f32_e32 v114, v84
	v_pk_add_f32 v[116:117], v[116:117], v[208:209] op_sel:[0,1] op_sel_hi:[1,1] neg_lo:[0,1] neg_hi:[0,1]
	v_exp_f32_e32 v216, v116
	v_pk_add_f32 v[68:69], v[68:69], v[210:211] op_sel_hi:[1,0] neg_lo:[0,1] neg_hi:[0,1]
	v_exp_f32_e32 v115, v68
	v_pk_add_f32 v[100:101], v[100:101], v[210:211] op_sel_hi:[1,0] neg_lo:[0,1] neg_hi:[0,1]
	v_exp_f32_e32 v217, v100
	v_exp_f32_e32 v84, v85
	v_exp_f32_e32 v100, v117
	v_exp_f32_e32 v85, v69
	v_exp_f32_e32 v101, v101
	v_pk_add_f32 v[86:87], v[86:87], v[208:209] op_sel:[0,1] op_sel_hi:[1,1] neg_lo:[0,1] neg_hi:[0,1]
	v_exp_f32_e32 v116, v86
	v_pk_add_f32 v[118:119], v[118:119], v[208:209] op_sel:[0,1] op_sel_hi:[1,1] neg_lo:[0,1] neg_hi:[0,1]
	v_exp_f32_e32 v218, v118
	v_pk_add_f32 v[70:71], v[70:71], v[210:211] op_sel_hi:[1,0] neg_lo:[0,1] neg_hi:[0,1]
	v_exp_f32_e32 v117, v70
	v_pk_add_f32 v[102:103], v[102:103], v[210:211] op_sel_hi:[1,0] neg_lo:[0,1] neg_hi:[0,1]
	v_exp_f32_e32 v219, v102
	v_exp_f32_e32 v70, v87
	v_exp_f32_e32 v86, v119
	v_exp_f32_e32 v71, v71
	v_exp_f32_e32 v87, v103
	v_pk_add_f32 v[88:89], v[88:89], v[208:209] op_sel:[0,1] op_sel_hi:[1,1] neg_lo:[0,1] neg_hi:[0,1]
; DI void attn_pass_da(const bfr* __restrict__ P, int b, int tq_wave, int qcol, int kcol, int vcol, int key0, int nkt, char* smem, f32x16 (&o0)[2], f32x16 (&o1)[2]) {
;     ...
; #pragma unroll
;     for (int i = 0; i < 16; ++i) {
;       s0[0][i] = __builtin_amdgcn_exp2f(s0[0][i] - mn0); ps0 += s0[0][i];
;       s0[1][i] = __builtin_amdgcn_exp2f(s0[1][i] - mn0); ps0 += s0[1][i];
;       s1[0][i] = __builtin_amdgcn_exp2f(s1[0][i] - mn1); ps1 += s1[0][i];
;       s1[1][i] = __builtin_amdgcn_exp2f(s1[1][i] - mn1); ps1 += s1[1][i];
;     }
;     l0 = l0 * al0 + ps0; l1 = l1 * al1 + ps1;
; #pragma unroll
;     for (int i = 0; i < 16; ++i) { acc0[0][i] *= al0; acc0[1][i] *= al0; acc1[0][i] *= al1; acc1[1][i] *= al1; }
	v_exp_f32_e32 v102, v88
	v_pk_add_f32 v[120:121], v[120:121], v[208:209] op_sel:[0,1] op_sel_hi:[1,1] neg_lo:[0,1] neg_hi:[0,1]
	v_exp_f32_e32 v118, v120
	v_pk_add_f32 v[72:73], v[72:73], v[210:211] op_sel_hi:[1,0] neg_lo:[0,1] neg_hi:[0,1]
	v_exp_f32_e32 v103, v72
	v_pk_add_f32 v[104:105], v[104:105], v[210:211] op_sel_hi:[1,0] neg_lo:[0,1] neg_hi:[0,1]
	v_exp_f32_e32 v119, v104
	v_exp_f32_e32 v88, v89
	v_exp_f32_e32 v104, v121
	v_exp_f32_e32 v89, v73
	v_exp_f32_e32 v105, v105
	v_pk_add_f32 v[90:91], v[90:91], v[208:209] op_sel:[0,1] op_sel_hi:[1,1] neg_lo:[0,1] neg_hi:[0,1]
	v_exp_f32_e32 v120, v90
	v_pk_add_f32 v[122:123], v[122:123], v[208:209] op_sel:[0,1] op_sel_hi:[1,1] neg_lo:[0,1] neg_hi:[0,1]
	v_exp_f32_e32 v220, v122
	v_pk_add_f32 v[74:75], v[74:75], v[210:211] op_sel_hi:[1,0] neg_lo:[0,1] neg_hi:[0,1]
	v_exp_f32_e32 v121, v74
	v_pk_add_f32 v[106:107], v[106:107], v[210:211] op_sel_hi:[1,0] neg_lo:[0,1] neg_hi:[0,1]
	v_exp_f32_e32 v221, v106
	v_exp_f32_e32 v90, v91
	v_exp_f32_e32 v106, v123
	v_exp_f32_e32 v91, v75
	v_exp_f32_e32 v107, v107
	v_pk_add_f32 v[92:93], v[92:93], v[208:209] op_sel:[0,1] op_sel_hi:[1,1] neg_lo:[0,1] neg_hi:[0,1]
	v_exp_f32_e32 v122, v92
	v_pk_add_f32 v[124:125], v[124:125], v[208:209] op_sel:[0,1] op_sel_hi:[1,1] neg_lo:[0,1] neg_hi:[0,1]
	v_exp_f32_e32 v222, v124
	v_pk_add_f32 v[76:77], v[76:77], v[210:211] op_sel_hi:[1,0] neg_lo:[0,1] neg_hi:[0,1]
	v_exp_f32_e32 v123, v76
	v_pk_add_f32 v[108:109], v[108:109], v[210:211] op_sel_hi:[1,0] neg_lo:[0,1] neg_hi:[0,1]
	v_exp_f32_e32 v223, v108
	v_exp_f32_e32 v92, v93
	v_exp_f32_e32 v108, v125
	v_exp_f32_e32 v93, v77
	v_exp_f32_e32 v109, v109
	v_pk_add_f32 v[94:95], v[94:95], v[208:209] op_sel:[0,1] op_sel_hi:[1,1] neg_lo:[0,1] neg_hi:[0,1]
	v_exp_f32_e32 v124, v94
	v_pk_add_f32 v[126:127], v[126:127], v[208:209] op_sel:[0,1] op_sel_hi:[1,1] neg_lo:[0,1] neg_hi:[0,1]
	v_exp_f32_e32 v224, v126
	v_pk_add_f32 v[78:79], v[78:79], v[210:211] op_sel_hi:[1,0] neg_lo:[0,1] neg_hi:[0,1]
	v_exp_f32_e32 v125, v78
	v_pk_add_f32 v[110:111], v[110:111], v[210:211] op_sel_hi:[1,0] neg_lo:[0,1] neg_hi:[0,1]
	v_exp_f32_e32 v225, v110
	v_exp_f32_e32 v94, v95
	v_exp_f32_e32 v110, v127
	v_exp_f32_e32 v95, v79
	v_exp_f32_e32 v111, v111
	v_pk_add_f32 v[64:65], v[192:193], 0 op_sel_hi:[1,0]
	v_sub_f32_e32 v161, v161, v210
	v_pk_add_f32 v[64:65], v[212:213], v[64:65]
	v_exp_f32_e32 v161, v161
	v_pk_add_f32 v[64:65], v[80:81], v[64:65]
	v_lshl_add_u32 v74, v180, 1, v194
	v_pk_add_f32 v[64:65], v[96:97], v[64:65]
	v_lshl_add_u32 v76, v179, 1, v195
	v_pk_add_f32 v[64:65], v[112:113], v[64:65]
	v_lshl_add_u32 v78, v178, 1, v195
	v_pk_add_f32 v[64:65], v[214:215], v[64:65]
	v_sub_f32_e32 v160, v160, v209
	v_pk_add_f32 v[64:65], v[82:83], v[64:65]
	v_exp_f32_e32 v160, v160
	v_pk_add_f32 v[64:65], v[98:99], v[64:65]
	v_pk_mul_f32 v[62:63], v[62:63], v[160:161] op_sel_hi:[1,0]
	v_pk_add_f32 v[64:65], v[114:115], v[64:65]
	v_pk_mul_f32 v[60:61], v[60:61], v[160:161] op_sel_hi:[1,0]
	v_pk_add_f32 v[64:65], v[216:217], v[64:65]
	v_pk_mul_f32 v[58:59], v[58:59], v[160:161] op_sel_hi:[1,0]
	v_pk_add_f32 v[64:65], v[84:85], v[64:65]
	v_pk_mul_f32 v[56:57], v[56:57], v[160:161] op_sel_hi:[1,0]
	v_pk_add_f32 v[64:65], v[100:101], v[64:65]
	v_pk_mul_f32 v[54:55], v[54:55], v[160:161] op_sel_hi:[1,0]
	v_pk_add_f32 v[64:65], v[116:117], v[64:65]
	v_pk_mul_f32 v[52:53], v[52:53], v[160:161] op_sel_hi:[1,0]
	v_pk_add_f32 v[64:65], v[218:219], v[64:65]
	v_pk_mul_f32 v[50:51], v[50:51], v[160:161] op_sel_hi:[1,0]
	v_pk_add_f32 v[64:65], v[70:71], v[64:65]
	v_pk_mul_f32 v[48:49], v[48:49], v[160:161] op_sel_hi:[1,0]
	v_pk_add_f32 v[64:65], v[86:87], v[64:65]
	v_pk_mul_f32 v[30:31], v[30:31], v[160:161] op_sel_hi:[1,0]
	v_pk_add_f32 v[64:65], v[102:103], v[64:65]
	v_pk_mul_f32 v[28:29], v[28:29], v[160:161] op_sel_hi:[1,0]
	v_pk_add_f32 v[64:65], v[118:119], v[64:65]
	v_pk_mul_f32 v[26:27], v[26:27], v[160:161] op_sel_hi:[1,0]
	v_pk_add_f32 v[64:65], v[88:89], v[64:65]
	v_pk_mul_f32 v[24:25], v[24:25], v[160:161] op_sel_hi:[1,0]
	v_pk_add_f32 v[64:65], v[104:105], v[64:65]
	v_pk_mul_f32 v[22:23], v[22:23], v[160:161] op_sel_hi:[1,0]
	v_pk_add_f32 v[64:65], v[120:121], v[64:65]
	v_pk_mul_f32 v[20:21], v[20:21], v[160:161] op_sel_hi:[1,0]
	v_pk_add_f32 v[126:127], v[220:221], v[64:65]
	v_cvt_pk_bf16_f32 v64, v192, v80
	v_cvt_pk_bf16_f32 v65, v112, v82
	v_lshl_add_u32 v112, v181, 1, v194
	v_cvt_pk_bf16_f32 v66, v114, v84
	v_cvt_pk_bf16_f32 v67, v116, v70
	v_cvt_pk_bf16_f32 v68, v193, v81
	v_cvt_pk_bf16_f32 v69, v113, v83
	v_cvt_pk_bf16_f32 v70, v115, v85
	v_cvt_pk_bf16_f32 v71, v117, v71
	ds_read_b64 v[72:73], v112 offset:9216
	ds_read_b64 v[74:75], v74 offset:9216
	ds_read_b64 v[76:77], v76 offset:9216
	ds_read_b64 v[78:79], v78 offset:9216
	v_mov_b32_e32 v82, v161
	v_pk_mul_f32 v[46:47], v[46:47], v[82:83] op_sel_hi:[1,0]
	v_pk_mul_f32 v[44:45], v[44:45], v[82:83] op_sel_hi:[1,0]
	v_pk_mul_f32 v[42:43], v[42:43], v[82:83] op_sel_hi:[1,0]
	v_pk_mul_f32 v[40:41], v[40:41], v[82:83] op_sel_hi:[1,0]
	v_pk_mul_f32 v[38:39], v[38:39], v[82:83] op_sel_hi:[1,0]
	v_pk_mul_f32 v[36:37], v[36:37], v[82:83] op_sel_hi:[1,0]
	v_pk_mul_f32 v[34:35], v[34:35], v[82:83] op_sel_hi:[1,0]
	v_pk_mul_f32 v[32:33], v[32:33], v[82:83] op_sel_hi:[1,0]
	v_pk_mul_f32 v[14:15], v[14:15], v[82:83] op_sel_hi:[1,0]
	v_pk_mul_f32 v[12:13], v[12:13], v[82:83] op_sel_hi:[1,0]
	v_pk_mul_f32 v[10:11], v[10:11], v[82:83] op_sel_hi:[1,0]
	v_pk_mul_f32 v[8:9], v[8:9], v[82:83] op_sel_hi:[1,0]
	v_pk_mul_f32 v[6:7], v[6:7], v[82:83] op_sel_hi:[1,0]
	v_pk_mul_f32 v[4:5], v[4:5], v[82:83] op_sel_hi:[1,0]
	v_pk_mul_f32 v[2:3], v[2:3], v[82:83] op_sel_hi:[1,0]
	v_pk_mul_f32 v[0:1], v[0:1], v[82:83] op_sel_hi:[1,0]
	v_pk_add_f32 v[82:83], v[90:91], v[126:127]
	s_waitcnt lgkmcnt(2)
; DI void attn_pass_da(const bfr* __restrict__ P, int b, int tq_wave, int qcol, int kcol, int vcol, int key0, int nkt, char* smem, f32x16 (&o0)[2], f32x16 (&o1)[2]) {
;     ...
;     bfr* sK = sbase + (kt & 1) * 9216;
;     bfr* sV = sK + 64 * 72;
;     { int c = gt, row = c >> 3, kc = c & 7; *(u32x4*)(sK + row * KP + kc * 8) = kreg[0]; }
;     for (int i = 0; i < 1; ++i) {
;       int c = gt, row = c >> 3, kc = c & 7;
;       unsigned wds[4] = {vreg[i].x, vreg[i].y, vreg[i].z, vreg[i].w};
; #pragma unroll
;       for (int e = 0; e < 4; ++e) {
;         sV[(kc * 8 + 2 * e) * 72 + (row ^ (kc << 3))] = (bfr)(wds[e] & 0xffffu);
;         sV[(kc * 8 + 2 * e + 1) * 72 + (row ^ (kc << 3))] = (bfr)(wds[e] >> 16);
;       }
;     }
;     __syncthreads();
;     if (kt + 1 < nkt) {
;       const bfr* Pn = Pb + (size_t)(kt + 1) * 64 * PW;
;       { int c = gt, row = c >> 3, kc = c & 7; kreg[0] = *(const u32x4*)(Pn + (size_t)row * PW + kcol + kc * 8); vreg[0] = *(const u32x4*)(Pn + (size_t)row * PW + vcol + kc * 8); }
;     }
;     f32x16 s0[2], s1[2];
; #pragma unroll
;     for (int t2 = 0; t2 < 2; ++t2) {
; #pragma unroll
;     ...
;     for (int t2 = 0; t2 < 2; ++t2)
; #pragma unroll
;       for (int j = 0; j < 2; ++j) {
;         u32x4 pk0, pk1;
;         pk0.x = pack2(s0[t2][8 * j + 0], s0[t2][8 * j + 1]); pk0.y = pack2(s0[t2][8 * j + 2], s0[t2][8 * j + 3]);
;         pk0.z = pack2(s0[t2][8 * j + 4], s0[t2][8 * j + 5]); pk0.w = pack2(s0[t2][8 * j + 6], s0[t2][8 * j + 7]);
;         pk1.x = pack2(s1[t2][8 * j + 0], s1[t2][8 * j + 1]); pk1.y = pack2(s1[t2][8 * j + 2], s1[t2][8 * j + 3]);
;         pk1.z = pack2(s1[t2][8 * j + 4], s1[t2][8 * j + 5]); pk1.w = pack2(s1[t2][8 * j + 6], s1[t2][8 * j + 7]);
;         const bf16x8 pf0 = __builtin_bit_cast(bf16x8, pk0), pf1 = __builtin_bit_cast(bf16x8, pk1);
; #pragma unroll
;         for (int dt = 0; dt < 2; ++dt) {
;           const int vsw = (((dt * 32 + r) >> 3) & 7) << 3;
;           const bfr* vrow = sV + (dt * 32 + r) * 72;
;           s16x4 lo = *(const s16x4*)(vrow + ((t2 * 32 + 16 * j + 4 * h) ^ vsw));
;           s16x4 hi = *(const s16x4*)(vrow + ((t2 * 32 + 16 * j + 4 * h + 8) ^ vsw));
;           bf16x8 vf = __builtin_shufflevector(lo, hi, 0, 1, 2, 3, 4, 5, 6, 7);
;           acc0[dt] = MFMA32(vf, pf0, acc0[dt]);
;           acc1[dt] = MFMA32(vf, pf1, acc1[dt]);
;         }
;       }
	v_mfma_f32_32x32x16_bf16 v[48:63], v[72:75], v[64:67], v[48:63]
	v_add_f32_e64 v82, v106, v82
	v_add_f32_e64 v83, v107, v83
	v_cvt_pk_bf16_f32 v80, v102, v88
	v_lshl_add_u32 v88, v177, 1, v194
	v_add_f32_e64 v82, v122, v82
	v_add_f32_e64 v83, v123, v83
	v_pk_mul_f32 v[18:19], v[18:19], v[160:161] op_sel_hi:[1,0]
	v_pk_add_f32 v[82:83], v[222:223], v[82:83]
	v_pk_mul_f32 v[16:17], v[16:17], v[160:161] op_sel_hi:[1,0]
	v_pk_add_f32 v[82:83], v[92:93], v[82:83]
	v_mfma_f32_32x32x16_bf16 v[32:47], v[72:75], v[68:71], v[32:47]
	v_add_f32_e64 v82, v108, v82
	v_add_f32_e64 v83, v109, v83
	v_cvt_pk_bf16_f32 v81, v120, v90
	v_lshl_add_u32 v102, v176, 1, v194
	v_add_f32_e64 v82, v124, v82
	v_add_f32_e64 v83, v125, v83
	v_lshl_add_u32 v113, v175, 1, v195
	v_pk_add_f32 v[82:83], v[224:225], v[82:83]
	v_lshl_add_u32 v114, v174, 1, v195
	v_pk_add_f32 v[82:83], v[94:95], v[82:83]
	s_waitcnt lgkmcnt(0)
	v_mfma_f32_32x32x16_bf16 v[16:31], v[76:79], v[64:67], v[16:31]
	v_add_f32_e64 v84, v110, v82
	v_add_f32_e64 v85, v111, v83
	v_cvt_pk_bf16_f32 v82, v122, v92
	v_cvt_pk_bf16_f32 v83, v124, v94
	v_cvt_pk_bf16_f32 v64, v103, v89
	v_cvt_pk_bf16_f32 v65, v121, v91
	v_cvt_pk_bf16_f32 v66, v123, v93
	v_cvt_pk_bf16_f32 v67, v125, v95
	v_mfma_f32_32x32x16_bf16 v[0:15], v[76:79], v[68:71], v[0:15]
	ds_read_b64 v[68:69], v88 offset:9216
	ds_read_b64 v[70:71], v102 offset:9216
	v_lshl_add_u32 v115, v173, 1, v194
	v_lshl_add_u32 v116, v172, 1, v195
	v_lshl_add_u32 v117, v171, 1, v195
	v_lshl_add_u32 v120, v169, 1, v194
	v_lshl_add_u32 v192, v170, 1, v194
	v_lshl_add_u32 v193, v168, 1, v195
	s_waitcnt lgkmcnt(0)
	v_mfma_f32_32x32x16_bf16 v[48:63], v[68:71], v[80:83], v[48:63]
	v_lshl_add_u32 v194, v167, 1, v195
	v_fma_f32 v156, v156, v160, v84
	v_fma_f32 v157, v157, v161, v85
	v_mfma_f32_32x32x16_bf16 v[32:47], v[68:71], v[64:67], v[32:47]
	ds_read_b64 v[68:69], v113 offset:9216
	ds_read_b64 v[70:71], v114 offset:9216
	s_waitcnt lgkmcnt(0)
	v_mfma_f32_32x32x16_bf16 v[16:31], v[68:71], v[80:83], v[16:31]
	v_mfma_f32_32x32x16_bf16 v[0:15], v[68:71], v[64:67], v[0:15]
	v_cvt_pk_bf16_f32 v64, v212, v96
	v_cvt_pk_bf16_f32 v65, v214, v98
	v_cvt_pk_bf16_f32 v66, v216, v100
	v_cvt_pk_bf16_f32 v67, v218, v86
	v_cvt_pk_bf16_f32 v68, v213, v97
	v_cvt_pk_bf16_f32 v69, v215, v99
	v_cvt_pk_bf16_f32 v70, v217, v101
	v_cvt_pk_bf16_f32 v71, v219, v87
	ds_read_b64 v[72:73], v112 offset:9280
	ds_read_b64 v[74:75], v115 offset:9216
	s_waitcnt lgkmcnt(0)
	v_mfma_f32_32x32x16_bf16 v[48:63], v[72:75], v[64:67], v[48:63]
	v_mfma_f32_32x32x16_bf16 v[32:47], v[72:75], v[68:71], v[32:47]
	ds_read_b64 v[72:73], v116 offset:9216
	ds_read_b64 v[74:75], v117 offset:9216
	s_waitcnt lgkmcnt(0)
	v_mfma_f32_32x32x16_bf16 v[16:31], v[72:75], v[64:67], v[16:31]
	v_cvt_pk_bf16_f32 v64, v118, v104
	v_cvt_pk_bf16_f32 v65, v220, v106
	v_cvt_pk_bf16_f32 v66, v222, v108
	v_cvt_pk_bf16_f32 v67, v224, v110
	v_mfma_f32_32x32x16_bf16 v[0:15], v[72:75], v[68:71], v[0:15]
	v_cvt_pk_bf16_f32 v68, v119, v105
	v_cvt_pk_bf16_f32 v69, v221, v107
	v_cvt_pk_bf16_f32 v70, v223, v109
	v_cvt_pk_bf16_f32 v71, v225, v111
	ds_read_b64 v[72:73], v120 offset:9216
	ds_read_b64 v[74:75], v192 offset:9216
	s_waitcnt lgkmcnt(0)
	v_mfma_f32_32x32x16_bf16 v[48:63], v[72:75], v[64:67], v[48:63]
	v_mfma_f32_32x32x16_bf16 v[32:47], v[72:75], v[68:71], v[32:47]
	ds_read_b64 v[72:73], v193 offset:9216
	ds_read_b64 v[74:75], v194 offset:9216
	s_waitcnt lgkmcnt(0)
	v_mfma_f32_32x32x16_bf16 v[16:31], v[72:75], v[64:67], v[16:31]
	v_mfma_f32_32x32x16_bf16 v[0:15], v[72:75], v[68:71], v[0:15]
	s_cbranch_scc1 .LBB0_421
	v_add3_u32 v64, 0, v206, v152
	s_waitcnt vmcnt(1)
	ds_write_b128 v64, v[148:151] offset:18432
	v_add3_u32 v64, 0, v207, v208
	v_add3_u32 v65, 0, v208, v207
	s_waitcnt vmcnt(0)
	ds_write_b16 v64, v144 offset:27648
	ds_write_b16_d16_hi v65, v144 offset:27792
	ds_write_b16 v64, v145 offset:27936
	ds_write_b16_d16_hi v65, v145 offset:28080
	ds_write_b16 v64, v146 offset:28224
	ds_write_b16_d16_hi v65, v146 offset:28368
	ds_write_b16 v64, v147 offset:28512
	ds_write_b16_d16_hi v65, v147 offset:28656
	v_add_u32_e32 v144, 0, v205
	v_add_u32_e32 v102, v144, v204
	s_waitcnt lgkmcnt(0)
	s_barrier
	ds_read_b128 v[64:67], v102 offset:18432
	ds_read_b128 v[96:99], v102 offset:18464
	s_waitcnt lgkmcnt(1)
	v_mfma_f32_32x32x16_bf16 v[64:79], v[64:67], v[140:143], 0
	ds_read_b128 v[80:83], v102 offset:18496
	v_readlane_b32 s10, v203, 16
	v_readlane_b32 s11, v203, 48
	v_add_u32_e32 v145, 0x1200, v144
	v_mov_b32_e32 v100, s10
	v_mov_b32_e32 v101, s11
	v_pk_add_f32 v[100:101], s[8:9], v[100:101]
	s_mov_b32 s10, 0x3fb8aa3b
	v_add_f32_e32 v146, v100, v101
	v_mul_f32_e32 v104, 0x3fb8aa3b, v146
	v_fma_f32 v105, v146, s10, -v104
	v_rndne_f32_e32 v106, v104
	s_waitcnt lgkmcnt(1)
	v_mfma_f32_32x32x16_bf16 v[64:79], v[96:99], v[132:135], v[64:79]
	v_fmac_f32_e32 v105, 0x32a5705f, v146
	v_sub_f32_e32 v96, v104, v106
	v_add_u32_e32 v147, v145, v204
	v_add_f32_e32 v104, v96, v105
	ds_read_b128 v[96:99], v147 offset:18432
	ds_read_b128 v[100:103], v102 offset:18528
	ds_read_b128 v[112:115], v147 offset:18496
	s_waitcnt lgkmcnt(3)
	v_mfma_f32_32x32x16_bf16 v[80:95], v[80:83], v[136:139], 0
	v_readlane_b32 s8, v202, 16
	v_readlane_b32 s9, v202, 48
	s_mov_b32 s11, 0xc2ce8ed0
	v_mov_b32_e32 v116, s8
	v_mov_b32_e32 v117, s9
	v_pk_add_f32 v[116:117], s[6:7], v[116:117]
	v_cmp_ngt_f32_e32 vcc, s11, v146
	s_waitcnt lgkmcnt(1)
	v_mfma_f32_32x32x16_bf16 v[80:95], v[100:103], v[128:131], v[80:95]
	v_exp_f32_e32 v100, v104
	v_cvt_i32_f32_e32 v101, v106
	v_add_f32_e32 v149, v116, v117
	v_mul_f32_e32 v150, 0x3fb8aa3b, v149
	v_rndne_f32_e32 v151, v150
	v_ldexp_f32 v148, v100, v101
	s_mov_b32 s6, 0x42b17218
	s_waitcnt lgkmcnt(0)
; #define MFMA32(a, b, c) __builtin_amdgcn_mfma_f32_32x32x16_bf16((a), (b), (c), 0, 0, 0)
; DI void attn_pass_da(const bfr* __restrict__ P, int b, int tq_wave, int qcol, int kcol, int vcol, int key0, int nkt, char* smem, f32x16 (&o0)[2], f32x16 (&o1)[2]) {
;     ...
;     for (int t2 = 0; t2 < 2; ++t2) {
; #pragma unroll
;       for (int i = 0; i < 16; ++i) { s0[t2][i] = 0.f; s1[t2][i] = 0.f; }
; #pragma unroll
;       for (int ks = 0; ks < 2; ++ks) {
;         bf16x8 a0 = *(const bf16x8*)(sK + (t2 * 32 + r) * KP + ks * 16 + h * 8);
;         bf16x8 a1 = *(const bf16x8*)(sK + (t2 * 32 + r) * KP + 32 + ks * 16 + h * 8);
;         s0[t2] = MFMA32(a0, qf[ks], s0[t2]);
;         s1[t2] = MFMA32(a1, qf[2 + ks], s1[t2]);
;       }
;     }
;     float mx0 = s0[0][0], mx1 = s1[0][0];
; #pragma unroll
;     for (int i = 0; i < 16; ++i) { mx0 = fmaxf(mx0, fmaxf(s0[0][i], s0[1][i])); mx1 = fmaxf(mx1, fmaxf(s1[0][i], s1[1][i])); }
;     mx0 = fmaxf(mx0, __shfl_xor(mx0, 32)); mx1 = fmaxf(mx1, __shfl_xor(mx1, 32));
	v_mfma_f32_32x32x16_bf16 v[112:127], v[112:115], v[136:139], 0
	v_fma_f32 v136, v149, s10, -v150
	v_fmac_f32_e32 v136, 0x32a5705f, v149
	v_sub_f32_e32 v137, v150, v151
	v_add_f32_e32 v136, v137, v136
	v_exp_f32_e32 v150, v136
	ds_read_b128 v[136:139], v147 offset:18528
	v_readlane_b32 s8, v253, 28
	v_mfma_f32_32x32x16_bf16 v[96:111], v[96:99], v[140:143], 0
	ds_read_b128 v[140:143], v147 offset:18464
	v_readlane_b32 s9, v253, 29
	s_waitcnt lgkmcnt(0)
	v_mfma_f32_32x32x16_bf16 v[96:111], v[140:143], v[132:135], v[96:111]
	v_max_f32_e32 v134, v82, v82
	v_max_f32_e32 v135, v67, v67
	v_cvt_i32_f32_e32 v132, v151
	v_cndmask_b32_e32 v133, 0, v148, vcc
	v_cmp_nlt_f32_e32 vcc, s6, v146
	v_ldexp_f32 v132, v150, v132
	v_mfma_f32_32x32x16_bf16 v[112:127], v[136:139], v[128:131], v[112:127]
	s_nop 4
	v_max_f32_e32 v128, v97, v97
	v_max_f32_e32 v129, v65, v65
	v_max_f32_e32 v128, v129, v128
	v_max_f32_e32 v130, v81, v81
	v_max_f32_e32 v131, v66, v66
	v_max3_f32 v128, v64, v96, v128
	v_cndmask_b32_e32 v133, v201, v133, vcc
	v_max_f32_e32 v129, v113, v113
	v_max_f32_e32 v129, v130, v129
	v_max_f32_e32 v130, v98, v98
	v_max_f32_e32 v130, v131, v130
	v_max_f32_e32 v131, v114, v114
	v_max_f32_e32 v131, v134, v131
	v_max_f32_e32 v134, v99, v99
	v_max_f32_e32 v134, v135, v134
	v_max3_f32 v128, v128, v130, v134
	v_max_f32_e32 v130, v115, v115
	v_max_f32_e32 v134, v83, v83
	v_max3_f32 v129, v80, v112, v129
	v_max_f32_e32 v130, v134, v130
	v_max3_f32 v129, v129, v131, v130
	v_max_f32_e32 v130, v100, v100
	v_max_f32_e32 v131, v68, v68
	v_max_f32_e32 v130, v131, v130
	v_max_f32_e32 v131, v116, v116
	v_max_f32_e32 v134, v84, v84
	v_max_f32_e32 v131, v134, v131
	v_max_f32_e32 v134, v101, v101
	v_max_f32_e32 v135, v69, v69
	v_max_f32_e32 v134, v135, v134
	v_max3_f32 v128, v128, v130, v134
	v_max_f32_e32 v130, v117, v117
	v_max_f32_e32 v134, v85, v85
	v_max_f32_e32 v130, v134, v130
	v_max3_f32 v129, v129, v131, v130
	v_max_f32_e32 v130, v102, v102
	v_max_f32_e32 v131, v70, v70
	v_max_f32_e32 v130, v131, v130
	v_max_f32_e32 v131, v118, v118
	v_max_f32_e32 v134, v86, v86
	v_max_f32_e32 v131, v134, v131
	v_max_f32_e32 v134, v103, v103
	v_max_f32_e32 v135, v71, v71
	v_max_f32_e32 v134, v135, v134
	v_max3_f32 v128, v128, v130, v134
	v_max_f32_e32 v130, v119, v119
	v_max_f32_e32 v134, v87, v87
	v_max_f32_e32 v130, v134, v130
	v_max3_f32 v129, v129, v131, v130
	v_max_f32_e32 v130, v104, v104
	v_max_f32_e32 v131, v72, v72
	v_max_f32_e32 v130, v131, v130
	v_max_f32_e32 v131, v120, v120
	v_max_f32_e32 v134, v88, v88
	v_max_f32_e32 v131, v134, v131
	v_max_f32_e32 v134, v105, v105
	v_max_f32_e32 v135, v73, v73
	v_max_f32_e32 v134, v135, v134
	v_max3_f32 v128, v128, v130, v134
	v_max_f32_e32 v130, v121, v121
	v_max_f32_e32 v134, v89, v89
	v_max_f32_e32 v130, v134, v130
	v_max3_f32 v129, v129, v131, v130
	v_max_f32_e32 v130, v106, v106
	v_max_f32_e32 v131, v74, v74
	v_max_f32_e32 v130, v131, v130
	v_max_f32_e32 v131, v122, v122
	v_max_f32_e32 v134, v90, v90
	v_max_f32_e32 v131, v134, v131
	v_max_f32_e32 v134, v107, v107
	v_max_f32_e32 v135, v75, v75
	v_max_f32_e32 v134, v135, v134
	v_max3_f32 v128, v128, v130, v134
	v_max_f32_e32 v130, v123, v123
	v_max_f32_e32 v134, v91, v91
	v_max_f32_e32 v130, v134, v130
	v_max3_f32 v129, v129, v131, v130
	v_max_f32_e32 v130, v108, v108
	v_max_f32_e32 v131, v76, v76
	v_max_f32_e32 v130, v131, v130
	v_max_f32_e32 v131, v124, v124
	v_max_f32_e32 v134, v92, v92
	v_max_f32_e32 v131, v134, v131
	v_max_f32_e32 v134, v109, v109
	v_max_f32_e32 v135, v77, v77
	v_max_f32_e32 v134, v135, v134
	v_max3_f32 v128, v128, v130, v134
	v_max_f32_e32 v130, v125, v125
	v_max_f32_e32 v134, v93, v93
	v_max_f32_e32 v130, v134, v130
	v_max3_f32 v129, v129, v131, v130
	v_max_f32_e32 v130, v110, v110
	v_max_f32_e32 v131, v78, v78
	v_max_f32_e32 v130, v131, v130
	v_max_f32_e32 v131, v126, v126
	v_max_f32_e32 v134, v94, v94
	v_max_f32_e32 v131, v134, v131
	v_max_f32_e32 v134, v111, v111
	v_max_f32_e32 v135, v79, v79
	v_max_f32_e32 v134, v135, v134
	v_max3_f32 v128, v128, v130, v134
	v_max_f32_e32 v130, v127, v127
	v_max_f32_e32 v134, v95, v95
	v_max_f32_e32 v130, v134, v130
	v_max3_f32 v130, v129, v131, v130
	ds_bpermute_b32 v131, v166, v128
	ds_bpermute_b32 v134, v166, v130
	v_cmp_ngt_f32_e32 vcc, s11, v149
	s_waitcnt lgkmcnt(0)
; DI void attn_pass_da(const bfr* __restrict__ P, int b, int tq_wave, int qcol, int kcol, int vcol, int key0, int nkt, char* smem, f32x16 (&o0)[2], f32x16 (&o1)[2]) {
;     ...
;     const float mn0 = fmaxf(m0, mx0), mn1 = fmaxf(m1, mx1);
;     const float al0 = __builtin_amdgcn_exp2f(m0 - mn0), al1 = __builtin_amdgcn_exp2f(m1 - mn1);
;     m0 = mn0; m1 = mn1;
;     float ps0 = 0.f, ps1 = 0.f;
; #pragma unroll
;     for (int i = 0; i < 16; ++i) {
;       s0[0][i] = __builtin_amdgcn_exp2f(s0[0][i] - mn0); ps0 += s0[0][i];
;       s0[1][i] = __builtin_amdgcn_exp2f(s0[1][i] - mn0); ps0 += s0[1][i];
;       s1[0][i] = __builtin_amdgcn_exp2f(s1[0][i] - mn1); ps1 += s1[0][i];
;       s1[1][i] = __builtin_amdgcn_exp2f(s1[1][i] - mn1); ps1 += s1[1][i];
;     }
;     l0 = l0 * al0 + ps0; l1 = l1 * al1 + ps1;
; #pragma unroll
;     for (int i = 0; i < 16; ++i) { acc0[0][i] *= al0; acc0[1][i] *= al0; acc1[0][i] *= al1; acc1[1][i] *= al1; }
	v_max3_f32 v150, v210, v130, v134
	v_cndmask_b32_e32 v132, 0, v132, vcc
	v_cmp_nlt_f32_e32 vcc, s6, v149
	v_max3_f32 v149, v209, v128, v131
	v_sub_f32_e32 v64, v64, v149
	v_exp_f32_e32 v148, v64
	v_sub_f32_e32 v64, v96, v149
	v_exp_f32_e32 v131, v64
	v_sub_f32_e32 v64, v80, v150
	v_exp_f32_e32 v151, v64
	v_sub_f32_e32 v64, v112, v150
	v_exp_f32_e32 v96, v64
	v_sub_f32_e32 v64, v65, v149
	v_exp_f32_e32 v152, v64
	v_sub_f32_e32 v64, v97, v149
	v_exp_f32_e32 v112, v64
	v_sub_f32_e32 v64, v81, v150
	v_exp_f32_e32 v158, v64
	v_sub_f32_e32 v64, v113, v150
	v_exp_f32_e32 v97, v64
	v_sub_f32_e32 v64, v66, v149
	v_exp_f32_e32 v143, v64
	v_sub_f32_e32 v64, v98, v149
	v_exp_f32_e32 v113, v64
	v_sub_f32_e32 v64, v82, v150
	v_exp_f32_e32 v146, v64
	v_sub_f32_e32 v64, v114, v150
	v_exp_f32_e32 v98, v64
	v_sub_f32_e32 v64, v67, v149
	v_exp_f32_e32 v147, v64
	v_sub_f32_e32 v64, v99, v149
	v_exp_f32_e32 v114, v64
	v_sub_f32_e32 v64, v83, v150
	v_exp_f32_e32 v138, v64
	v_sub_f32_e32 v64, v115, v150
	v_exp_f32_e32 v99, v64
	v_sub_f32_e32 v64, v68, v149
	v_exp_f32_e32 v139, v64
	v_sub_f32_e32 v64, v100, v149
	v_exp_f32_e32 v115, v64
	v_sub_f32_e32 v64, v84, v150
	v_exp_f32_e32 v140, v64
	v_sub_f32_e32 v64, v116, v150
	v_exp_f32_e32 v100, v64
	v_sub_f32_e32 v64, v69, v149
	v_exp_f32_e32 v141, v64
	v_sub_f32_e32 v64, v101, v149
	v_exp_f32_e32 v116, v64
	v_sub_f32_e32 v64, v85, v150
	v_exp_f32_e32 v142, v64
	v_sub_f32_e32 v64, v117, v150
	v_exp_f32_e32 v101, v64
	v_sub_f32_e32 v64, v70, v149
	v_exp_f32_e32 v134, v64
	v_sub_f32_e32 v64, v102, v149
	v_cndmask_b32_e32 v129, v201, v132, vcc
	v_exp_f32_e32 v132, v64
	v_sub_f32_e32 v64, v86, v150
	v_exp_f32_e32 v135, v64
	v_sub_f32_e32 v64, v118, v150
	v_exp_f32_e32 v117, v64
	v_sub_f32_e32 v64, v71, v149
	v_exp_f32_e32 v136, v64
	v_sub_f32_e32 v64, v103, v149
	v_sub_f32_e32 v129, v133, v129
	v_exp_f32_e32 v133, v64
	v_sub_f32_e32 v64, v87, v150
	v_exp_f32_e32 v137, v64
	v_sub_f32_e32 v64, v119, v150
	v_exp_f32_e32 v102, v64
	v_sub_f32_e32 v64, v72, v149
	v_exp_f32_e32 v103, v64
	v_sub_f32_e32 v64, v104, v149
	v_exp_f32_e32 v71, v64
	v_sub_f32_e32 v64, v88, v150
	v_exp_f32_e32 v104, v64
	v_sub_f32_e32 v64, v120, v150
	v_exp_f32_e32 v70, v64
	v_sub_f32_e32 v64, v73, v149
	v_exp_f32_e32 v118, v64
	v_sub_f32_e32 v64, v105, v149
	v_exp_f32_e32 v73, v64
	v_sub_f32_e32 v64, v89, v150
	v_exp_f32_e32 v105, v64
	v_sub_f32_e32 v64, v121, v150
	v_exp_f32_e32 v72, v64
	v_sub_f32_e32 v64, v74, v149
	v_exp_f32_e32 v119, v64
	v_sub_f32_e32 v64, v106, v149
	v_exp_f32_e32 v81, v64
	v_sub_f32_e32 v64, v90, v150
	v_exp_f32_e32 v89, v64
	v_sub_f32_e32 v64, v122, v150
	v_exp_f32_e32 v80, v64
	v_sub_f32_e32 v64, v75, v149
	v_exp_f32_e32 v90, v64
	v_sub_f32_e32 v64, v107, v149
	v_exp_f32_e32 v87, v64
	v_sub_f32_e32 v64, v91, v150
	v_exp_f32_e32 v91, v64
	v_sub_f32_e32 v64, v123, v150
	v_exp_f32_e32 v86, v64
	v_sub_f32_e32 v64, v76, v149
	v_exp_f32_e32 v74, v64
	v_sub_f32_e32 v64, v108, v149
	v_exp_f32_e32 v75, v64
	v_sub_f32_e32 v64, v92, v150
	v_exp_f32_e32 v76, v64
	v_sub_f32_e32 v64, v124, v150
	v_exp_f32_e32 v82, v64
	v_sub_f32_e32 v64, v77, v149
	v_exp_f32_e32 v77, v64
	v_sub_f32_e32 v64, v109, v149
	v_exp_f32_e32 v83, v64
	v_sub_f32_e32 v64, v93, v150
	v_exp_f32_e32 v84, v64
	v_sub_f32_e32 v64, v125, v150
	v_exp_f32_e32 v85, v64
	v_sub_f32_e32 v64, v78, v149
	v_exp_f32_e32 v78, v64
	v_sub_f32_e32 v64, v110, v149
	v_exp_f32_e32 v88, v64
	v_sub_f32_e32 v64, v94, v150
	v_exp_f32_e32 v66, v64
	v_sub_f32_e32 v64, v126, v150
	v_exp_f32_e32 v67, v64
	v_sub_f32_e32 v64, v79, v149
	v_exp_f32_e32 v68, v64
	v_sub_f32_e32 v64, v111, v149
	v_lshl_add_u32 v79, v181, 1, v144
	v_lshl_add_u32 v110, v180, 1, v144
	v_lshl_add_u32 v124, v179, 1, v145
	v_lshl_add_u32 v126, v178, 1, v145
	v_exp_f32_e32 v69, v64
	v_sub_f32_e32 v64, v95, v150
	v_sub_f32_e32 v65, v127, v150
	v_cvt_pk_bf16_f32 v92, v148, v152
	v_cvt_pk_bf16_f32 v93, v143, v147
	v_cvt_pk_bf16_f32 v94, v139, v141
	v_cvt_pk_bf16_f32 v95, v134, v136
	v_cvt_pk_bf16_f32 v106, v151, v158
	v_cvt_pk_bf16_f32 v107, v146, v138
	v_cvt_pk_bf16_f32 v108, v140, v142
	v_cvt_pk_bf16_f32 v109, v135, v137
	ds_read_b64 v[120:121], v79 offset:27648
	ds_read_b64 v[122:123], v110 offset:27648
	ds_read_b64 v[124:125], v124 offset:27648
	ds_read_b64 v[126:127], v126 offset:27648
	v_sub_f32_e32 v128, v209, v149
	v_exp_f32_e32 v130, v128
	v_sub_f32_e32 v128, v210, v150
	v_add_f32_e32 v111, 0, v151
	v_exp_f32_e32 v128, v128
	v_add_f32_e32 v110, 0, v148
	v_add_f32_e32 v111, v96, v111
	v_add_f32_e32 v110, v131, v110
	v_add_f32_e32 v111, v158, v111
	v_add_f32_e32 v110, v152, v110
	v_add_f32_e32 v111, v97, v111
	v_add_f32_e32 v110, v112, v110
	v_add_f32_e32 v111, v146, v111
	v_pk_mul_f32 v[46:47], v[46:47], v[128:129] op_sel_hi:[1,0]
	v_pk_mul_f32 v[44:45], v[44:45], v[128:129] op_sel_hi:[1,0]
	v_pk_mul_f32 v[42:43], v[42:43], v[128:129] op_sel_hi:[1,0]
	v_pk_mul_f32 v[40:41], v[40:41], v[128:129] op_sel_hi:[1,0]
	v_pk_mul_f32 v[38:39], v[38:39], v[128:129] op_sel_hi:[1,0]
	v_pk_mul_f32 v[36:37], v[36:37], v[128:129] op_sel_hi:[1,0]
	v_pk_mul_f32 v[34:35], v[34:35], v[128:129] op_sel_hi:[1,0]
	v_pk_mul_f32 v[32:33], v[32:33], v[128:129] op_sel_hi:[1,0]
	v_pk_mul_f32 v[14:15], v[14:15], v[128:129] op_sel_hi:[1,0]
	v_pk_mul_f32 v[12:13], v[12:13], v[128:129] op_sel_hi:[1,0]
	v_pk_mul_f32 v[10:11], v[10:11], v[128:129] op_sel_hi:[1,0]
	v_pk_mul_f32 v[8:9], v[8:9], v[128:129] op_sel_hi:[1,0]
	v_pk_mul_f32 v[6:7], v[6:7], v[128:129] op_sel_hi:[1,0]
	v_pk_mul_f32 v[4:5], v[4:5], v[128:129] op_sel_hi:[1,0]
	v_pk_mul_f32 v[2:3], v[2:3], v[128:129] op_sel_hi:[1,0]
	v_pk_mul_f32 v[0:1], v[0:1], v[128:129] op_sel_hi:[1,0]
	v_add_f32_e32 v110, v143, v110
	v_add_f32_e32 v111, v98, v111
	s_waitcnt lgkmcnt(2)
; #define MFMA32(a, b, c) __builtin_amdgcn_mfma_f32_32x32x16_bf16((a), (b), (c), 0, 0, 0)
; DI unsigned pack2(float a, float b) { unsigned r; asm volatile("v_cvt_pk_bf16_f32 %0, %1, %2" : "=v"(r) : "v"(a), "v"(b)); return r; }
; DI void attn_pass_da(const bfr* __restrict__ P, int b, int tq_wave, int qcol, int kcol, int vcol, int key0, int nkt, char* smem, f32x16 (&o0)[2], f32x16 (&o1)[2]) {
;     ...
;     float ps0 = 0.f, ps1 = 0.f;
; #pragma unroll
;     for (int i = 0; i < 16; ++i) {
;       s0[0][i] = __builtin_amdgcn_exp2f(s0[0][i] - mn0); ps0 += s0[0][i];
;       s0[1][i] = __builtin_amdgcn_exp2f(s0[1][i] - mn0); ps0 += s0[1][i];
;       s1[0][i] = __builtin_amdgcn_exp2f(s1[0][i] - mn1); ps1 += s1[0][i];
;       s1[1][i] = __builtin_amdgcn_exp2f(s1[1][i] - mn1); ps1 += s1[1][i];
;     }
;     l0 = l0 * al0 + ps0; l1 = l1 * al1 + ps1;
; #pragma unroll
;     for (int i = 0; i < 16; ++i) { acc0[0][i] *= al0; acc0[1][i] *= al0; acc1[0][i] *= al1; acc1[1][i] *= al1; }
; #pragma unroll
;     for (int t2 = 0; t2 < 2; ++t2)
; #pragma unroll
;       for (int j = 0; j < 2; ++j) {
;         u32x4 pk0, pk1;
;         pk0.x = pack2(s0[t2][8 * j + 0], s0[t2][8 * j + 1]); pk0.y = pack2(s0[t2][8 * j + 2], s0[t2][8 * j + 3]);
;         pk0.z = pack2(s0[t2][8 * j + 4], s0[t2][8 * j + 5]); pk0.w = pack2(s0[t2][8 * j + 6], s0[t2][8 * j + 7]);
;         pk1.x = pack2(s1[t2][8 * j + 0], s1[t2][8 * j + 1]); pk1.y = pack2(s1[t2][8 * j + 2], s1[t2][8 * j + 3]);
;         pk1.z = pack2(s1[t2][8 * j + 4], s1[t2][8 * j + 5]); pk1.w = pack2(s1[t2][8 * j + 6], s1[t2][8 * j + 7]);
;         const bf16x8 pf0 = __builtin_bit_cast(bf16x8, pk0), pf1 = __builtin_bit_cast(bf16x8, pk1);
; #pragma unroll
;         for (int dt = 0; dt < 2; ++dt) {
;           const int vsw = (((dt * 32 + r) >> 3) & 7) << 3;
;           const bfr* vrow = sV + (dt * 32 + r) * 72;
;           s16x4 lo = *(const s16x4*)(vrow + ((t2 * 32 + 16 * j + 4 * h) ^ vsw));
;           s16x4 hi = *(const s16x4*)(vrow + ((t2 * 32 + 16 * j + 4 * h + 8) ^ vsw));
;           bf16x8 vf = __builtin_shufflevector(lo, hi, 0, 1, 2, 3, 4, 5, 6, 7);
;           acc0[dt] = MFMA32(vf, pf0, acc0[dt]);
;           acc1[dt] = MFMA32(vf, pf1, acc1[dt]);
;         }
;       }
	v_mfma_f32_32x32x16_bf16 v[32:47], v[120:123], v[106:109], v[32:47]
	v_add_f32_e32 v110, v113, v110
	v_add_f32_e32 v110, v147, v110
	v_add_f32_e32 v110, v114, v110
	v_mul_f32_e64 v62, v62, v130
	v_mul_f32_e64 v63, v63, v130
	v_pk_mul_f32 v[60:61], v[60:61], v[130:131] op_sel_hi:[1,0]
	v_pk_mul_f32 v[58:59], v[58:59], v[130:131] op_sel_hi:[1,0]
	v_pk_mul_f32 v[56:57], v[56:57], v[130:131] op_sel_hi:[1,0]
	s_waitcnt lgkmcnt(0)
	v_mfma_f32_32x32x16_bf16 v[0:15], v[124:127], v[106:109], v[0:15]
	v_add_f32_e32 v106, v138, v111
	v_add_f32_e32 v106, v99, v106
	v_add_f32_e32 v106, v140, v106
	v_add_f32_e32 v107, v139, v110
	v_add_f32_e32 v106, v100, v106
	v_add_f32_e32 v107, v115, v107
	v_add_f32_e32 v106, v142, v106
	v_pk_mul_f32 v[54:55], v[54:55], v[130:131] op_sel_hi:[1,0]
	v_pk_mul_f32 v[52:53], v[52:53], v[130:131] op_sel_hi:[1,0]
	v_pk_mul_f32 v[50:51], v[50:51], v[130:131] op_sel_hi:[1,0]
	v_pk_mul_f32 v[48:49], v[48:49], v[130:131] op_sel_hi:[1,0]
	v_pk_mul_f32 v[30:31], v[30:31], v[130:131] op_sel_hi:[1,0]
	v_pk_mul_f32 v[28:29], v[28:29], v[130:131] op_sel_hi:[1,0]
	v_pk_mul_f32 v[26:27], v[26:27], v[130:131] op_sel_hi:[1,0]
	v_pk_mul_f32 v[24:25], v[24:25], v[130:131] op_sel_hi:[1,0]
	v_pk_mul_f32 v[22:23], v[22:23], v[130:131] op_sel_hi:[1,0]
	v_pk_mul_f32 v[20:21], v[20:21], v[130:131] op_sel_hi:[1,0]
	v_pk_mul_f32 v[18:19], v[18:19], v[130:131] op_sel_hi:[1,0]
	v_pk_mul_f32 v[16:17], v[16:17], v[130:131] op_sel_hi:[1,0]
	v_lshl_add_u32 v143, v177, 1, v144
	v_add_f32_e32 v107, v141, v107
	v_add_f32_e32 v111, v101, v106
	v_lshl_add_u32 v106, v175, 1, v145
	v_lshl_add_u32 v108, v174, 1, v145
	v_exp_f32_e32 v64, v64
	v_mfma_f32_32x32x16_bf16 v[48:63], v[120:123], v[92:95], v[48:63]
	v_add_f32_e32 v110, v116, v107
	v_add_f32_e32 v110, v134, v110
	v_add_f32_e32 v110, v132, v110
	v_add_f32_e32 v110, v136, v110
	v_add_f32_e32 v111, v135, v111
	v_add_f32_e32 v111, v117, v111
	v_exp_f32_e32 v65, v65
	v_mfma_f32_32x32x16_bf16 v[16:31], v[124:127], v[92:95], v[16:31]
	v_cvt_pk_bf16_f32 v92, v103, v118
	v_cvt_pk_bf16_f32 v93, v119, v90
	v_cvt_pk_bf16_f32 v94, v74, v77
	v_cvt_pk_bf16_f32 v95, v78, v68
	v_cvt_pk_bf16_f32 v120, v104, v105
	v_cvt_pk_bf16_f32 v121, v89, v91
	v_cvt_pk_bf16_f32 v122, v76, v84
	v_cvt_pk_bf16_f32 v123, v66, v64
	ds_read_b64 v[146:147], v143 offset:27648
	ds_read_b64 v[106:107], v106 offset:27648
	ds_read_b64 v[108:109], v108 offset:27648
	v_lshl_add_u32 v143, v176, 1, v144
	ds_read_b64 v[148:149], v143 offset:27648
	v_add_f32_e32 v124, v133, v110
	s_waitcnt lgkmcnt(0)
	v_mfma_f32_32x32x16_bf16 v[48:63], v[146:149], v[92:95], v[48:63]
	v_add_f32_e32 v125, v137, v111
	v_lshlrev_b32_e32 v152, 1, v154
	v_mfma_f32_32x32x16_bf16 v[16:31], v[106:109], v[92:95], v[16:31]
	v_cvt_pk_bf16_f32 v92, v131, v112
	v_cvt_pk_bf16_f32 v93, v113, v114
	v_cvt_pk_bf16_f32 v94, v115, v116
	v_cvt_pk_bf16_f32 v95, v132, v133
	v_cvt_pk_bf16_f32 v96, v96, v97
	v_cvt_pk_bf16_f32 v97, v98, v99
	v_cvt_pk_bf16_f32 v98, v100, v101
	v_add_f32_e32 v100, v103, v124
	v_add_f32_e32 v100, v71, v100
	v_cvt_pk_bf16_f32 v99, v117, v102
	ds_read_b64 v[110:111], v79 offset:27712
	v_lshl_add_u32 v79, v173, 1, v144
	v_add_f32_e32 v100, v118, v100
	ds_read_b64 v[112:113], v79 offset:27648
	v_add_f32_e32 v79, v102, v125
	v_add_f32_e32 v100, v73, v100
	v_add_f32_e32 v79, v104, v79
	v_add_f32_e32 v104, v119, v100
	v_lshl_add_u32 v100, v172, 1, v145
	v_lshl_add_u32 v102, v171, 1, v145
	ds_read_b64 v[100:101], v100 offset:27648
	ds_read_b64 v[102:103], v102 offset:27648
	v_add_f32_e32 v79, v70, v79
	v_add_f32_e32 v79, v105, v79
	v_add_f32_e32 v79, v72, v79
	v_add_f32_e32 v104, v81, v104
	v_add_f32_e32 v79, v89, v79
	v_add_f32_e32 v79, v80, v79
	v_add_f32_e32 v89, v90, v104
	v_add_f32_e32 v89, v87, v89
	v_add_f32_e32 v79, v91, v79
	v_add_f32_e32 v79, v86, v79
	v_add_f32_e32 v74, v74, v89
	s_waitcnt lgkmcnt(2)
	v_mfma_f32_32x32x16_bf16 v[48:63], v[110:113], v[92:95], v[48:63]
	v_cvt_pk_bf16_f32 v90, v71, v73
	v_cvt_pk_bf16_f32 v91, v81, v87
	v_add_f32_e32 v74, v75, v74
	v_add_f32_e32 v74, v77, v74
	v_add_f32_e32 v74, v83, v74
	v_add_f32_e32 v74, v78, v74
	v_add_f32_e32 v78, v88, v74
	s_waitcnt lgkmcnt(0)
	v_mfma_f32_32x32x16_bf16 v[16:31], v[100:103], v[92:95], v[16:31]
	v_cvt_pk_bf16_f32 v92, v75, v83
	v_add_f32_e32 v75, v76, v79
	v_add_f32_e32 v75, v82, v75
	v_add_f32_e32 v75, v84, v75
	v_add_f32_e32 v79, v85, v75
	v_add_f32_e32 v66, v66, v79
	v_cvt_pk_bf16_f32 v93, v88, v69
	v_mfma_f32_32x32x16_bf16 v[32:47], v[146:149], v[120:123], v[32:47]
	v_cvt_pk_bf16_f32 v70, v70, v72
	v_cvt_pk_bf16_f32 v71, v80, v86
	v_cvt_pk_bf16_f32 v72, v82, v85
	v_cvt_pk_bf16_f32 v73, v67, v65
	v_add_f32_e32 v66, v67, v66
	v_add_f32_e32 v67, v68, v78
	v_add_f32_e32 v67, v69, v67
	v_mfma_f32_32x32x16_bf16 v[0:15], v[106:109], v[120:123], v[0:15]
	v_fmac_f32_e32 v67, v156, v130
	ds_bpermute_b32 v68, v166, v67
	v_lshl_add_u32 v80, v169, 1, v144
	v_lshl_add_u32 v74, v168, 1, v145
	v_lshl_add_u32 v76, v167, 1, v145
	ds_read_b64 v[104:105], v80 offset:27648
	ds_read_b64 v[74:75], v74 offset:27648
	ds_read_b64 v[76:77], v76 offset:27648
	v_lshl_add_u32 v80, v170, 1, v144
	v_add_f32_e32 v64, v64, v66
	ds_read_b64 v[106:107], v80 offset:27648
	v_add_f32_e32 v65, v65, v64
	v_mfma_f32_32x32x16_bf16 v[32:47], v[110:113], v[96:99], v[32:47]
	v_fmac_f32_e32 v65, v157, v128
	s_waitcnt lgkmcnt(4)
	v_add_f32_e32 v66, v67, v68
	ds_bpermute_b32 v67, v166, v65
	v_div_scale_f32 v68, s[6:7], v66, v66, 1.0
	v_rcp_f32_e32 v69, v68
	v_add_f32_e32 v64, v155, v129
	v_mfma_f32_32x32x16_bf16 v[0:15], v[100:103], v[96:99], v[0:15]
	s_waitcnt lgkmcnt(0)
; DI int oidx(int i) { asm volatile("" : "+s"(i)); return i; }
; DI void attn_pass_da(const bfr* __restrict__ P, int b, int tq_wave, int qcol, int kcol, int vcol, int key0, int nkt, char* smem, f32x16 (&o0)[2], f32x16 (&o1)[2]) {
;     ...
;   l0 += __shfl_xor(l0, 32); l1 += __shfl_xor(l1, 32);
;   const float i0 = 1.f / l0, i1 = 1.f / l1;
; #pragma unroll
;   for (int i = 0; i < 16; ++i) { o0[0][i] = acc0[0][i] * i0; o0[1][i] = acc0[1][i] * i0; o1[0][i] = acc1[0][i] * i1; o1[1][i] = acc1[1][i] * i1; }
; DN void da_item(const Params& p, int l, int b, int hd, int tq0, int key0, int nkt, char* smem) {
;     ...
;   float ss = 0.f;
; #pragma unroll
;   for (int dt = 0; dt < 2; ++dt)
; #pragma unroll
;     for (int i = 0; i < 16; ++i) { float v = o0[dt][i] - lam * o1[dt][i]; o0[dt][i] = v; ss += v * v; }
;   ss += __shfl_xor(ss, 32);
;   float rstd = rsqrtf(ss * (1.f / 64.f) + 1e-6f) * (1.f - lam_init);
;   const float* sg = p.in[oidx(23)] + l * 64;
; #pragma unroll
;   for (int dt = 0; dt < 2; ++dt)
; #pragma unroll
;     for (int i = 0; i < 16; ++i) { int dv = dt * 32 + 8 * (i >> 2) + 4 * h + (i & 3); o0[dt][i] = o0[dt][i] * rstd * sg[dv]; }
	v_add_f32_e32 v65, v65, v67
	v_fma_f32 v67, -v68, v69, 1.0
	v_fmac_f32_e32 v69, v67, v69
	v_div_scale_f32 v67, vcc, 1.0, v66, 1.0
	v_mfma_f32_32x32x16_bf16 v[32:47], v[104:107], v[70:73], v[32:47]
	v_mfma_f32_32x32x16_bf16 v[0:15], v[74:77], v[70:73], v[0:15]
	v_mul_f32_e32 v70, v67, v69
	v_fma_f32 v71, -v68, v70, v67
	v_fmac_f32_e32 v70, v71, v69
	v_fma_f32 v67, -v68, v70, v67
	v_div_scale_f32 v68, s[6:7], v65, v65, 1.0
	v_rcp_f32_e32 v71, v68
	v_div_fmas_f32 v67, v67, v69, v70
	v_div_fixup_f32 v66, v67, v66, 1.0
	v_mfma_f32_32x32x16_bf16 v[48:63], v[104:107], v[90:93], v[48:63]
	v_fma_f32 v67, -v68, v71, 1.0
	v_fmac_f32_e32 v71, v67, v71
	v_div_scale_f32 v67, vcc, 1.0, v65, 1.0
	v_mul_f32_e32 v69, v67, v71
	v_fma_f32 v70, -v68, v69, v67
	v_fmac_f32_e32 v69, v70, v71
	v_fma_f32 v67, -v68, v69, v67
	v_div_fmas_f32 v67, v67, v71, v69
	v_div_fixup_f32 v68, v67, v65, 1.0
	v_mul_f32_e32 v65, v0, v68
	v_mul_f32_e32 v0, v33, v68
	v_mul_f32_e32 v67, v1, v68
	v_mul_f32_e32 v1, v34, v68
	v_mul_f32_e32 v0, v64, v0
	v_mul_f32_e32 v32, v32, v68
	v_mul_f32_e32 v69, v2, v68
	v_mul_f32_e32 v2, v35, v68
	v_mul_f32_e32 v33, v37, v68
	v_mul_f32_e32 v37, v41, v68
	v_mul_f32_e32 v41, v45, v68
	v_fma_f32 v45, v49, v66, -v0
	v_mul_f32_e32 v0, v64, v1
	v_mul_f32_e32 v70, v3, v68
	v_mul_f32_e32 v3, v36, v68
	v_mul_f32_e32 v35, v39, v68
	v_mul_f32_e32 v39, v43, v68
	v_mul_f32_e32 v43, v47, v68
	v_mul_f32_e32 v32, v64, v32
	v_fma_f32 v47, v50, v66, -v0
	v_mul_f32_e32 v0, v64, v2
	v_mul_f32_e32 v36, v40, v68
	v_mul_f32_e32 v40, v44, v68
	v_fma_f32 v44, v48, v66, -v32
	v_fma_f32 v48, v51, v66, -v0
	v_mul_f32_e32 v0, v64, v3
	v_mul_f32_e32 v34, v38, v68
	v_fma_f32 v49, v52, v66, -v0
	v_mul_f32_e32 v0, v64, v33
	s_mov_b32 s6, 23
	v_fma_f32 v50, v53, v66, -v0
	v_mul_f32_e32 v0, v64, v34
	s_ashr_i32 s7, s6, 31
	v_fma_f32 v51, v54, v66, -v0
	v_mul_f32_e32 v0, v64, v35
	s_lshl_b64 s[6:7], s[6:7], 3
	v_fma_f32 v52, v55, v66, -v0
	v_mul_f32_e32 v0, v64, v36
	s_add_u32 s6, s0, s6
	v_mul_f32_e32 v38, v42, v68
	v_fma_f32 v53, v56, v66, -v0
	v_mul_f32_e32 v0, v64, v37
	s_addc_u32 s7, s1, s7
	v_fma_f32 v54, v57, v66, -v0
	v_mul_f32_e32 v0, v64, v38
	s_load_dwordx2 s[6:7], s[6:7], 0x0
	v_mul_f32_e32 v42, v46, v68
	v_mul_f32_e32 v46, v45, v45
	v_fma_f32 v55, v58, v66, -v0
	v_mul_f32_e32 v0, v64, v39
	v_fmac_f32_e32 v46, v44, v44
	v_fma_f32 v56, v59, v66, -v0
	v_mul_f32_e32 v0, v64, v40
	v_fmac_f32_e32 v46, v47, v47
	v_fma_f32 v57, v60, v66, -v0
	v_mul_f32_e32 v0, v64, v41
	v_fmac_f32_e32 v46, v48, v48
	v_fma_f32 v58, v61, v66, -v0
	s_lshl_b64 s[8:9], s[8:9], 2
	v_lshrrev_b32_e32 v0, 3, v164
	v_fmac_f32_e32 v46, v49, v49
	s_waitcnt lgkmcnt(0)
	s_add_u32 s6, s6, s8
	v_and_b32_e32 v59, 4, v0
	v_fmac_f32_e32 v46, v50, v50
	s_addc_u32 s7, s7, s9
	v_lshlrev_b32_e32 v60, 2, v59
	v_mfma_f32_32x32x16_bf16 v[16:31], v[74:77], v[90:93], v[16:31]
	v_fmac_f32_e32 v46, v51, v51
	global_load_dwordx4 v[0:3], v60, s[6:7]
	v_fmac_f32_e32 v46, v52, v52
	v_fmac_f32_e32 v46, v53, v53
	v_mul_f32_e32 v32, v64, v42
	v_fmac_f32_e32 v46, v54, v54
	v_fma_f32 v61, v62, v66, -v32
	v_mul_f32_e32 v32, v64, v43
	v_fmac_f32_e32 v46, v55, v55
	v_fma_f32 v62, v63, v66, -v32
	global_load_dwordx4 v[32:35], v60, s[6:7] offset:32
	v_fmac_f32_e32 v46, v56, v56
	v_fmac_f32_e32 v46, v57, v57
	v_fmac_f32_e32 v46, v58, v58
	v_mul_f32_e32 v36, v64, v65
	v_fmac_f32_e32 v46, v61, v61
	v_fma_f32 v63, v16, v66, -v36
	v_mul_f32_e32 v16, v64, v67
	global_load_dwordx4 v[36:39], v60, s[6:7] offset:64
	v_mul_f32_e32 v4, v4, v68
	v_fmac_f32_e32 v46, v62, v62
	v_fma_f32 v65, v17, v66, -v16
	v_mul_f32_e32 v16, v64, v69
	v_mul_f32_e32 v5, v5, v68
	v_fmac_f32_e32 v46, v63, v63
	v_fma_f32 v67, v18, v66, -v16
	v_mul_f32_e32 v16, v64, v70
	v_mul_f32_e32 v4, v64, v4
	v_fmac_f32_e32 v46, v65, v65
	v_fma_f32 v69, v19, v66, -v16
	v_fma_f32 v70, v20, v66, -v4
	v_mul_f32_e32 v4, v64, v5
	v_fmac_f32_e32 v46, v67, v67
	global_load_dwordx4 v[16:19], v60, s[6:7] offset:96
	v_fma_f32 v71, v21, v66, -v4
	v_pk_mul_f32 v[4:5], v[6:7], v[68:69] op_sel_hi:[1,0]
	v_fmac_f32_e32 v46, v69, v69
	v_pk_mul_f32 v[4:5], v[64:65], v[4:5] op_sel_hi:[0,1]
	v_fmac_f32_e32 v46, v70, v70
	v_pk_fma_f32 v[40:41], v[22:23], v[66:67], v[4:5] op_sel_hi:[1,0,1] neg_lo:[0,0,1] neg_hi:[0,0,1]
	v_pk_mul_f32 v[8:9], v[8:9], v[68:69] op_sel_hi:[1,0]
	v_fmac_f32_e32 v46, v71, v71
	v_pk_mul_f32 v[20:21], v[40:41], v[40:41]
	v_pk_mul_f32 v[8:9], v[64:65], v[8:9] op_sel_hi:[0,1]
	global_load_dwordx4 v[4:7], v60, s[6:7] offset:128
	v_add_f32_e32 v20, v20, v46
	v_pk_fma_f32 v[24:25], v[24:25], v[66:67], v[8:9] op_sel_hi:[1,0,1] neg_lo:[0,0,1] neg_hi:[0,0,1]
	v_add_f32_e32 v20, v21, v20
	v_pk_mul_f32 v[8:9], v[24:25], v[24:25]
	v_pk_mul_f32 v[12:13], v[12:13], v[68:69] op_sel_hi:[1,0]
	v_add_f32_e32 v8, v8, v20
	v_add_f32_e32 v42, v9, v8
	v_pk_mul_f32 v[8:9], v[10:11], v[68:69] op_sel_hi:[1,0]
	global_load_dwordx4 v[20:23], v60, s[6:7] offset:160
	v_pk_mul_f32 v[8:9], v[64:65], v[8:9] op_sel_hi:[0,1]
	v_pk_fma_f32 v[26:27], v[26:27], v[66:67], v[8:9] op_sel_hi:[1,0,1] neg_lo:[0,0,1] neg_hi:[0,0,1]
	v_pk_mul_f32 v[12:13], v[64:65], v[12:13] op_sel_hi:[0,1]
	v_pk_mul_f32 v[8:9], v[26:27], v[26:27]
	v_pk_fma_f32 v[28:29], v[28:29], v[66:67], v[12:13] op_sel_hi:[1,0,1] neg_lo:[0,0,1] neg_hi:[0,0,1]
	v_add_f32_e32 v8, v8, v42
	v_add_f32_e32 v42, v9, v8
	global_load_dwordx4 v[8:11], v60, s[6:7] offset:192
	v_pk_mul_f32 v[12:13], v[28:29], v[28:29]
	s_load_dwordx4 s[8:11], s[0:1], 0x100
	v_add_f32_e32 v12, v12, v42
	v_add_f32_e32 v46, v13, v12
	v_pk_mul_f32 v[42:43], v[14:15], v[68:69] op_sel_hi:[1,0]
	global_load_dwordx4 v[12:15], v60, s[6:7] offset:224
	v_pk_mul_f32 v[42:43], v[64:65], v[42:43] op_sel_hi:[0,1]
	v_pk_fma_f32 v[30:31], v[30:31], v[66:67], v[42:43] op_sel_hi:[1,0,1] neg_lo:[0,0,1] neg_hi:[0,0,1]
	s_mov_b64 s[6:7], 0x2b7c300
	v_pk_mul_f32 v[42:43], v[30:31], v[30:31]
	s_nop 0
	v_add_f32_e32 v42, v42, v46
	v_add_f32_e32 v42, v43, v42
	ds_bpermute_b32 v43, v166, v42
	s_waitcnt lgkmcnt(0)
; DI int oidx(int i) { asm volatile("" : "+s"(i)); return i; }
; DI unsigned pack2(float a, float b) { unsigned r; asm volatile("v_cvt_pk_bf16_f32 %0, %1, %2" : "=v"(r) : "v"(a), "v"(b)); return r; }
; DI void store_o(bfr* O, int m, int colbase, int h, const f32x16 (&o)[2]) {
; #pragma unroll
;   for (int dt = 0; dt < 2; ++dt)
; #pragma unroll
;     for (int g4 = 0; g4 < 4; ++g4) {
;       int dv = dt * 32 + 8 * g4 + 4 * h;
;       uint2 pk; pk.x = pack2(o[dt][4 * g4], o[dt][4 * g4 + 1]); pk.y = pack2(o[dt][4 * g4 + 2], o[dt][4 * g4 + 3]);
;       *(uint2*)(O + (size_t)m * DM + colbase + dv) = pk;
;     }
; }
; DN void da_item(const Params& p, int l, int b, int hd, int tq0, int key0, int nkt, char* smem) {
;     ...
;   ss += __shfl_xor(ss, 32);
;   float rstd = rsqrtf(ss * (1.f / 64.f) + 1e-6f) * (1.f - lam_init);
;   const float* sg = p.in[oidx(23)] + l * 64;
; #pragma unroll
;   for (int dt = 0; dt < 2; ++dt)
; #pragma unroll
;     for (int i = 0; i < 16; ++i) { int dv = dt * 32 + 8 * (i >> 2) + 4 * h + (i & 3); o0[dt][i] = o0[dt][i] * rstd * sg[dv]; }
;   store_o(O, b * TT + tqw + r, 256 + hd * 64, h, o0);
	v_add_f32_e32 v42, v42, v43
	v_fmamk_f32 v42, v42, 0x3c800000, v186
	v_cmp_gt_f32_e32 vcc, s33, v42
	v_mul_f32_e32 v43, 0x4b800000, v42
	s_nop 0
	v_cndmask_b32_e32 v42, v42, v43, vcc
	v_rsq_f32_e32 v42, v42
	s_nop 0
	v_mul_f32_e32 v43, 0x45800000, v42
	v_cndmask_b32_e32 v42, v42, v43, vcc
	v_mul_f32_e32 v42, v162, v42
	v_mul_f32_e32 v43, v44, v42
	s_waitcnt vmcnt(7)
	v_mul_f32_e32 v43, v0, v43
	v_mul_f32_e32 v0, v45, v42
	v_mul_f32_e32 v44, v1, v0
	v_mul_f32_e32 v0, v47, v42
	v_mul_f32_e32 v45, v2, v0
	v_mul_f32_e32 v0, v48, v42
	v_mul_f32_e32 v3, v3, v0
	v_mul_f32_e32 v0, v49, v42
	s_waitcnt vmcnt(6)
	v_mul_f32_e32 v32, v32, v0
	v_mul_f32_e32 v0, v50, v42
	v_mul_f32_e32 v33, v33, v0
	v_mul_f32_e32 v0, v51, v42
	v_mul_f32_e32 v34, v34, v0
	v_mul_f32_e32 v0, v52, v42
	v_mul_f32_e32 v35, v35, v0
	v_mul_f32_e32 v0, v53, v42
	s_waitcnt vmcnt(5)
	v_mul_f32_e32 v36, v36, v0
	v_mul_f32_e32 v0, v54, v42
	v_mul_f32_e32 v37, v37, v0
	v_mul_f32_e32 v0, v55, v42
	v_mul_f32_e32 v38, v38, v0
	v_mul_f32_e32 v0, v56, v42
	v_mul_f32_e32 v39, v39, v0
	v_mul_f32_e32 v0, v57, v42
	s_waitcnt vmcnt(4)
	v_mul_f32_e32 v16, v16, v0
	v_mul_f32_e32 v0, v58, v42
	v_mul_f32_e32 v17, v17, v0
	v_mul_f32_e32 v0, v61, v42
	v_mul_f32_e32 v18, v18, v0
	v_mul_f32_e32 v0, v62, v42
	v_mul_f32_e32 v19, v19, v0
	v_mul_f32_e32 v0, v63, v42
	s_waitcnt vmcnt(3)
	v_mul_f32_e32 v46, v4, v0
	v_mul_f32_e32 v0, v65, v42
	v_mul_f32_e32 v47, v5, v0
	v_mul_f32_e32 v0, v67, v42
	v_mul_f32_e32 v6, v6, v0
	v_mul_f32_e32 v0, v69, v42
	v_mul_f32_e32 v7, v7, v0
	v_mul_f32_e32 v0, v70, v42
	s_waitcnt vmcnt(2)
	v_mul_f32_e32 v20, v20, v0
	v_mul_f32_e32 v0, v71, v42
	v_mul_f32_e32 v21, v21, v0
	v_mul_f32_e32 v0, v40, v42
	v_mul_f32_e32 v22, v22, v0
	v_mul_f32_e32 v0, v41, v42
	v_mul_f32_e32 v23, v23, v0
	v_mul_f32_e32 v0, v24, v42
	s_waitcnt vmcnt(1)
	v_mul_f32_e32 v8, v8, v0
	v_mul_f32_e32 v0, v25, v42
	v_mul_f32_e32 v9, v9, v0
	v_mul_f32_e32 v0, v26, v42
	v_mul_f32_e32 v10, v10, v0
	v_mul_f32_e32 v0, v27, v42
	v_mul_f32_e32 v11, v11, v0
	v_mul_f32_e32 v0, v28, v42
	s_waitcnt vmcnt(0)
	v_mul_f32_e32 v12, v12, v0
	v_mul_f32_e32 v0, v29, v42
	v_mul_f32_e32 v13, v13, v0
	v_mul_f32_e32 v0, v30, v42
	v_mul_f32_e32 v14, v14, v0
	v_mul_f32_e32 v0, v31, v42
	v_mul_f32_e32 v15, v15, v0
	v_and_or_b32 v0, v164, 31, v165
	v_ashrrev_i32_e32 v1, 31, v0
	v_lshlrev_b64 v[0:1], 11, v[0:1]
	v_lshl_add_u64 v[0:1], s[10:11], 0, v[0:1]
	v_lshl_add_u64 v[0:1], v[0:1], 0, v[152:153]
	v_lshlrev_b32_e32 v152, 1, v59
	v_lshl_add_u64 v[0:1], v[0:1], 0, v[152:153]
	v_lshl_add_u64 v[4:5], v[0:1], 0, s[6:7]
	s_mov_b32 s6, 0x2b7c000
	v_add_co_u32_e32 v0, vcc, s6, v0
	v_cvt_pk_bf16_f32 v2, v43, v44
	v_cvt_pk_bf16_f32 v3, v45, v3
	s_nop 1
	v_addc_co_u32_e32 v1, vcc, 0, v1, vcc
	global_store_dwordx2 v[0:1], v[2:3], off offset:768
	v_cvt_pk_bf16_f32 v0, v32, v33
	v_cvt_pk_bf16_f32 v1, v34, v35
	global_store_dwordx2 v[4:5], v[0:1], off offset:16
	v_cvt_pk_bf16_f32 v0, v36, v37
	v_cvt_pk_bf16_f32 v1, v38, v39
	global_store_dwordx2 v[4:5], v[0:1], off offset:32
	v_cvt_pk_bf16_f32 v0, v16, v17
	v_cvt_pk_bf16_f32 v1, v18, v19
	global_store_dwordx2 v[4:5], v[0:1], off offset:48
	v_cvt_pk_bf16_f32 v0, v46, v47
	v_cvt_pk_bf16_f32 v1, v6, v7
	global_store_dwordx2 v[4:5], v[0:1], off offset:64
	v_cvt_pk_bf16_f32 v0, v20, v21
	v_cvt_pk_bf16_f32 v1, v22, v23
	global_store_dwordx2 v[4:5], v[0:1], off offset:80
	v_cvt_pk_bf16_f32 v0, v8, v9
	v_cvt_pk_bf16_f32 v1, v10, v11
	global_store_dwordx2 v[4:5], v[0:1], off offset:96
	v_cvt_pk_bf16_f32 v0, v12, v13
	v_cvt_pk_bf16_f32 v1, v14, v15
	global_store_dwordx2 v[4:5], v[0:1], off offset:112
